# indexer scoring: v_pk_mul/v_pk_fma_f32 replaced by scalar v_mul/v_fmac pairs (same fused math; packed f32 is slow beside MFMAs)
# speedup vs baseline: 1.0471x; 1.0145x over previous
.LBB0_532:
	v_mov_b32_e32 v129, v194
	v_readfirstlane_b32 s83, v194
	v_and_b32_e32 v180, 31, v194
	v_bfe_u32 v131, v194, 5, 1
	v_and_b32_e32 v243, 63, v194
	s_ashr_i32 s84, s83, 6
	s_lshl_b32 s0, s84, 5
	v_or_b32_e32 v130, s0, v180
	v_lshlrev_b32_e32 v243, 2, v243
	s_lshl_b32 s0, s2, 17
	s_lshl_b32 s1, s84, 8
	s_add_u32 s0, s0, s1
	s_add_u32 s8, s28, s0
	s_addc_u32 s9, s29, 0
	s_lshl_b32 s21, s84, 12
	s_cmp_lg_u32 s82, 0
	s_cbranch_scc1 .Lix_reload
	s_mov_b32 s100, 0
	v_bfe_u32 v0, v194, 2, 1
	v_lshrrev_b32_e32 v1, 1, v194
	v_and_b32_e32 v1, 12, v1
	v_and_b32_e32 v228, 3, v194
	v_or_b32_e32 v1, v1, v228
	v_add_u32_e32 v0, s34, v0
	v_lshlrev_b32_e32 v0, 11, v0
	v_lshl_add_u32 v0, v1, 7, v0
	v_lshl_add_u32 v0, v131, 4, v0
	v_add_u32_e32 v1, 0x1000, v0
	global_load_dwordx4 v[70:73], v0, s[36:37]
	global_load_dwordx4 v[74:77], v0, s[36:37] offset:32
	global_load_dwordx4 v[78:81], v0, s[36:37] offset:64
	global_load_dwordx4 v[82:85], v0, s[36:37] offset:96
	global_load_dwordx4 v[86:89], v1, s[36:37]
	global_load_dwordx4 v[90:93], v1, s[36:37] offset:32
	global_load_dwordx4 v[94:97], v1, s[36:37] offset:64
	global_load_dwordx4 v[98:101], v1, s[36:37] offset:96
	v_add_u32_e32 v228, s34, v131
	v_lshlrev_b32_e32 v228, 6, v228
	global_load_dwordx4 v[22:25], v228, s[38:39]
	global_load_dwordx4 v[26:29], v228, s[38:39] offset:16
	global_load_dwordx4 v[30:33], v228, s[38:39] offset:32
	global_load_dwordx4 v[34:37], v228, s[38:39] offset:48
	global_load_dwordx2 v[244:245], v228, s[38:39] offset:128
	global_load_dwordx2 v[246:247], v228, s[38:39] offset:136
	global_load_dwordx2 v[248:249], v228, s[38:39] offset:144
	global_load_dwordx2 v[250:251], v228, s[38:39] offset:152
	global_load_dwordx2 v[252:253], v228, s[38:39] offset:160
	global_load_dwordx2 v[254:255], v228, s[38:39] offset:168
	global_load_dwordx2 v[200:201], v228, s[38:39] offset:176
	global_load_dwordx2 v[202:203], v228, s[38:39] offset:184
	v_lshrrev_b32_e32 v0, 2, v243
	v_lshrrev_b32_e32 v1, 3, v0
	v_lshrrev_b32_e32 v228, 4, v0
	v_and_b32_e32 v229, 7, v0
	v_xor_b32_e32 v228, v229, v228
	v_xor_b32_e32 v229, 4, v228
	s_lshl_b32 s0, s84, 12
	v_lshl_add_u32 v1, v1, 7, s0
	v_lshl_add_u32 v102, v228, 4, v1
	v_lshl_add_u32 v110, v229, 4, v1
	v_add_u32_e32 v110, 0x400, v110
	v_add_u32_e32 v112, 0x800, v102
	v_add_u32_e32 v193, 0x800, v110
	v_lshlrev_b32_e32 v0, 7, v130
	v_bfe_u32 v1, v180, 1, 3
	v_or_b32_e32 v228, 0, v131
	v_xor_b32_e32 v228, v228, v1
	v_lshl_add_u32 v5, v228, 4, v0
	v_or_b32_e32 v228, 2, v131
	v_xor_b32_e32 v228, v228, v1
	v_lshl_add_u32 v52, v228, 4, v0
	v_or_b32_e32 v228, 4, v131
	v_xor_b32_e32 v228, v228, v1
	v_lshl_add_u32 v55, v228, 4, v0
	v_or_b32_e32 v228, 6, v131
	v_xor_b32_e32 v228, v228, v1
	v_lshl_add_u32 v56, v228, 4, v0
	s_mov_b32 s6, s14
	s_mov_b32 s7, s15
	s_add_i32 s10, s0, 10496
	s_sub_i32 s11, s35, s84
	s_add_i32 m0, s10, 0
	s_nop 0
	global_load_lds_dwordx4 v102, s[6:7]
	s_add_i32 m0, s10, 1024
	s_nop 0
	global_load_lds_dwordx4 v110, s[6:7]
	s_add_i32 m0, s10, 2048
	s_nop 0
	global_load_lds_dwordx4 v112, s[6:7]
	s_add_i32 m0, s10, 3072
	s_nop 0
	global_load_lds_dwordx4 v193, s[6:7]
	s_add_u32 s6, s6, 0x8000
	s_addc_u32 s7, s7, 0
	s_add_i32 m0, s10, 32768
	s_nop 0
	global_load_lds_dwordx4 v102, s[6:7]
	s_add_i32 m0, s10, 33792
	s_nop 0
	global_load_lds_dwordx4 v110, s[6:7]
	s_add_i32 m0, s10, 34816
	s_nop 0
	global_load_lds_dwordx4 v112, s[6:7]
	s_add_i32 m0, s10, 35840
	s_nop 0
	global_load_lds_dwordx4 v193, s[6:7]
	s_add_u32 s6, s6, 0x8000
	s_addc_u32 s7, s7, 0
	s_add_i32 m0, s10, 65536
	s_nop 0
	global_load_lds_dwordx4 v102, s[6:7]
	s_add_i32 m0, s10, 66560
	s_nop 0
	global_load_lds_dwordx4 v110, s[6:7]
	s_add_i32 m0, s10, 67584
	s_nop 0
	global_load_lds_dwordx4 v112, s[6:7]
	s_add_i32 m0, s10, 68608
	s_nop 0
	global_load_lds_dwordx4 v193, s[6:7]
	s_add_u32 s6, s6, 0x8000
	s_addc_u32 s7, s7, 0
	s_waitcnt vmcnt(8)
	ds_read_b128 v[38:41], v5 offset:10496
	ds_read_b128 v[42:45], v52 offset:10496
	ds_read_b128 v[46:49], v55 offset:10496
	ds_read_b128 v[196:199], v56 offset:10496
	s_waitcnt lgkmcnt(3)
	v_mfma_f32_32x32x16_bf16 v[212:227], v[70:73], v[38:41], 0
	s_add_i32 m0, s10, 98304
	s_nop 0
	global_load_lds_dwordx4 v102, s[6:7]
	s_waitcnt lgkmcnt(2)
	v_mfma_f32_32x32x16_bf16 v[212:227], v[74:77], v[42:45], v[212:227]
	s_add_i32 m0, s10, 99328
	s_nop 0
	global_load_lds_dwordx4 v110, s[6:7]
	s_waitcnt lgkmcnt(1)
	v_mfma_f32_32x32x16_bf16 v[212:227], v[78:81], v[46:49], v[212:227]
	s_add_i32 m0, s10, 100352
	s_nop 0
	global_load_lds_dwordx4 v112, s[6:7]
	s_waitcnt lgkmcnt(0)
	v_mfma_f32_32x32x16_bf16 v[212:227], v[82:85], v[196:199], v[212:227]
	s_add_i32 m0, s10, 101376
	s_nop 0
	global_load_lds_dwordx4 v193, s[6:7]
	s_add_u32 s6, s6, 0x8000
	s_addc_u32 s7, s7, 0
	v_mfma_f32_32x32x16_bf16 v[6:21], v[86:89], v[38:41], 0
	s_nop 7
	s_nop 2
	v_max_f32_e32 v108, 0, v212
	v_max_f32_e32 v109, 0, v213
	v_mul_f32_e32 v0, v22, v108
	v_mul_f32_e32 v1, v23, v109
	v_max_f32_e32 v210, 0, v214
	v_max_f32_e32 v211, 0, v215
	v_fmac_f32_e32 v0, v24, v210
	v_fmac_f32_e32 v1, v25, v211
	v_max_f32_e32 v108, 0, v216
	v_max_f32_e32 v109, 0, v217
	v_fmac_f32_e32 v0, v26, v108
	v_fmac_f32_e32 v1, v27, v109
	v_mfma_f32_32x32x16_bf16 v[6:21], v[90:93], v[42:45], v[6:21]
	v_max_f32_e32 v210, 0, v218
	v_max_f32_e32 v211, 0, v219
	v_fmac_f32_e32 v0, v28, v210
	v_fmac_f32_e32 v1, v29, v211
	v_max_f32_e32 v108, 0, v220
	v_max_f32_e32 v109, 0, v221
	v_fmac_f32_e32 v0, v30, v108
	v_fmac_f32_e32 v1, v31, v109
	v_max_f32_e32 v210, 0, v222
	v_max_f32_e32 v211, 0, v223
	v_fmac_f32_e32 v0, v32, v210
	v_fmac_f32_e32 v1, v33, v211
	v_mfma_f32_32x32x16_bf16 v[6:21], v[94:97], v[46:49], v[6:21]
	v_max_f32_e32 v108, 0, v224
	v_max_f32_e32 v109, 0, v225
	v_fmac_f32_e32 v0, v34, v108
	v_fmac_f32_e32 v1, v35, v109
	v_max_f32_e32 v210, 0, v226
	v_max_f32_e32 v211, 0, v227
	v_fmac_f32_e32 v0, v36, v210
	v_fmac_f32_e32 v1, v37, v211
	v_add_f32_e32 v0, v0, v1
	v_ashrrev_i32_e32 v1, 31, v0
	v_mfma_f32_32x32x16_bf16 v[6:21], v[98:101], v[196:199], v[6:21]
	s_waitcnt vmcnt(8)
	ds_read_b128 v[38:41], v5 offset:43264
	ds_read_b128 v[42:45], v52 offset:43264
	ds_read_b128 v[46:49], v55 offset:43264
	ds_read_b128 v[196:199], v56 offset:43264
	v_or_b32_e32 v1, 0x80000000, v1
	s_cmpk_gt_i32 s11, 0
	s_cselect_b64 vcc, -1, 0
	v_xor_b32_e32 v0, v1, v0
	v_cndmask_b32_e32 v133, v123, v0, vcc
	s_nop 3
	s_waitcnt lgkmcnt(3)
	v_mfma_f32_32x32x16_bf16 v[212:227], v[70:73], v[38:41], 0
	v_max_f32_e32 v108, 0, v6
	v_max_f32_e32 v109, 0, v7
	v_mul_f32_e32 v50, v244, v108
	v_mul_f32_e32 v51, v245, v109
	v_max_f32_e32 v210, 0, v8
	v_max_f32_e32 v211, 0, v9
	v_fmac_f32_e32 v50, v246, v210
	v_fmac_f32_e32 v51, v247, v211
	v_max_f32_e32 v108, 0, v10
	v_max_f32_e32 v109, 0, v11
	v_fmac_f32_e32 v50, v248, v108
	v_fmac_f32_e32 v51, v249, v109
	s_waitcnt lgkmcnt(2)
	v_mfma_f32_32x32x16_bf16 v[212:227], v[74:77], v[42:45], v[212:227]
	v_max_f32_e32 v210, 0, v12
	v_max_f32_e32 v211, 0, v13
	v_fmac_f32_e32 v50, v250, v210
	v_fmac_f32_e32 v51, v251, v211
	v_max_f32_e32 v108, 0, v14
	v_max_f32_e32 v109, 0, v15
	v_fmac_f32_e32 v50, v252, v108
	v_fmac_f32_e32 v51, v253, v109
	v_max_f32_e32 v210, 0, v16
	v_max_f32_e32 v211, 0, v17
	v_fmac_f32_e32 v50, v254, v210
	v_fmac_f32_e32 v51, v255, v211
	s_waitcnt lgkmcnt(1)
	v_mfma_f32_32x32x16_bf16 v[212:227], v[78:81], v[46:49], v[212:227]
	v_max_f32_e32 v108, 0, v18
	v_max_f32_e32 v109, 0, v19
	v_fmac_f32_e32 v50, v200, v108
	v_fmac_f32_e32 v51, v201, v109
	v_max_f32_e32 v210, 0, v20
	v_max_f32_e32 v211, 0, v21
	v_fmac_f32_e32 v50, v202, v210
	v_fmac_f32_e32 v51, v203, v211
	v_add_f32_e32 v50, v50, v51
	v_ashrrev_i32_e32 v51, 31, v50
	s_waitcnt lgkmcnt(0)
	v_mfma_f32_32x32x16_bf16 v[212:227], v[82:85], v[196:199], v[212:227]
	v_or_b32_e32 v51, 0x80000000, v51
	s_cmpk_gt_i32 s11, 0
	s_cselect_b64 vcc, -1, 0
	v_xor_b32_e32 v50, v51, v50
	v_cndmask_b32_e32 v50, v123, v50, vcc
	global_store_dword v243, v50, s[8:9]
	v_mfma_f32_32x32x16_bf16 v[6:21], v[86:89], v[38:41], 0
	s_add_i32 m0, s10, 0
	s_nop 0
	global_load_lds_dwordx4 v102, s[6:7]
	s_add_i32 m0, s10, 1024
	s_nop 0
	global_load_lds_dwordx4 v110, s[6:7]
	s_add_i32 m0, s10, 2048
	s_nop 0
	global_load_lds_dwordx4 v112, s[6:7]
	s_add_i32 m0, s10, 3072
	s_nop 0
	global_load_lds_dwordx4 v193, s[6:7]
	s_add_u32 s6, s6, 0x8000
	s_addc_u32 s7, s7, 0
	v_max_f32_e32 v108, 0, v212
	v_max_f32_e32 v109, 0, v213
	v_mul_f32_e32 v0, v22, v108
	v_mul_f32_e32 v1, v23, v109
	v_max_f32_e32 v210, 0, v214
	v_max_f32_e32 v211, 0, v215
	v_fmac_f32_e32 v0, v24, v210
	v_fmac_f32_e32 v1, v25, v211
	v_max_f32_e32 v108, 0, v216
	v_max_f32_e32 v109, 0, v217
	v_fmac_f32_e32 v0, v26, v108
	v_fmac_f32_e32 v1, v27, v109
	v_mfma_f32_32x32x16_bf16 v[6:21], v[90:93], v[42:45], v[6:21]
	v_max_f32_e32 v210, 0, v218
	v_max_f32_e32 v211, 0, v219
	v_fmac_f32_e32 v0, v28, v210
	v_fmac_f32_e32 v1, v29, v211
	v_max_f32_e32 v108, 0, v220
	v_max_f32_e32 v109, 0, v221
	v_fmac_f32_e32 v0, v30, v108
	v_fmac_f32_e32 v1, v31, v109
	v_max_f32_e32 v210, 0, v222
	v_max_f32_e32 v211, 0, v223
	v_fmac_f32_e32 v0, v32, v210
	v_fmac_f32_e32 v1, v33, v211
	v_mfma_f32_32x32x16_bf16 v[6:21], v[94:97], v[46:49], v[6:21]
	v_max_f32_e32 v108, 0, v224
	v_max_f32_e32 v109, 0, v225
	v_fmac_f32_e32 v0, v34, v108
	v_fmac_f32_e32 v1, v35, v109
	v_max_f32_e32 v210, 0, v226
	v_max_f32_e32 v211, 0, v227
	v_fmac_f32_e32 v0, v36, v210
	v_fmac_f32_e32 v1, v37, v211
	v_add_f32_e32 v0, v0, v1
	v_ashrrev_i32_e32 v1, 31, v0
	v_mfma_f32_32x32x16_bf16 v[6:21], v[98:101], v[196:199], v[6:21]
	s_waitcnt vmcnt(9)
	v_add_u32_e32 v228, 0x10000, v5
	ds_read_b128 v[38:41], v228 offset:10496
	v_add_u32_e32 v228, 0x10000, v52
	ds_read_b128 v[42:45], v228 offset:10496
	v_add_u32_e32 v228, 0x10000, v55
	ds_read_b128 v[46:49], v228 offset:10496
	v_add_u32_e32 v228, 0x10000, v56
	ds_read_b128 v[196:199], v228 offset:10496
	v_or_b32_e32 v1, 0x80000000, v1
	s_cmpk_gt_i32 s11, 8
	s_cselect_b64 vcc, -1, 0
	v_xor_b32_e32 v0, v1, v0
	v_cndmask_b32_e32 v132, v123, v0, vcc
	s_nop 3
	s_waitcnt lgkmcnt(3)
	v_mfma_f32_32x32x16_bf16 v[212:227], v[70:73], v[38:41], 0
	v_max_f32_e32 v108, 0, v6
	v_max_f32_e32 v109, 0, v7
	v_mul_f32_e32 v50, v244, v108
	v_mul_f32_e32 v51, v245, v109
	v_max_f32_e32 v210, 0, v8
	v_max_f32_e32 v211, 0, v9
	v_fmac_f32_e32 v50, v246, v210
	v_fmac_f32_e32 v51, v247, v211
	v_max_f32_e32 v108, 0, v10
	v_max_f32_e32 v109, 0, v11
	v_fmac_f32_e32 v50, v248, v108
	v_fmac_f32_e32 v51, v249, v109
	s_waitcnt lgkmcnt(2)
	v_mfma_f32_32x32x16_bf16 v[212:227], v[74:77], v[42:45], v[212:227]
	v_max_f32_e32 v210, 0, v12
	v_max_f32_e32 v211, 0, v13
	v_fmac_f32_e32 v50, v250, v210
	v_fmac_f32_e32 v51, v251, v211
	v_max_f32_e32 v108, 0, v14
	v_max_f32_e32 v109, 0, v15
	v_fmac_f32_e32 v50, v252, v108
	v_fmac_f32_e32 v51, v253, v109
	v_max_f32_e32 v210, 0, v16
	v_max_f32_e32 v211, 0, v17
	v_fmac_f32_e32 v50, v254, v210
	v_fmac_f32_e32 v51, v255, v211
	s_waitcnt lgkmcnt(1)
	v_mfma_f32_32x32x16_bf16 v[212:227], v[78:81], v[46:49], v[212:227]
	v_max_f32_e32 v108, 0, v18
	v_max_f32_e32 v109, 0, v19
	v_fmac_f32_e32 v50, v200, v108
	v_fmac_f32_e32 v51, v201, v109
	v_max_f32_e32 v210, 0, v20
	v_max_f32_e32 v211, 0, v21
	v_fmac_f32_e32 v50, v202, v210
	v_fmac_f32_e32 v51, v203, v211
	v_add_f32_e32 v50, v50, v51
	v_ashrrev_i32_e32 v51, 31, v50
	s_waitcnt lgkmcnt(0)
	v_mfma_f32_32x32x16_bf16 v[212:227], v[82:85], v[196:199], v[212:227]
	v_or_b32_e32 v51, 0x80000000, v51
	s_cmpk_gt_i32 s11, 8
	s_cselect_b64 vcc, -1, 0
	v_xor_b32_e32 v50, v51, v50
	v_cndmask_b32_e32 v50, v123, v50, vcc
	global_store_dword v243, v50, s[8:9] offset:2048
	s_add_u32 s8, s8, 0x1000
	s_addc_u32 s9, s9, 0
	v_mfma_f32_32x32x16_bf16 v[6:21], v[86:89], v[38:41], 0
	s_add_i32 m0, s10, 32768
	s_nop 0
	global_load_lds_dwordx4 v102, s[6:7]
	s_add_i32 m0, s10, 33792
	s_nop 0
	global_load_lds_dwordx4 v110, s[6:7]
	s_add_i32 m0, s10, 34816
	s_nop 0
	global_load_lds_dwordx4 v112, s[6:7]
	s_add_i32 m0, s10, 35840
	s_nop 0
	global_load_lds_dwordx4 v193, s[6:7]
	s_add_u32 s6, s6, 0x8000
	s_addc_u32 s7, s7, 0
	v_max_f32_e32 v108, 0, v212
	v_max_f32_e32 v109, 0, v213
	v_mul_f32_e32 v0, v22, v108
	v_mul_f32_e32 v1, v23, v109
	v_max_f32_e32 v210, 0, v214
	v_max_f32_e32 v211, 0, v215
	v_fmac_f32_e32 v0, v24, v210
	v_fmac_f32_e32 v1, v25, v211
	v_max_f32_e32 v108, 0, v216
	v_max_f32_e32 v109, 0, v217
	v_fmac_f32_e32 v0, v26, v108
	v_fmac_f32_e32 v1, v27, v109
	v_mfma_f32_32x32x16_bf16 v[6:21], v[90:93], v[42:45], v[6:21]
	v_max_f32_e32 v210, 0, v218
	v_max_f32_e32 v211, 0, v219
	v_fmac_f32_e32 v0, v28, v210
	v_fmac_f32_e32 v1, v29, v211
	v_max_f32_e32 v108, 0, v220
	v_max_f32_e32 v109, 0, v221
	v_fmac_f32_e32 v0, v30, v108
	v_fmac_f32_e32 v1, v31, v109
	v_max_f32_e32 v210, 0, v222
	v_max_f32_e32 v211, 0, v223
	v_fmac_f32_e32 v0, v32, v210
	v_fmac_f32_e32 v1, v33, v211
	v_mfma_f32_32x32x16_bf16 v[6:21], v[94:97], v[46:49], v[6:21]
	v_max_f32_e32 v108, 0, v224
	v_max_f32_e32 v109, 0, v225
	v_fmac_f32_e32 v0, v34, v108
	v_fmac_f32_e32 v1, v35, v109
	v_max_f32_e32 v210, 0, v226
	v_max_f32_e32 v211, 0, v227
	v_fmac_f32_e32 v0, v36, v210
	v_fmac_f32_e32 v1, v37, v211
	v_add_f32_e32 v0, v0, v1
	v_ashrrev_i32_e32 v1, 31, v0
	v_mfma_f32_32x32x16_bf16 v[6:21], v[98:101], v[196:199], v[6:21]
	s_waitcnt vmcnt(10)
	v_add_u32_e32 v228, 0x10000, v5
	ds_read_b128 v[38:41], v228 offset:43264
	v_add_u32_e32 v228, 0x10000, v52
	ds_read_b128 v[42:45], v228 offset:43264
	v_add_u32_e32 v228, 0x10000, v55
	ds_read_b128 v[46:49], v228 offset:43264
	v_add_u32_e32 v228, 0x10000, v56
	ds_read_b128 v[196:199], v228 offset:43264
	v_or_b32_e32 v1, 0x80000000, v1
	s_cmpk_gt_i32 s11, 16
	s_cselect_b64 vcc, -1, 0
	v_xor_b32_e32 v0, v1, v0
	v_cndmask_b32_e32 v135, v123, v0, vcc
	s_nop 3
	s_waitcnt lgkmcnt(3)
	v_mfma_f32_32x32x16_bf16 v[212:227], v[70:73], v[38:41], 0
	v_max_f32_e32 v108, 0, v6
	v_max_f32_e32 v109, 0, v7
	v_mul_f32_e32 v50, v244, v108
	v_mul_f32_e32 v51, v245, v109
	v_max_f32_e32 v210, 0, v8
	v_max_f32_e32 v211, 0, v9
	v_fmac_f32_e32 v50, v246, v210
	v_fmac_f32_e32 v51, v247, v211
	v_max_f32_e32 v108, 0, v10
	v_max_f32_e32 v109, 0, v11
	v_fmac_f32_e32 v50, v248, v108
	v_fmac_f32_e32 v51, v249, v109
	s_waitcnt lgkmcnt(2)
	v_mfma_f32_32x32x16_bf16 v[212:227], v[74:77], v[42:45], v[212:227]
	v_max_f32_e32 v210, 0, v12
	v_max_f32_e32 v211, 0, v13
	v_fmac_f32_e32 v50, v250, v210
	v_fmac_f32_e32 v51, v251, v211
	v_max_f32_e32 v108, 0, v14
	v_max_f32_e32 v109, 0, v15
	v_fmac_f32_e32 v50, v252, v108
	v_fmac_f32_e32 v51, v253, v109
	v_max_f32_e32 v210, 0, v16
	v_max_f32_e32 v211, 0, v17
	v_fmac_f32_e32 v50, v254, v210
	v_fmac_f32_e32 v51, v255, v211
	s_waitcnt lgkmcnt(1)
	v_mfma_f32_32x32x16_bf16 v[212:227], v[78:81], v[46:49], v[212:227]
	v_max_f32_e32 v108, 0, v18
	v_max_f32_e32 v109, 0, v19
	v_fmac_f32_e32 v50, v200, v108
	v_fmac_f32_e32 v51, v201, v109
	v_max_f32_e32 v210, 0, v20
	v_max_f32_e32 v211, 0, v21
	v_fmac_f32_e32 v50, v202, v210
	v_fmac_f32_e32 v51, v203, v211
	v_add_f32_e32 v50, v50, v51
	v_ashrrev_i32_e32 v51, 31, v50
	s_waitcnt lgkmcnt(0)
	v_mfma_f32_32x32x16_bf16 v[212:227], v[82:85], v[196:199], v[212:227]
	v_or_b32_e32 v51, 0x80000000, v51
	s_cmpk_gt_i32 s11, 16
	s_cselect_b64 vcc, -1, 0
	v_xor_b32_e32 v50, v51, v50
	v_cndmask_b32_e32 v50, v123, v50, vcc
	global_store_dword v243, v50, s[8:9]
	v_mfma_f32_32x32x16_bf16 v[6:21], v[86:89], v[38:41], 0
	s_add_i32 m0, s10, 65536
	s_nop 0
	global_load_lds_dwordx4 v102, s[6:7]
	s_add_i32 m0, s10, 66560
	s_nop 0
	global_load_lds_dwordx4 v110, s[6:7]
	s_add_i32 m0, s10, 67584
	s_nop 0
	global_load_lds_dwordx4 v112, s[6:7]
	s_add_i32 m0, s10, 68608
	s_nop 0
	global_load_lds_dwordx4 v193, s[6:7]
	s_add_u32 s6, s6, 0x8000
	s_addc_u32 s7, s7, 0
	v_max_f32_e32 v108, 0, v212
	v_max_f32_e32 v109, 0, v213
	v_mul_f32_e32 v0, v22, v108
	v_mul_f32_e32 v1, v23, v109
	v_max_f32_e32 v210, 0, v214
	v_max_f32_e32 v211, 0, v215
	v_fmac_f32_e32 v0, v24, v210
	v_fmac_f32_e32 v1, v25, v211
	v_max_f32_e32 v108, 0, v216
	v_max_f32_e32 v109, 0, v217
	v_fmac_f32_e32 v0, v26, v108
	v_fmac_f32_e32 v1, v27, v109
	v_mfma_f32_32x32x16_bf16 v[6:21], v[90:93], v[42:45], v[6:21]
	v_max_f32_e32 v210, 0, v218
	v_max_f32_e32 v211, 0, v219
	v_fmac_f32_e32 v0, v28, v210
	v_fmac_f32_e32 v1, v29, v211
	v_max_f32_e32 v108, 0, v220
	v_max_f32_e32 v109, 0, v221
	v_fmac_f32_e32 v0, v30, v108
	v_fmac_f32_e32 v1, v31, v109
	v_max_f32_e32 v210, 0, v222
	v_max_f32_e32 v211, 0, v223
	v_fmac_f32_e32 v0, v32, v210
	v_fmac_f32_e32 v1, v33, v211
	v_mfma_f32_32x32x16_bf16 v[6:21], v[94:97], v[46:49], v[6:21]
	v_max_f32_e32 v108, 0, v224
	v_max_f32_e32 v109, 0, v225
	v_fmac_f32_e32 v0, v34, v108
	v_fmac_f32_e32 v1, v35, v109
	v_max_f32_e32 v210, 0, v226
	v_max_f32_e32 v211, 0, v227
	v_fmac_f32_e32 v0, v36, v210
	v_fmac_f32_e32 v1, v37, v211
	v_add_f32_e32 v0, v0, v1
	v_ashrrev_i32_e32 v1, 31, v0
	v_mfma_f32_32x32x16_bf16 v[6:21], v[98:101], v[196:199], v[6:21]
	s_waitcnt vmcnt(10)
	ds_read_b128 v[38:41], v5 offset:10496
	ds_read_b128 v[42:45], v52 offset:10496
	ds_read_b128 v[46:49], v55 offset:10496
	ds_read_b128 v[196:199], v56 offset:10496
	v_or_b32_e32 v1, 0x80000000, v1
	s_cmpk_gt_i32 s11, 24
	s_cselect_b64 vcc, -1, 0
	v_xor_b32_e32 v0, v1, v0
	v_cndmask_b32_e32 v134, v123, v0, vcc
	s_nop 3
	s_waitcnt lgkmcnt(3)
	v_mfma_f32_32x32x16_bf16 v[212:227], v[70:73], v[38:41], 0
	v_max_f32_e32 v108, 0, v6
	v_max_f32_e32 v109, 0, v7
	v_mul_f32_e32 v50, v244, v108
	v_mul_f32_e32 v51, v245, v109
	v_max_f32_e32 v210, 0, v8
	v_max_f32_e32 v211, 0, v9
	v_fmac_f32_e32 v50, v246, v210
	v_fmac_f32_e32 v51, v247, v211
	v_max_f32_e32 v108, 0, v10
	v_max_f32_e32 v109, 0, v11
	v_fmac_f32_e32 v50, v248, v108
	v_fmac_f32_e32 v51, v249, v109
	s_waitcnt lgkmcnt(2)
	v_mfma_f32_32x32x16_bf16 v[212:227], v[74:77], v[42:45], v[212:227]
	v_max_f32_e32 v210, 0, v12
	v_max_f32_e32 v211, 0, v13
	v_fmac_f32_e32 v50, v250, v210
	v_fmac_f32_e32 v51, v251, v211
	v_max_f32_e32 v108, 0, v14
	v_max_f32_e32 v109, 0, v15
	v_fmac_f32_e32 v50, v252, v108
	v_fmac_f32_e32 v51, v253, v109
	v_max_f32_e32 v210, 0, v16
	v_max_f32_e32 v211, 0, v17
	v_fmac_f32_e32 v50, v254, v210
	v_fmac_f32_e32 v51, v255, v211
	s_waitcnt lgkmcnt(1)
	v_mfma_f32_32x32x16_bf16 v[212:227], v[78:81], v[46:49], v[212:227]
	v_max_f32_e32 v108, 0, v18
	v_max_f32_e32 v109, 0, v19
	v_fmac_f32_e32 v50, v200, v108
	v_fmac_f32_e32 v51, v201, v109
	v_max_f32_e32 v210, 0, v20
	v_max_f32_e32 v211, 0, v21
	v_fmac_f32_e32 v50, v202, v210
	v_fmac_f32_e32 v51, v203, v211
	v_add_f32_e32 v50, v50, v51
	v_ashrrev_i32_e32 v51, 31, v50
	s_waitcnt lgkmcnt(0)
	v_mfma_f32_32x32x16_bf16 v[212:227], v[82:85], v[196:199], v[212:227]
	v_or_b32_e32 v51, 0x80000000, v51
	s_cmpk_gt_i32 s11, 24
	s_cselect_b64 vcc, -1, 0
	v_xor_b32_e32 v50, v51, v50
	v_cndmask_b32_e32 v50, v123, v50, vcc
	global_store_dword v243, v50, s[8:9] offset:2048
	s_add_u32 s8, s8, 0x1000
	s_addc_u32 s9, s9, 0
	v_mfma_f32_32x32x16_bf16 v[6:21], v[86:89], v[38:41], 0
	s_add_i32 m0, s10, 98304
	s_nop 0
	global_load_lds_dwordx4 v102, s[6:7]
	s_add_i32 m0, s10, 99328
	s_nop 0
	global_load_lds_dwordx4 v110, s[6:7]
	s_add_i32 m0, s10, 100352
	s_nop 0
	global_load_lds_dwordx4 v112, s[6:7]
	s_add_i32 m0, s10, 101376
	s_nop 0
	global_load_lds_dwordx4 v193, s[6:7]
	s_add_u32 s6, s6, 0x8000
	s_addc_u32 s7, s7, 0
	v_max_f32_e32 v108, 0, v212
	v_max_f32_e32 v109, 0, v213
	v_mul_f32_e32 v0, v22, v108
	v_mul_f32_e32 v1, v23, v109
	v_max_f32_e32 v210, 0, v214
	v_max_f32_e32 v211, 0, v215
	v_fmac_f32_e32 v0, v24, v210
	v_fmac_f32_e32 v1, v25, v211
	v_max_f32_e32 v108, 0, v216
	v_max_f32_e32 v109, 0, v217
	v_fmac_f32_e32 v0, v26, v108
	v_fmac_f32_e32 v1, v27, v109
	v_mfma_f32_32x32x16_bf16 v[6:21], v[90:93], v[42:45], v[6:21]
	v_max_f32_e32 v210, 0, v218
	v_max_f32_e32 v211, 0, v219
	v_fmac_f32_e32 v0, v28, v210
	v_fmac_f32_e32 v1, v29, v211
	v_max_f32_e32 v108, 0, v220
	v_max_f32_e32 v109, 0, v221
	v_fmac_f32_e32 v0, v30, v108
	v_fmac_f32_e32 v1, v31, v109
	v_max_f32_e32 v210, 0, v222
	v_max_f32_e32 v211, 0, v223
	v_fmac_f32_e32 v0, v32, v210
	v_fmac_f32_e32 v1, v33, v211
	v_mfma_f32_32x32x16_bf16 v[6:21], v[94:97], v[46:49], v[6:21]
	v_max_f32_e32 v108, 0, v224
	v_max_f32_e32 v109, 0, v225
	v_fmac_f32_e32 v0, v34, v108
	v_fmac_f32_e32 v1, v35, v109
	v_max_f32_e32 v210, 0, v226
	v_max_f32_e32 v211, 0, v227
	v_fmac_f32_e32 v0, v36, v210
	v_fmac_f32_e32 v1, v37, v211
	v_add_f32_e32 v0, v0, v1
	v_ashrrev_i32_e32 v1, 31, v0
	v_mfma_f32_32x32x16_bf16 v[6:21], v[98:101], v[196:199], v[6:21]
	s_waitcnt vmcnt(10)
	ds_read_b128 v[38:41], v5 offset:43264
	ds_read_b128 v[42:45], v52 offset:43264
	ds_read_b128 v[46:49], v55 offset:43264
	ds_read_b128 v[196:199], v56 offset:43264
	v_or_b32_e32 v1, 0x80000000, v1
	s_cmpk_gt_i32 s11, 32
	s_cselect_b64 vcc, -1, 0
	v_xor_b32_e32 v0, v1, v0
	v_cndmask_b32_e32 v138, v123, v0, vcc
	s_nop 3
	s_waitcnt lgkmcnt(3)
	v_mfma_f32_32x32x16_bf16 v[212:227], v[70:73], v[38:41], 0
	v_max_f32_e32 v108, 0, v6
	v_max_f32_e32 v109, 0, v7
	v_mul_f32_e32 v50, v244, v108
	v_mul_f32_e32 v51, v245, v109
	v_max_f32_e32 v210, 0, v8
	v_max_f32_e32 v211, 0, v9
	v_fmac_f32_e32 v50, v246, v210
	v_fmac_f32_e32 v51, v247, v211
	v_max_f32_e32 v108, 0, v10
	v_max_f32_e32 v109, 0, v11
	v_fmac_f32_e32 v50, v248, v108
	v_fmac_f32_e32 v51, v249, v109
	s_waitcnt lgkmcnt(2)
	v_mfma_f32_32x32x16_bf16 v[212:227], v[74:77], v[42:45], v[212:227]
	v_max_f32_e32 v210, 0, v12
	v_max_f32_e32 v211, 0, v13
	v_fmac_f32_e32 v50, v250, v210
	v_fmac_f32_e32 v51, v251, v211
	v_max_f32_e32 v108, 0, v14
	v_max_f32_e32 v109, 0, v15
	v_fmac_f32_e32 v50, v252, v108
	v_fmac_f32_e32 v51, v253, v109
	v_max_f32_e32 v210, 0, v16
	v_max_f32_e32 v211, 0, v17
	v_fmac_f32_e32 v50, v254, v210
	v_fmac_f32_e32 v51, v255, v211
	s_waitcnt lgkmcnt(1)
	v_mfma_f32_32x32x16_bf16 v[212:227], v[78:81], v[46:49], v[212:227]
	v_max_f32_e32 v108, 0, v18
	v_max_f32_e32 v109, 0, v19
	v_fmac_f32_e32 v50, v200, v108
	v_fmac_f32_e32 v51, v201, v109
	v_max_f32_e32 v210, 0, v20
	v_max_f32_e32 v211, 0, v21
	v_fmac_f32_e32 v50, v202, v210
	v_fmac_f32_e32 v51, v203, v211
	v_add_f32_e32 v50, v50, v51
	v_ashrrev_i32_e32 v51, 31, v50
	s_waitcnt lgkmcnt(0)
	v_mfma_f32_32x32x16_bf16 v[212:227], v[82:85], v[196:199], v[212:227]
	v_or_b32_e32 v51, 0x80000000, v51
	s_cmpk_gt_i32 s11, 32
	s_cselect_b64 vcc, -1, 0
	v_xor_b32_e32 v50, v51, v50
	v_cndmask_b32_e32 v50, v123, v50, vcc
	global_store_dword v243, v50, s[8:9]
	v_mfma_f32_32x32x16_bf16 v[6:21], v[86:89], v[38:41], 0
	s_add_i32 m0, s10, 0
	s_nop 0
	global_load_lds_dwordx4 v102, s[6:7]
	s_add_i32 m0, s10, 1024
	s_nop 0
	global_load_lds_dwordx4 v110, s[6:7]
	s_add_i32 m0, s10, 2048
	s_nop 0
	global_load_lds_dwordx4 v112, s[6:7]
	s_add_i32 m0, s10, 3072
	s_nop 0
	global_load_lds_dwordx4 v193, s[6:7]
	s_add_u32 s6, s6, 0x8000
	s_addc_u32 s7, s7, 0
	v_max_f32_e32 v108, 0, v212
	v_max_f32_e32 v109, 0, v213
	v_mul_f32_e32 v0, v22, v108
	v_mul_f32_e32 v1, v23, v109
	v_max_f32_e32 v210, 0, v214
	v_max_f32_e32 v211, 0, v215
	v_fmac_f32_e32 v0, v24, v210
	v_fmac_f32_e32 v1, v25, v211
	v_max_f32_e32 v108, 0, v216
	v_max_f32_e32 v109, 0, v217
	v_fmac_f32_e32 v0, v26, v108
	v_fmac_f32_e32 v1, v27, v109
	v_mfma_f32_32x32x16_bf16 v[6:21], v[90:93], v[42:45], v[6:21]
	v_max_f32_e32 v210, 0, v218
	v_max_f32_e32 v211, 0, v219
	v_fmac_f32_e32 v0, v28, v210
	v_fmac_f32_e32 v1, v29, v211
	v_max_f32_e32 v108, 0, v220
	v_max_f32_e32 v109, 0, v221
	v_fmac_f32_e32 v0, v30, v108
	v_fmac_f32_e32 v1, v31, v109
	v_max_f32_e32 v210, 0, v222
	v_max_f32_e32 v211, 0, v223
	v_fmac_f32_e32 v0, v32, v210
	v_fmac_f32_e32 v1, v33, v211
	v_mfma_f32_32x32x16_bf16 v[6:21], v[94:97], v[46:49], v[6:21]
	v_max_f32_e32 v108, 0, v224
	v_max_f32_e32 v109, 0, v225
	v_fmac_f32_e32 v0, v34, v108
	v_fmac_f32_e32 v1, v35, v109
	v_max_f32_e32 v210, 0, v226
	v_max_f32_e32 v211, 0, v227
	v_fmac_f32_e32 v0, v36, v210
	v_fmac_f32_e32 v1, v37, v211
	v_add_f32_e32 v0, v0, v1
	v_ashrrev_i32_e32 v1, 31, v0
	v_mfma_f32_32x32x16_bf16 v[6:21], v[98:101], v[196:199], v[6:21]
	s_waitcnt vmcnt(10)
	v_add_u32_e32 v228, 0x10000, v5
	ds_read_b128 v[38:41], v228 offset:10496
	v_add_u32_e32 v228, 0x10000, v52
	ds_read_b128 v[42:45], v228 offset:10496
	v_add_u32_e32 v228, 0x10000, v55
	ds_read_b128 v[46:49], v228 offset:10496
	v_add_u32_e32 v228, 0x10000, v56
	ds_read_b128 v[196:199], v228 offset:10496
	v_or_b32_e32 v1, 0x80000000, v1
	s_cmpk_gt_i32 s11, 40
	s_cselect_b64 vcc, -1, 0
	v_xor_b32_e32 v0, v1, v0
	v_cndmask_b32_e32 v137, v123, v0, vcc
	s_nop 3
	s_waitcnt lgkmcnt(3)
	v_mfma_f32_32x32x16_bf16 v[212:227], v[70:73], v[38:41], 0
	v_max_f32_e32 v108, 0, v6
	v_max_f32_e32 v109, 0, v7
	v_mul_f32_e32 v50, v244, v108
	v_mul_f32_e32 v51, v245, v109
	v_max_f32_e32 v210, 0, v8
	v_max_f32_e32 v211, 0, v9
	v_fmac_f32_e32 v50, v246, v210
	v_fmac_f32_e32 v51, v247, v211
	v_max_f32_e32 v108, 0, v10
	v_max_f32_e32 v109, 0, v11
	v_fmac_f32_e32 v50, v248, v108
	v_fmac_f32_e32 v51, v249, v109
	s_waitcnt lgkmcnt(2)
	v_mfma_f32_32x32x16_bf16 v[212:227], v[74:77], v[42:45], v[212:227]
	v_max_f32_e32 v210, 0, v12
	v_max_f32_e32 v211, 0, v13
	v_fmac_f32_e32 v50, v250, v210
	v_fmac_f32_e32 v51, v251, v211
	v_max_f32_e32 v108, 0, v14
	v_max_f32_e32 v109, 0, v15
	v_fmac_f32_e32 v50, v252, v108
	v_fmac_f32_e32 v51, v253, v109
	v_max_f32_e32 v210, 0, v16
	v_max_f32_e32 v211, 0, v17
	v_fmac_f32_e32 v50, v254, v210
	v_fmac_f32_e32 v51, v255, v211
	s_waitcnt lgkmcnt(1)
	v_mfma_f32_32x32x16_bf16 v[212:227], v[78:81], v[46:49], v[212:227]
	v_max_f32_e32 v108, 0, v18
	v_max_f32_e32 v109, 0, v19
	v_fmac_f32_e32 v50, v200, v108
	v_fmac_f32_e32 v51, v201, v109
	v_max_f32_e32 v210, 0, v20
	v_max_f32_e32 v211, 0, v21
	v_fmac_f32_e32 v50, v202, v210
	v_fmac_f32_e32 v51, v203, v211
	v_add_f32_e32 v50, v50, v51
	v_ashrrev_i32_e32 v51, 31, v50
	s_waitcnt lgkmcnt(0)
	v_mfma_f32_32x32x16_bf16 v[212:227], v[82:85], v[196:199], v[212:227]
	v_or_b32_e32 v51, 0x80000000, v51
	s_cmpk_gt_i32 s11, 40
	s_cselect_b64 vcc, -1, 0
	v_xor_b32_e32 v50, v51, v50
	v_cndmask_b32_e32 v50, v123, v50, vcc
	global_store_dword v243, v50, s[8:9] offset:2048
	s_add_u32 s8, s8, 0x1000
	s_addc_u32 s9, s9, 0
	v_mfma_f32_32x32x16_bf16 v[6:21], v[86:89], v[38:41], 0
	s_add_i32 m0, s10, 32768
	s_nop 0
	global_load_lds_dwordx4 v102, s[6:7]
	s_add_i32 m0, s10, 33792
	s_nop 0
	global_load_lds_dwordx4 v110, s[6:7]
	s_add_i32 m0, s10, 34816
	s_nop 0
	global_load_lds_dwordx4 v112, s[6:7]
	s_add_i32 m0, s10, 35840
	s_nop 0
	global_load_lds_dwordx4 v193, s[6:7]
	s_add_u32 s6, s6, 0x8000
	s_addc_u32 s7, s7, 0
	v_max_f32_e32 v108, 0, v212
	v_max_f32_e32 v109, 0, v213
	v_mul_f32_e32 v0, v22, v108
	v_mul_f32_e32 v1, v23, v109
	v_max_f32_e32 v210, 0, v214
	v_max_f32_e32 v211, 0, v215
	v_fmac_f32_e32 v0, v24, v210
	v_fmac_f32_e32 v1, v25, v211
	v_max_f32_e32 v108, 0, v216
	v_max_f32_e32 v109, 0, v217
	v_fmac_f32_e32 v0, v26, v108
	v_fmac_f32_e32 v1, v27, v109
	v_mfma_f32_32x32x16_bf16 v[6:21], v[90:93], v[42:45], v[6:21]
	v_max_f32_e32 v210, 0, v218
	v_max_f32_e32 v211, 0, v219
	v_fmac_f32_e32 v0, v28, v210
	v_fmac_f32_e32 v1, v29, v211
	v_max_f32_e32 v108, 0, v220
	v_max_f32_e32 v109, 0, v221
	v_fmac_f32_e32 v0, v30, v108
	v_fmac_f32_e32 v1, v31, v109
	v_max_f32_e32 v210, 0, v222
	v_max_f32_e32 v211, 0, v223
	v_fmac_f32_e32 v0, v32, v210
	v_fmac_f32_e32 v1, v33, v211
	v_mfma_f32_32x32x16_bf16 v[6:21], v[94:97], v[46:49], v[6:21]
	v_max_f32_e32 v108, 0, v224
	v_max_f32_e32 v109, 0, v225
	v_fmac_f32_e32 v0, v34, v108
	v_fmac_f32_e32 v1, v35, v109
	v_max_f32_e32 v210, 0, v226
	v_max_f32_e32 v211, 0, v227
	v_fmac_f32_e32 v0, v36, v210
	v_fmac_f32_e32 v1, v37, v211
	v_add_f32_e32 v0, v0, v1
	v_ashrrev_i32_e32 v1, 31, v0
	v_mfma_f32_32x32x16_bf16 v[6:21], v[98:101], v[196:199], v[6:21]
	s_waitcnt vmcnt(10)
	v_add_u32_e32 v228, 0x10000, v5
	ds_read_b128 v[38:41], v228 offset:43264
	v_add_u32_e32 v228, 0x10000, v52
	ds_read_b128 v[42:45], v228 offset:43264
	v_add_u32_e32 v228, 0x10000, v55
	ds_read_b128 v[46:49], v228 offset:43264
	v_add_u32_e32 v228, 0x10000, v56
	ds_read_b128 v[196:199], v228 offset:43264
	v_or_b32_e32 v1, 0x80000000, v1
	s_cmpk_gt_i32 s11, 48
	s_cselect_b64 vcc, -1, 0
	v_xor_b32_e32 v0, v1, v0
	v_cndmask_b32_e32 v140, v123, v0, vcc
	s_nop 3
	s_waitcnt lgkmcnt(3)
	v_mfma_f32_32x32x16_bf16 v[212:227], v[70:73], v[38:41], 0
	v_max_f32_e32 v108, 0, v6
	v_max_f32_e32 v109, 0, v7
	v_mul_f32_e32 v50, v244, v108
	v_mul_f32_e32 v51, v245, v109
	v_max_f32_e32 v210, 0, v8
	v_max_f32_e32 v211, 0, v9
	v_fmac_f32_e32 v50, v246, v210
	v_fmac_f32_e32 v51, v247, v211
	v_max_f32_e32 v108, 0, v10
	v_max_f32_e32 v109, 0, v11
	v_fmac_f32_e32 v50, v248, v108
	v_fmac_f32_e32 v51, v249, v109
	s_waitcnt lgkmcnt(2)
	v_mfma_f32_32x32x16_bf16 v[212:227], v[74:77], v[42:45], v[212:227]
	v_max_f32_e32 v210, 0, v12
	v_max_f32_e32 v211, 0, v13
	v_fmac_f32_e32 v50, v250, v210
	v_fmac_f32_e32 v51, v251, v211
	v_max_f32_e32 v108, 0, v14
	v_max_f32_e32 v109, 0, v15
	v_fmac_f32_e32 v50, v252, v108
	v_fmac_f32_e32 v51, v253, v109
	v_max_f32_e32 v210, 0, v16
	v_max_f32_e32 v211, 0, v17
	v_fmac_f32_e32 v50, v254, v210
	v_fmac_f32_e32 v51, v255, v211
	s_waitcnt lgkmcnt(1)
	v_mfma_f32_32x32x16_bf16 v[212:227], v[78:81], v[46:49], v[212:227]
	v_max_f32_e32 v108, 0, v18
	v_max_f32_e32 v109, 0, v19
	v_fmac_f32_e32 v50, v200, v108
	v_fmac_f32_e32 v51, v201, v109
	v_max_f32_e32 v210, 0, v20
	v_max_f32_e32 v211, 0, v21
	v_fmac_f32_e32 v50, v202, v210
	v_fmac_f32_e32 v51, v203, v211
	v_add_f32_e32 v50, v50, v51
	v_ashrrev_i32_e32 v51, 31, v50
	s_waitcnt lgkmcnt(0)
	v_mfma_f32_32x32x16_bf16 v[212:227], v[82:85], v[196:199], v[212:227]
	v_or_b32_e32 v51, 0x80000000, v51
	s_cmpk_gt_i32 s11, 48
	s_cselect_b64 vcc, -1, 0
	v_xor_b32_e32 v50, v51, v50
	v_cndmask_b32_e32 v50, v123, v50, vcc
	global_store_dword v243, v50, s[8:9]
	v_mfma_f32_32x32x16_bf16 v[6:21], v[86:89], v[38:41], 0
	s_add_i32 m0, s10, 65536
	s_nop 0
	global_load_lds_dwordx4 v102, s[6:7]
	s_add_i32 m0, s10, 66560
	s_nop 0
	global_load_lds_dwordx4 v110, s[6:7]
	s_add_i32 m0, s10, 67584
	s_nop 0
	global_load_lds_dwordx4 v112, s[6:7]
	s_add_i32 m0, s10, 68608
	s_nop 0
	global_load_lds_dwordx4 v193, s[6:7]
	s_add_u32 s6, s6, 0x8000
	s_addc_u32 s7, s7, 0
	v_max_f32_e32 v108, 0, v212
	v_max_f32_e32 v109, 0, v213
	v_mul_f32_e32 v0, v22, v108
	v_mul_f32_e32 v1, v23, v109
	v_max_f32_e32 v210, 0, v214
	v_max_f32_e32 v211, 0, v215
	v_fmac_f32_e32 v0, v24, v210
	v_fmac_f32_e32 v1, v25, v211
	v_max_f32_e32 v108, 0, v216
	v_max_f32_e32 v109, 0, v217
	v_fmac_f32_e32 v0, v26, v108
	v_fmac_f32_e32 v1, v27, v109
	v_mfma_f32_32x32x16_bf16 v[6:21], v[90:93], v[42:45], v[6:21]
	v_max_f32_e32 v210, 0, v218
	v_max_f32_e32 v211, 0, v219
	v_fmac_f32_e32 v0, v28, v210
	v_fmac_f32_e32 v1, v29, v211
	v_max_f32_e32 v108, 0, v220
	v_max_f32_e32 v109, 0, v221
	v_fmac_f32_e32 v0, v30, v108
	v_fmac_f32_e32 v1, v31, v109
	v_max_f32_e32 v210, 0, v222
	v_max_f32_e32 v211, 0, v223
	v_fmac_f32_e32 v0, v32, v210
	v_fmac_f32_e32 v1, v33, v211
	v_mfma_f32_32x32x16_bf16 v[6:21], v[94:97], v[46:49], v[6:21]
	v_max_f32_e32 v108, 0, v224
	v_max_f32_e32 v109, 0, v225
	v_fmac_f32_e32 v0, v34, v108
	v_fmac_f32_e32 v1, v35, v109
	v_max_f32_e32 v210, 0, v226
	v_max_f32_e32 v211, 0, v227
	v_fmac_f32_e32 v0, v36, v210
	v_fmac_f32_e32 v1, v37, v211
	v_add_f32_e32 v0, v0, v1
	v_ashrrev_i32_e32 v1, 31, v0
	v_mfma_f32_32x32x16_bf16 v[6:21], v[98:101], v[196:199], v[6:21]
	s_waitcnt vmcnt(10)
	ds_read_b128 v[38:41], v5 offset:10496
	ds_read_b128 v[42:45], v52 offset:10496
	ds_read_b128 v[46:49], v55 offset:10496
	ds_read_b128 v[196:199], v56 offset:10496
	v_or_b32_e32 v1, 0x80000000, v1
	s_cmpk_gt_i32 s11, 56
	s_cselect_b64 vcc, -1, 0
	v_xor_b32_e32 v0, v1, v0
	v_cndmask_b32_e32 v139, v123, v0, vcc
	s_nop 3
	v_max_f32_e32 v108, 0, v6
	v_max_f32_e32 v109, 0, v7
	v_mul_f32_e32 v50, v244, v108
	v_mul_f32_e32 v51, v245, v109
	v_max_f32_e32 v210, 0, v8
	v_max_f32_e32 v211, 0, v9
	v_fmac_f32_e32 v50, v246, v210
	v_fmac_f32_e32 v51, v247, v211
	v_max_f32_e32 v108, 0, v10
	v_max_f32_e32 v109, 0, v11
	v_fmac_f32_e32 v50, v248, v108
	v_fmac_f32_e32 v51, v249, v109
	v_max_f32_e32 v210, 0, v12
	v_max_f32_e32 v211, 0, v13
	v_fmac_f32_e32 v50, v250, v210
	v_fmac_f32_e32 v51, v251, v211
	v_max_f32_e32 v108, 0, v14
	v_max_f32_e32 v109, 0, v15
	v_fmac_f32_e32 v50, v252, v108
	v_fmac_f32_e32 v51, v253, v109
	v_max_f32_e32 v210, 0, v16
	v_max_f32_e32 v211, 0, v17
	v_fmac_f32_e32 v50, v254, v210
	v_fmac_f32_e32 v51, v255, v211
	v_max_f32_e32 v108, 0, v18
	v_max_f32_e32 v109, 0, v19
	v_fmac_f32_e32 v50, v200, v108
	v_fmac_f32_e32 v51, v201, v109
	v_max_f32_e32 v210, 0, v20
	v_max_f32_e32 v211, 0, v21
	v_fmac_f32_e32 v50, v202, v210
	v_fmac_f32_e32 v51, v203, v211
	v_add_f32_e32 v50, v50, v51
	v_ashrrev_i32_e32 v51, 31, v50
	v_or_b32_e32 v51, 0x80000000, v51
	s_cmpk_gt_i32 s11, 56
	s_cselect_b64 vcc, -1, 0
	v_xor_b32_e32 v50, v51, v50
	v_cndmask_b32_e32 v50, v123, v50, vcc
	global_store_dword v243, v50, s[8:9] offset:2048
	s_add_u32 s8, s8, 0x1000
	s_addc_u32 s9, s9, 0
	s_cmpk_gt_i32 s81, 8
	s_cbranch_scc0 .Lix_fill_1
	s_waitcnt lgkmcnt(3)
	v_mfma_f32_32x32x16_bf16 v[212:227], v[70:73], v[38:41], 0
	s_add_i32 m0, s10, 98304
	s_nop 0
	global_load_lds_dwordx4 v102, s[6:7]
	s_waitcnt lgkmcnt(2)
	v_mfma_f32_32x32x16_bf16 v[212:227], v[74:77], v[42:45], v[212:227]
	s_add_i32 m0, s10, 99328
	s_nop 0
	global_load_lds_dwordx4 v110, s[6:7]
	s_waitcnt lgkmcnt(1)
	v_mfma_f32_32x32x16_bf16 v[212:227], v[78:81], v[46:49], v[212:227]
	s_add_i32 m0, s10, 100352
	s_nop 0
	global_load_lds_dwordx4 v112, s[6:7]
	s_waitcnt lgkmcnt(0)
	v_mfma_f32_32x32x16_bf16 v[212:227], v[82:85], v[196:199], v[212:227]
	s_add_i32 m0, s10, 101376
	s_nop 0
	global_load_lds_dwordx4 v193, s[6:7]
	s_add_u32 s6, s6, 0x8000
	s_addc_u32 s7, s7, 0
	v_mfma_f32_32x32x16_bf16 v[6:21], v[86:89], v[38:41], 0
	s_nop 7
	s_nop 2
	v_max_f32_e32 v108, 0, v212
	v_max_f32_e32 v109, 0, v213
	v_mul_f32_e32 v0, v22, v108
	v_mul_f32_e32 v1, v23, v109
	v_max_f32_e32 v210, 0, v214
	v_max_f32_e32 v211, 0, v215
	v_fmac_f32_e32 v0, v24, v210
	v_fmac_f32_e32 v1, v25, v211
	v_max_f32_e32 v108, 0, v216
	v_max_f32_e32 v109, 0, v217
	v_fmac_f32_e32 v0, v26, v108
	v_fmac_f32_e32 v1, v27, v109
	v_mfma_f32_32x32x16_bf16 v[6:21], v[90:93], v[42:45], v[6:21]
	v_max_f32_e32 v210, 0, v218
	v_max_f32_e32 v211, 0, v219
	v_fmac_f32_e32 v0, v28, v210
	v_fmac_f32_e32 v1, v29, v211
	v_max_f32_e32 v108, 0, v220
	v_max_f32_e32 v109, 0, v221
	v_fmac_f32_e32 v0, v30, v108
	v_fmac_f32_e32 v1, v31, v109
	v_max_f32_e32 v210, 0, v222
	v_max_f32_e32 v211, 0, v223
	v_fmac_f32_e32 v0, v32, v210
	v_fmac_f32_e32 v1, v33, v211
	v_mfma_f32_32x32x16_bf16 v[6:21], v[94:97], v[46:49], v[6:21]
	v_max_f32_e32 v108, 0, v224
	v_max_f32_e32 v109, 0, v225
	v_fmac_f32_e32 v0, v34, v108
	v_fmac_f32_e32 v1, v35, v109
	v_max_f32_e32 v210, 0, v226
	v_max_f32_e32 v211, 0, v227
	v_fmac_f32_e32 v0, v36, v210
	v_fmac_f32_e32 v1, v37, v211
	v_add_f32_e32 v0, v0, v1
	v_ashrrev_i32_e32 v1, 31, v0
	v_mfma_f32_32x32x16_bf16 v[6:21], v[98:101], v[196:199], v[6:21]
	s_waitcnt vmcnt(10)
	ds_read_b128 v[38:41], v5 offset:43264
	ds_read_b128 v[42:45], v52 offset:43264
	ds_read_b128 v[46:49], v55 offset:43264
	ds_read_b128 v[196:199], v56 offset:43264
	v_or_b32_e32 v1, 0x80000000, v1
	s_cmpk_gt_i32 s11, 64
	s_cselect_b64 vcc, -1, 0
	v_xor_b32_e32 v0, v1, v0
	v_cndmask_b32_e32 v142, v123, v0, vcc
	s_nop 3
	s_waitcnt lgkmcnt(3)
	v_mfma_f32_32x32x16_bf16 v[212:227], v[70:73], v[38:41], 0
	v_max_f32_e32 v108, 0, v6
	v_max_f32_e32 v109, 0, v7
	v_mul_f32_e32 v50, v244, v108
	v_mul_f32_e32 v51, v245, v109
	v_max_f32_e32 v210, 0, v8
	v_max_f32_e32 v211, 0, v9
	v_fmac_f32_e32 v50, v246, v210
	v_fmac_f32_e32 v51, v247, v211
	v_max_f32_e32 v108, 0, v10
	v_max_f32_e32 v109, 0, v11
	v_fmac_f32_e32 v50, v248, v108
	v_fmac_f32_e32 v51, v249, v109
	s_waitcnt lgkmcnt(2)
	v_mfma_f32_32x32x16_bf16 v[212:227], v[74:77], v[42:45], v[212:227]
	v_max_f32_e32 v210, 0, v12
	v_max_f32_e32 v211, 0, v13
	v_fmac_f32_e32 v50, v250, v210
	v_fmac_f32_e32 v51, v251, v211
	v_max_f32_e32 v108, 0, v14
	v_max_f32_e32 v109, 0, v15
	v_fmac_f32_e32 v50, v252, v108
	v_fmac_f32_e32 v51, v253, v109
	v_max_f32_e32 v210, 0, v16
	v_max_f32_e32 v211, 0, v17
	v_fmac_f32_e32 v50, v254, v210
	v_fmac_f32_e32 v51, v255, v211
	s_waitcnt lgkmcnt(1)
	v_mfma_f32_32x32x16_bf16 v[212:227], v[78:81], v[46:49], v[212:227]
	v_max_f32_e32 v108, 0, v18
	v_max_f32_e32 v109, 0, v19
	v_fmac_f32_e32 v50, v200, v108
	v_fmac_f32_e32 v51, v201, v109
	v_max_f32_e32 v210, 0, v20
	v_max_f32_e32 v211, 0, v21
	v_fmac_f32_e32 v50, v202, v210
	v_fmac_f32_e32 v51, v203, v211
	v_add_f32_e32 v50, v50, v51
	v_ashrrev_i32_e32 v51, 31, v50
	s_waitcnt lgkmcnt(0)
	v_mfma_f32_32x32x16_bf16 v[212:227], v[82:85], v[196:199], v[212:227]
	v_or_b32_e32 v51, 0x80000000, v51
	s_cmpk_gt_i32 s11, 64
	s_cselect_b64 vcc, -1, 0
	v_xor_b32_e32 v50, v51, v50
	v_cndmask_b32_e32 v50, v123, v50, vcc
	global_store_dword v243, v50, s[8:9]
	v_mfma_f32_32x32x16_bf16 v[6:21], v[86:89], v[38:41], 0
	s_add_i32 m0, s10, 0
	s_nop 0
	global_load_lds_dwordx4 v102, s[6:7]
	s_add_i32 m0, s10, 1024
	s_nop 0
	global_load_lds_dwordx4 v110, s[6:7]
	s_add_i32 m0, s10, 2048
	s_nop 0
	global_load_lds_dwordx4 v112, s[6:7]
	s_add_i32 m0, s10, 3072
	s_nop 0
	global_load_lds_dwordx4 v193, s[6:7]
	s_add_u32 s6, s6, 0x8000
	s_addc_u32 s7, s7, 0
	v_max_f32_e32 v108, 0, v212
	v_max_f32_e32 v109, 0, v213
	v_mul_f32_e32 v0, v22, v108
	v_mul_f32_e32 v1, v23, v109
	v_max_f32_e32 v210, 0, v214
	v_max_f32_e32 v211, 0, v215
	v_fmac_f32_e32 v0, v24, v210
	v_fmac_f32_e32 v1, v25, v211
	v_max_f32_e32 v108, 0, v216
	v_max_f32_e32 v109, 0, v217
	v_fmac_f32_e32 v0, v26, v108
	v_fmac_f32_e32 v1, v27, v109
	v_mfma_f32_32x32x16_bf16 v[6:21], v[90:93], v[42:45], v[6:21]
	v_max_f32_e32 v210, 0, v218
	v_max_f32_e32 v211, 0, v219
	v_fmac_f32_e32 v0, v28, v210
	v_fmac_f32_e32 v1, v29, v211
	v_max_f32_e32 v108, 0, v220
	v_max_f32_e32 v109, 0, v221
	v_fmac_f32_e32 v0, v30, v108
	v_fmac_f32_e32 v1, v31, v109
	v_max_f32_e32 v210, 0, v222
	v_max_f32_e32 v211, 0, v223
	v_fmac_f32_e32 v0, v32, v210
	v_fmac_f32_e32 v1, v33, v211
	v_mfma_f32_32x32x16_bf16 v[6:21], v[94:97], v[46:49], v[6:21]
	v_max_f32_e32 v108, 0, v224
	v_max_f32_e32 v109, 0, v225
	v_fmac_f32_e32 v0, v34, v108
	v_fmac_f32_e32 v1, v35, v109
	v_max_f32_e32 v210, 0, v226
	v_max_f32_e32 v211, 0, v227
	v_fmac_f32_e32 v0, v36, v210
	v_fmac_f32_e32 v1, v37, v211
	v_add_f32_e32 v0, v0, v1
	v_ashrrev_i32_e32 v1, 31, v0
	v_mfma_f32_32x32x16_bf16 v[6:21], v[98:101], v[196:199], v[6:21]
	s_waitcnt vmcnt(10)
	v_add_u32_e32 v228, 0x10000, v5
	ds_read_b128 v[38:41], v228 offset:10496
	v_add_u32_e32 v228, 0x10000, v52
	ds_read_b128 v[42:45], v228 offset:10496
	v_add_u32_e32 v228, 0x10000, v55
	ds_read_b128 v[46:49], v228 offset:10496
	v_add_u32_e32 v228, 0x10000, v56
	ds_read_b128 v[196:199], v228 offset:10496
	v_or_b32_e32 v1, 0x80000000, v1
	s_cmpk_gt_i32 s11, 72
	s_cselect_b64 vcc, -1, 0
	v_xor_b32_e32 v0, v1, v0
	v_cndmask_b32_e32 v141, v123, v0, vcc
	s_nop 3
	s_waitcnt lgkmcnt(3)
	v_mfma_f32_32x32x16_bf16 v[212:227], v[70:73], v[38:41], 0
	v_max_f32_e32 v108, 0, v6
	v_max_f32_e32 v109, 0, v7
	v_mul_f32_e32 v50, v244, v108
	v_mul_f32_e32 v51, v245, v109
	v_max_f32_e32 v210, 0, v8
	v_max_f32_e32 v211, 0, v9
	v_fmac_f32_e32 v50, v246, v210
	v_fmac_f32_e32 v51, v247, v211
	v_max_f32_e32 v108, 0, v10
	v_max_f32_e32 v109, 0, v11
	v_fmac_f32_e32 v50, v248, v108
	v_fmac_f32_e32 v51, v249, v109
	s_waitcnt lgkmcnt(2)
	v_mfma_f32_32x32x16_bf16 v[212:227], v[74:77], v[42:45], v[212:227]
	v_max_f32_e32 v210, 0, v12
	v_max_f32_e32 v211, 0, v13
	v_fmac_f32_e32 v50, v250, v210
	v_fmac_f32_e32 v51, v251, v211
	v_max_f32_e32 v108, 0, v14
	v_max_f32_e32 v109, 0, v15
	v_fmac_f32_e32 v50, v252, v108
	v_fmac_f32_e32 v51, v253, v109
	v_max_f32_e32 v210, 0, v16
	v_max_f32_e32 v211, 0, v17
	v_fmac_f32_e32 v50, v254, v210
	v_fmac_f32_e32 v51, v255, v211
	s_waitcnt lgkmcnt(1)
	v_mfma_f32_32x32x16_bf16 v[212:227], v[78:81], v[46:49], v[212:227]
	v_max_f32_e32 v108, 0, v18
	v_max_f32_e32 v109, 0, v19
	v_fmac_f32_e32 v50, v200, v108
	v_fmac_f32_e32 v51, v201, v109
	v_max_f32_e32 v210, 0, v20
	v_max_f32_e32 v211, 0, v21
	v_fmac_f32_e32 v50, v202, v210
	v_fmac_f32_e32 v51, v203, v211
	v_add_f32_e32 v50, v50, v51
	v_ashrrev_i32_e32 v51, 31, v50
	s_waitcnt lgkmcnt(0)
	v_mfma_f32_32x32x16_bf16 v[212:227], v[82:85], v[196:199], v[212:227]
	v_or_b32_e32 v51, 0x80000000, v51
	s_cmpk_gt_i32 s11, 72
	s_cselect_b64 vcc, -1, 0
	v_xor_b32_e32 v50, v51, v50
	v_cndmask_b32_e32 v50, v123, v50, vcc
	global_store_dword v243, v50, s[8:9] offset:2048
	s_add_u32 s8, s8, 0x1000
	s_addc_u32 s9, s9, 0
	v_mfma_f32_32x32x16_bf16 v[6:21], v[86:89], v[38:41], 0
	s_add_i32 m0, s10, 32768
	s_nop 0
	global_load_lds_dwordx4 v102, s[6:7]
	s_add_i32 m0, s10, 33792
	s_nop 0
	global_load_lds_dwordx4 v110, s[6:7]
	s_add_i32 m0, s10, 34816
	s_nop 0
	global_load_lds_dwordx4 v112, s[6:7]
	s_add_i32 m0, s10, 35840
	s_nop 0
	global_load_lds_dwordx4 v193, s[6:7]
	s_add_u32 s6, s6, 0x8000
	s_addc_u32 s7, s7, 0
	v_max_f32_e32 v108, 0, v212
	v_max_f32_e32 v109, 0, v213
	v_mul_f32_e32 v0, v22, v108
	v_mul_f32_e32 v1, v23, v109
	v_max_f32_e32 v210, 0, v214
	v_max_f32_e32 v211, 0, v215
	v_fmac_f32_e32 v0, v24, v210
	v_fmac_f32_e32 v1, v25, v211
	v_max_f32_e32 v108, 0, v216
	v_max_f32_e32 v109, 0, v217
	v_fmac_f32_e32 v0, v26, v108
	v_fmac_f32_e32 v1, v27, v109
	v_mfma_f32_32x32x16_bf16 v[6:21], v[90:93], v[42:45], v[6:21]
	v_max_f32_e32 v210, 0, v218
	v_max_f32_e32 v211, 0, v219
	v_fmac_f32_e32 v0, v28, v210
	v_fmac_f32_e32 v1, v29, v211
	v_max_f32_e32 v108, 0, v220
	v_max_f32_e32 v109, 0, v221
	v_fmac_f32_e32 v0, v30, v108
	v_fmac_f32_e32 v1, v31, v109
	v_max_f32_e32 v210, 0, v222
	v_max_f32_e32 v211, 0, v223
	v_fmac_f32_e32 v0, v32, v210
	v_fmac_f32_e32 v1, v33, v211
	v_mfma_f32_32x32x16_bf16 v[6:21], v[94:97], v[46:49], v[6:21]
	v_max_f32_e32 v108, 0, v224
	v_max_f32_e32 v109, 0, v225
	v_fmac_f32_e32 v0, v34, v108
	v_fmac_f32_e32 v1, v35, v109
	v_max_f32_e32 v210, 0, v226
	v_max_f32_e32 v211, 0, v227
	v_fmac_f32_e32 v0, v36, v210
	v_fmac_f32_e32 v1, v37, v211
	v_add_f32_e32 v0, v0, v1
	v_ashrrev_i32_e32 v1, 31, v0
	v_mfma_f32_32x32x16_bf16 v[6:21], v[98:101], v[196:199], v[6:21]
	s_waitcnt vmcnt(10)
	v_add_u32_e32 v228, 0x10000, v5
	ds_read_b128 v[38:41], v228 offset:43264
	v_add_u32_e32 v228, 0x10000, v52
	ds_read_b128 v[42:45], v228 offset:43264
	v_add_u32_e32 v228, 0x10000, v55
	ds_read_b128 v[46:49], v228 offset:43264
	v_add_u32_e32 v228, 0x10000, v56
	ds_read_b128 v[196:199], v228 offset:43264
	v_or_b32_e32 v1, 0x80000000, v1
	s_cmpk_gt_i32 s11, 80
	s_cselect_b64 vcc, -1, 0
	v_xor_b32_e32 v0, v1, v0
	v_cndmask_b32_e32 v144, v123, v0, vcc
	s_nop 3
	s_waitcnt lgkmcnt(3)
	v_mfma_f32_32x32x16_bf16 v[212:227], v[70:73], v[38:41], 0
	v_max_f32_e32 v108, 0, v6
	v_max_f32_e32 v109, 0, v7
	v_mul_f32_e32 v50, v244, v108
	v_mul_f32_e32 v51, v245, v109
	v_max_f32_e32 v210, 0, v8
	v_max_f32_e32 v211, 0, v9
	v_fmac_f32_e32 v50, v246, v210
	v_fmac_f32_e32 v51, v247, v211
	v_max_f32_e32 v108, 0, v10
	v_max_f32_e32 v109, 0, v11
	v_fmac_f32_e32 v50, v248, v108
	v_fmac_f32_e32 v51, v249, v109
	s_waitcnt lgkmcnt(2)
	v_mfma_f32_32x32x16_bf16 v[212:227], v[74:77], v[42:45], v[212:227]
	v_max_f32_e32 v210, 0, v12
	v_max_f32_e32 v211, 0, v13
	v_fmac_f32_e32 v50, v250, v210
	v_fmac_f32_e32 v51, v251, v211
	v_max_f32_e32 v108, 0, v14
	v_max_f32_e32 v109, 0, v15
	v_fmac_f32_e32 v50, v252, v108
	v_fmac_f32_e32 v51, v253, v109
	v_max_f32_e32 v210, 0, v16
	v_max_f32_e32 v211, 0, v17
	v_fmac_f32_e32 v50, v254, v210
	v_fmac_f32_e32 v51, v255, v211
	s_waitcnt lgkmcnt(1)
	v_mfma_f32_32x32x16_bf16 v[212:227], v[78:81], v[46:49], v[212:227]
	v_max_f32_e32 v108, 0, v18
	v_max_f32_e32 v109, 0, v19
	v_fmac_f32_e32 v50, v200, v108
	v_fmac_f32_e32 v51, v201, v109
	v_max_f32_e32 v210, 0, v20
	v_max_f32_e32 v211, 0, v21
	v_fmac_f32_e32 v50, v202, v210
	v_fmac_f32_e32 v51, v203, v211
	v_add_f32_e32 v50, v50, v51
	v_ashrrev_i32_e32 v51, 31, v50
	s_waitcnt lgkmcnt(0)
	v_mfma_f32_32x32x16_bf16 v[212:227], v[82:85], v[196:199], v[212:227]
	v_or_b32_e32 v51, 0x80000000, v51
	s_cmpk_gt_i32 s11, 80
	s_cselect_b64 vcc, -1, 0
	v_xor_b32_e32 v50, v51, v50
	v_cndmask_b32_e32 v50, v123, v50, vcc
	global_store_dword v243, v50, s[8:9]
	v_mfma_f32_32x32x16_bf16 v[6:21], v[86:89], v[38:41], 0
	s_add_i32 m0, s10, 65536
	s_nop 0
	global_load_lds_dwordx4 v102, s[6:7]
	s_add_i32 m0, s10, 66560
	s_nop 0
	global_load_lds_dwordx4 v110, s[6:7]
	s_add_i32 m0, s10, 67584
	s_nop 0
	global_load_lds_dwordx4 v112, s[6:7]
	s_add_i32 m0, s10, 68608
	s_nop 0
	global_load_lds_dwordx4 v193, s[6:7]
	s_add_u32 s6, s6, 0x8000
	s_addc_u32 s7, s7, 0
	v_max_f32_e32 v108, 0, v212
	v_max_f32_e32 v109, 0, v213
	v_mul_f32_e32 v0, v22, v108
	v_mul_f32_e32 v1, v23, v109
	v_max_f32_e32 v210, 0, v214
	v_max_f32_e32 v211, 0, v215
	v_fmac_f32_e32 v0, v24, v210
	v_fmac_f32_e32 v1, v25, v211
	v_max_f32_e32 v108, 0, v216
	v_max_f32_e32 v109, 0, v217
	v_fmac_f32_e32 v0, v26, v108
	v_fmac_f32_e32 v1, v27, v109
	v_mfma_f32_32x32x16_bf16 v[6:21], v[90:93], v[42:45], v[6:21]
	v_max_f32_e32 v210, 0, v218
	v_max_f32_e32 v211, 0, v219
	v_fmac_f32_e32 v0, v28, v210
	v_fmac_f32_e32 v1, v29, v211
	v_max_f32_e32 v108, 0, v220
	v_max_f32_e32 v109, 0, v221
	v_fmac_f32_e32 v0, v30, v108
	v_fmac_f32_e32 v1, v31, v109
	v_max_f32_e32 v210, 0, v222
	v_max_f32_e32 v211, 0, v223
	v_fmac_f32_e32 v0, v32, v210
	v_fmac_f32_e32 v1, v33, v211
	v_mfma_f32_32x32x16_bf16 v[6:21], v[94:97], v[46:49], v[6:21]
	v_max_f32_e32 v108, 0, v224
	v_max_f32_e32 v109, 0, v225
	v_fmac_f32_e32 v0, v34, v108
	v_fmac_f32_e32 v1, v35, v109
	v_max_f32_e32 v210, 0, v226
	v_max_f32_e32 v211, 0, v227
	v_fmac_f32_e32 v0, v36, v210
	v_fmac_f32_e32 v1, v37, v211
	v_add_f32_e32 v0, v0, v1
	v_ashrrev_i32_e32 v1, 31, v0
	v_mfma_f32_32x32x16_bf16 v[6:21], v[98:101], v[196:199], v[6:21]
	s_waitcnt vmcnt(10)
	ds_read_b128 v[38:41], v5 offset:10496
	ds_read_b128 v[42:45], v52 offset:10496
	ds_read_b128 v[46:49], v55 offset:10496
	ds_read_b128 v[196:199], v56 offset:10496
	v_or_b32_e32 v1, 0x80000000, v1
	s_cmpk_gt_i32 s11, 88
	s_cselect_b64 vcc, -1, 0
	v_xor_b32_e32 v0, v1, v0
	v_cndmask_b32_e32 v143, v123, v0, vcc
	s_nop 3
	s_waitcnt lgkmcnt(3)
	v_mfma_f32_32x32x16_bf16 v[212:227], v[70:73], v[38:41], 0
	v_max_f32_e32 v108, 0, v6
	v_max_f32_e32 v109, 0, v7
	v_mul_f32_e32 v50, v244, v108
	v_mul_f32_e32 v51, v245, v109
	v_max_f32_e32 v210, 0, v8
	v_max_f32_e32 v211, 0, v9
	v_fmac_f32_e32 v50, v246, v210
	v_fmac_f32_e32 v51, v247, v211
	v_max_f32_e32 v108, 0, v10
	v_max_f32_e32 v109, 0, v11
	v_fmac_f32_e32 v50, v248, v108
	v_fmac_f32_e32 v51, v249, v109
	s_waitcnt lgkmcnt(2)
	v_mfma_f32_32x32x16_bf16 v[212:227], v[74:77], v[42:45], v[212:227]
	v_max_f32_e32 v210, 0, v12
	v_max_f32_e32 v211, 0, v13
	v_fmac_f32_e32 v50, v250, v210
	v_fmac_f32_e32 v51, v251, v211
	v_max_f32_e32 v108, 0, v14
	v_max_f32_e32 v109, 0, v15
	v_fmac_f32_e32 v50, v252, v108
	v_fmac_f32_e32 v51, v253, v109
	v_max_f32_e32 v210, 0, v16
	v_max_f32_e32 v211, 0, v17
	v_fmac_f32_e32 v50, v254, v210
	v_fmac_f32_e32 v51, v255, v211
	s_waitcnt lgkmcnt(1)
	v_mfma_f32_32x32x16_bf16 v[212:227], v[78:81], v[46:49], v[212:227]
	v_max_f32_e32 v108, 0, v18
	v_max_f32_e32 v109, 0, v19
	v_fmac_f32_e32 v50, v200, v108
	v_fmac_f32_e32 v51, v201, v109
	v_max_f32_e32 v210, 0, v20
	v_max_f32_e32 v211, 0, v21
	v_fmac_f32_e32 v50, v202, v210
	v_fmac_f32_e32 v51, v203, v211
	v_add_f32_e32 v50, v50, v51
	v_ashrrev_i32_e32 v51, 31, v50
	s_waitcnt lgkmcnt(0)
	v_mfma_f32_32x32x16_bf16 v[212:227], v[82:85], v[196:199], v[212:227]
	v_or_b32_e32 v51, 0x80000000, v51
	s_cmpk_gt_i32 s11, 88
	s_cselect_b64 vcc, -1, 0
	v_xor_b32_e32 v50, v51, v50
	v_cndmask_b32_e32 v50, v123, v50, vcc
	global_store_dword v243, v50, s[8:9] offset:2048
	s_add_u32 s8, s8, 0x1000
	s_addc_u32 s9, s9, 0
	v_mfma_f32_32x32x16_bf16 v[6:21], v[86:89], v[38:41], 0
	s_add_i32 m0, s10, 98304
	s_nop 0
	global_load_lds_dwordx4 v102, s[6:7]
	s_add_i32 m0, s10, 99328
	s_nop 0
	global_load_lds_dwordx4 v110, s[6:7]
	s_add_i32 m0, s10, 100352
	s_nop 0
	global_load_lds_dwordx4 v112, s[6:7]
	s_add_i32 m0, s10, 101376
	s_nop 0
	global_load_lds_dwordx4 v193, s[6:7]
	s_add_u32 s6, s6, 0x8000
	s_addc_u32 s7, s7, 0
	v_max_f32_e32 v108, 0, v212
	v_max_f32_e32 v109, 0, v213
	v_mul_f32_e32 v0, v22, v108
	v_mul_f32_e32 v1, v23, v109
	v_max_f32_e32 v210, 0, v214
	v_max_f32_e32 v211, 0, v215
	v_fmac_f32_e32 v0, v24, v210
	v_fmac_f32_e32 v1, v25, v211
	v_max_f32_e32 v108, 0, v216
	v_max_f32_e32 v109, 0, v217
	v_fmac_f32_e32 v0, v26, v108
	v_fmac_f32_e32 v1, v27, v109
	v_mfma_f32_32x32x16_bf16 v[6:21], v[90:93], v[42:45], v[6:21]
	v_max_f32_e32 v210, 0, v218
	v_max_f32_e32 v211, 0, v219
	v_fmac_f32_e32 v0, v28, v210
	v_fmac_f32_e32 v1, v29, v211
	v_max_f32_e32 v108, 0, v220
	v_max_f32_e32 v109, 0, v221
	v_fmac_f32_e32 v0, v30, v108
	v_fmac_f32_e32 v1, v31, v109
	v_max_f32_e32 v210, 0, v222
	v_max_f32_e32 v211, 0, v223
	v_fmac_f32_e32 v0, v32, v210
	v_fmac_f32_e32 v1, v33, v211
	v_mfma_f32_32x32x16_bf16 v[6:21], v[94:97], v[46:49], v[6:21]
	v_max_f32_e32 v108, 0, v224
	v_max_f32_e32 v109, 0, v225
	v_fmac_f32_e32 v0, v34, v108
	v_fmac_f32_e32 v1, v35, v109
	v_max_f32_e32 v210, 0, v226
	v_max_f32_e32 v211, 0, v227
	v_fmac_f32_e32 v0, v36, v210
	v_fmac_f32_e32 v1, v37, v211
	v_add_f32_e32 v0, v0, v1
	v_ashrrev_i32_e32 v1, 31, v0
	v_mfma_f32_32x32x16_bf16 v[6:21], v[98:101], v[196:199], v[6:21]
	s_waitcnt vmcnt(10)
	ds_read_b128 v[38:41], v5 offset:43264
	ds_read_b128 v[42:45], v52 offset:43264
	ds_read_b128 v[46:49], v55 offset:43264
	ds_read_b128 v[196:199], v56 offset:43264
	v_or_b32_e32 v1, 0x80000000, v1
	s_cmpk_gt_i32 s11, 96
	s_cselect_b64 vcc, -1, 0
	v_xor_b32_e32 v0, v1, v0
	v_cndmask_b32_e32 v146, v123, v0, vcc
	s_nop 3
	s_waitcnt lgkmcnt(3)
	v_mfma_f32_32x32x16_bf16 v[212:227], v[70:73], v[38:41], 0
	v_max_f32_e32 v108, 0, v6
	v_max_f32_e32 v109, 0, v7
	v_mul_f32_e32 v50, v244, v108
	v_mul_f32_e32 v51, v245, v109
	v_max_f32_e32 v210, 0, v8
	v_max_f32_e32 v211, 0, v9
	v_fmac_f32_e32 v50, v246, v210
	v_fmac_f32_e32 v51, v247, v211
	v_max_f32_e32 v108, 0, v10
	v_max_f32_e32 v109, 0, v11
	v_fmac_f32_e32 v50, v248, v108
	v_fmac_f32_e32 v51, v249, v109
	s_waitcnt lgkmcnt(2)
	v_mfma_f32_32x32x16_bf16 v[212:227], v[74:77], v[42:45], v[212:227]
	v_max_f32_e32 v210, 0, v12
	v_max_f32_e32 v211, 0, v13
	v_fmac_f32_e32 v50, v250, v210
	v_fmac_f32_e32 v51, v251, v211
	v_max_f32_e32 v108, 0, v14
	v_max_f32_e32 v109, 0, v15
	v_fmac_f32_e32 v50, v252, v108
	v_fmac_f32_e32 v51, v253, v109
	v_max_f32_e32 v210, 0, v16
	v_max_f32_e32 v211, 0, v17
	v_fmac_f32_e32 v50, v254, v210
	v_fmac_f32_e32 v51, v255, v211
	s_waitcnt lgkmcnt(1)
	v_mfma_f32_32x32x16_bf16 v[212:227], v[78:81], v[46:49], v[212:227]
	v_max_f32_e32 v108, 0, v18
	v_max_f32_e32 v109, 0, v19
	v_fmac_f32_e32 v50, v200, v108
	v_fmac_f32_e32 v51, v201, v109
	v_max_f32_e32 v210, 0, v20
	v_max_f32_e32 v211, 0, v21
	v_fmac_f32_e32 v50, v202, v210
	v_fmac_f32_e32 v51, v203, v211
	v_add_f32_e32 v50, v50, v51
	v_ashrrev_i32_e32 v51, 31, v50
	s_waitcnt lgkmcnt(0)
	v_mfma_f32_32x32x16_bf16 v[212:227], v[82:85], v[196:199], v[212:227]
	v_or_b32_e32 v51, 0x80000000, v51
	s_cmpk_gt_i32 s11, 96
	s_cselect_b64 vcc, -1, 0
	v_xor_b32_e32 v50, v51, v50
	v_cndmask_b32_e32 v50, v123, v50, vcc
	global_store_dword v243, v50, s[8:9]
	v_mfma_f32_32x32x16_bf16 v[6:21], v[86:89], v[38:41], 0
	s_add_i32 m0, s10, 0
	s_nop 0
	global_load_lds_dwordx4 v102, s[6:7]
	s_add_i32 m0, s10, 1024
	s_nop 0
	global_load_lds_dwordx4 v110, s[6:7]
	s_add_i32 m0, s10, 2048
	s_nop 0
	global_load_lds_dwordx4 v112, s[6:7]
	s_add_i32 m0, s10, 3072
	s_nop 0
	global_load_lds_dwordx4 v193, s[6:7]
	s_add_u32 s6, s6, 0x8000
	s_addc_u32 s7, s7, 0
	v_max_f32_e32 v108, 0, v212
	v_max_f32_e32 v109, 0, v213
	v_mul_f32_e32 v0, v22, v108
	v_mul_f32_e32 v1, v23, v109
	v_max_f32_e32 v210, 0, v214
	v_max_f32_e32 v211, 0, v215
	v_fmac_f32_e32 v0, v24, v210
	v_fmac_f32_e32 v1, v25, v211
	v_max_f32_e32 v108, 0, v216
	v_max_f32_e32 v109, 0, v217
	v_fmac_f32_e32 v0, v26, v108
	v_fmac_f32_e32 v1, v27, v109
	v_mfma_f32_32x32x16_bf16 v[6:21], v[90:93], v[42:45], v[6:21]
	v_max_f32_e32 v210, 0, v218
	v_max_f32_e32 v211, 0, v219
	v_fmac_f32_e32 v0, v28, v210
	v_fmac_f32_e32 v1, v29, v211
	v_max_f32_e32 v108, 0, v220
	v_max_f32_e32 v109, 0, v221
	v_fmac_f32_e32 v0, v30, v108
	v_fmac_f32_e32 v1, v31, v109
	v_max_f32_e32 v210, 0, v222
	v_max_f32_e32 v211, 0, v223
	v_fmac_f32_e32 v0, v32, v210
	v_fmac_f32_e32 v1, v33, v211
	v_mfma_f32_32x32x16_bf16 v[6:21], v[94:97], v[46:49], v[6:21]
	v_max_f32_e32 v108, 0, v224
	v_max_f32_e32 v109, 0, v225
	v_fmac_f32_e32 v0, v34, v108
	v_fmac_f32_e32 v1, v35, v109
	v_max_f32_e32 v210, 0, v226
	v_max_f32_e32 v211, 0, v227
	v_fmac_f32_e32 v0, v36, v210
	v_fmac_f32_e32 v1, v37, v211
	v_add_f32_e32 v0, v0, v1
	v_ashrrev_i32_e32 v1, 31, v0
	v_mfma_f32_32x32x16_bf16 v[6:21], v[98:101], v[196:199], v[6:21]
	s_waitcnt vmcnt(10)
	v_add_u32_e32 v228, 0x10000, v5
	ds_read_b128 v[38:41], v228 offset:10496
	v_add_u32_e32 v228, 0x10000, v52
	ds_read_b128 v[42:45], v228 offset:10496
	v_add_u32_e32 v228, 0x10000, v55
	ds_read_b128 v[46:49], v228 offset:10496
	v_add_u32_e32 v228, 0x10000, v56
	ds_read_b128 v[196:199], v228 offset:10496
	v_or_b32_e32 v1, 0x80000000, v1
	s_cmpk_gt_i32 s11, 104
	s_cselect_b64 vcc, -1, 0
	v_xor_b32_e32 v0, v1, v0
	v_cndmask_b32_e32 v145, v123, v0, vcc
	s_nop 3
	s_waitcnt lgkmcnt(3)
	v_mfma_f32_32x32x16_bf16 v[212:227], v[70:73], v[38:41], 0
	v_max_f32_e32 v108, 0, v6
	v_max_f32_e32 v109, 0, v7
	v_mul_f32_e32 v50, v244, v108
	v_mul_f32_e32 v51, v245, v109
	v_max_f32_e32 v210, 0, v8
	v_max_f32_e32 v211, 0, v9
	v_fmac_f32_e32 v50, v246, v210
	v_fmac_f32_e32 v51, v247, v211
	v_max_f32_e32 v108, 0, v10
	v_max_f32_e32 v109, 0, v11
	v_fmac_f32_e32 v50, v248, v108
	v_fmac_f32_e32 v51, v249, v109
	s_waitcnt lgkmcnt(2)
	v_mfma_f32_32x32x16_bf16 v[212:227], v[74:77], v[42:45], v[212:227]
	v_max_f32_e32 v210, 0, v12
	v_max_f32_e32 v211, 0, v13
	v_fmac_f32_e32 v50, v250, v210
	v_fmac_f32_e32 v51, v251, v211
	v_max_f32_e32 v108, 0, v14
	v_max_f32_e32 v109, 0, v15
	v_fmac_f32_e32 v50, v252, v108
	v_fmac_f32_e32 v51, v253, v109
	v_max_f32_e32 v210, 0, v16
	v_max_f32_e32 v211, 0, v17
	v_fmac_f32_e32 v50, v254, v210
	v_fmac_f32_e32 v51, v255, v211
	s_waitcnt lgkmcnt(1)
	v_mfma_f32_32x32x16_bf16 v[212:227], v[78:81], v[46:49], v[212:227]
	v_max_f32_e32 v108, 0, v18
	v_max_f32_e32 v109, 0, v19
	v_fmac_f32_e32 v50, v200, v108
	v_fmac_f32_e32 v51, v201, v109
	v_max_f32_e32 v210, 0, v20
	v_max_f32_e32 v211, 0, v21
	v_fmac_f32_e32 v50, v202, v210
	v_fmac_f32_e32 v51, v203, v211
	v_add_f32_e32 v50, v50, v51
	v_ashrrev_i32_e32 v51, 31, v50
	s_waitcnt lgkmcnt(0)
	v_mfma_f32_32x32x16_bf16 v[212:227], v[82:85], v[196:199], v[212:227]
	v_or_b32_e32 v51, 0x80000000, v51
	s_cmpk_gt_i32 s11, 104
	s_cselect_b64 vcc, -1, 0
	v_xor_b32_e32 v50, v51, v50
	v_cndmask_b32_e32 v50, v123, v50, vcc
	global_store_dword v243, v50, s[8:9] offset:2048
	s_add_u32 s8, s8, 0x1000
	s_addc_u32 s9, s9, 0
	v_mfma_f32_32x32x16_bf16 v[6:21], v[86:89], v[38:41], 0
	s_add_i32 m0, s10, 32768
	s_nop 0
	global_load_lds_dwordx4 v102, s[6:7]
	s_add_i32 m0, s10, 33792
	s_nop 0
	global_load_lds_dwordx4 v110, s[6:7]
	s_add_i32 m0, s10, 34816
	s_nop 0
	global_load_lds_dwordx4 v112, s[6:7]
	s_add_i32 m0, s10, 35840
	s_nop 0
	global_load_lds_dwordx4 v193, s[6:7]
	s_add_u32 s6, s6, 0x8000
	s_addc_u32 s7, s7, 0
	v_max_f32_e32 v108, 0, v212
	v_max_f32_e32 v109, 0, v213
	v_mul_f32_e32 v0, v22, v108
	v_mul_f32_e32 v1, v23, v109
	v_max_f32_e32 v210, 0, v214
	v_max_f32_e32 v211, 0, v215
	v_fmac_f32_e32 v0, v24, v210
	v_fmac_f32_e32 v1, v25, v211
	v_max_f32_e32 v108, 0, v216
	v_max_f32_e32 v109, 0, v217
	v_fmac_f32_e32 v0, v26, v108
	v_fmac_f32_e32 v1, v27, v109
	v_mfma_f32_32x32x16_bf16 v[6:21], v[90:93], v[42:45], v[6:21]
	v_max_f32_e32 v210, 0, v218
	v_max_f32_e32 v211, 0, v219
	v_fmac_f32_e32 v0, v28, v210
	v_fmac_f32_e32 v1, v29, v211
	v_max_f32_e32 v108, 0, v220
	v_max_f32_e32 v109, 0, v221
	v_fmac_f32_e32 v0, v30, v108
	v_fmac_f32_e32 v1, v31, v109
	v_max_f32_e32 v210, 0, v222
	v_max_f32_e32 v211, 0, v223
	v_fmac_f32_e32 v0, v32, v210
	v_fmac_f32_e32 v1, v33, v211
	v_mfma_f32_32x32x16_bf16 v[6:21], v[94:97], v[46:49], v[6:21]
	v_max_f32_e32 v108, 0, v224
	v_max_f32_e32 v109, 0, v225
	v_fmac_f32_e32 v0, v34, v108
	v_fmac_f32_e32 v1, v35, v109
	v_max_f32_e32 v210, 0, v226
	v_max_f32_e32 v211, 0, v227
	v_fmac_f32_e32 v0, v36, v210
	v_fmac_f32_e32 v1, v37, v211
	v_add_f32_e32 v0, v0, v1
	v_ashrrev_i32_e32 v1, 31, v0
	v_mfma_f32_32x32x16_bf16 v[6:21], v[98:101], v[196:199], v[6:21]
	s_waitcnt vmcnt(10)
	v_add_u32_e32 v228, 0x10000, v5
	ds_read_b128 v[38:41], v228 offset:43264
	v_add_u32_e32 v228, 0x10000, v52
	ds_read_b128 v[42:45], v228 offset:43264
	v_add_u32_e32 v228, 0x10000, v55
	ds_read_b128 v[46:49], v228 offset:43264
	v_add_u32_e32 v228, 0x10000, v56
	ds_read_b128 v[196:199], v228 offset:43264
	v_or_b32_e32 v1, 0x80000000, v1
	s_cmpk_gt_i32 s11, 112
	s_cselect_b64 vcc, -1, 0
	v_xor_b32_e32 v0, v1, v0
	v_cndmask_b32_e32 v147, v123, v0, vcc
	s_nop 3
	s_waitcnt lgkmcnt(3)
	v_mfma_f32_32x32x16_bf16 v[212:227], v[70:73], v[38:41], 0
	v_max_f32_e32 v108, 0, v6
	v_max_f32_e32 v109, 0, v7
	v_mul_f32_e32 v50, v244, v108
	v_mul_f32_e32 v51, v245, v109
	v_max_f32_e32 v210, 0, v8
	v_max_f32_e32 v211, 0, v9
	v_fmac_f32_e32 v50, v246, v210
	v_fmac_f32_e32 v51, v247, v211
	v_max_f32_e32 v108, 0, v10
	v_max_f32_e32 v109, 0, v11
	v_fmac_f32_e32 v50, v248, v108
	v_fmac_f32_e32 v51, v249, v109
	s_waitcnt lgkmcnt(2)
	v_mfma_f32_32x32x16_bf16 v[212:227], v[74:77], v[42:45], v[212:227]
	v_max_f32_e32 v210, 0, v12
	v_max_f32_e32 v211, 0, v13
	v_fmac_f32_e32 v50, v250, v210
	v_fmac_f32_e32 v51, v251, v211
	v_max_f32_e32 v108, 0, v14
	v_max_f32_e32 v109, 0, v15
	v_fmac_f32_e32 v50, v252, v108
	v_fmac_f32_e32 v51, v253, v109
	v_max_f32_e32 v210, 0, v16
	v_max_f32_e32 v211, 0, v17
	v_fmac_f32_e32 v50, v254, v210
	v_fmac_f32_e32 v51, v255, v211
	s_waitcnt lgkmcnt(1)
	v_mfma_f32_32x32x16_bf16 v[212:227], v[78:81], v[46:49], v[212:227]
	v_max_f32_e32 v108, 0, v18
	v_max_f32_e32 v109, 0, v19
	v_fmac_f32_e32 v50, v200, v108
	v_fmac_f32_e32 v51, v201, v109
	v_max_f32_e32 v210, 0, v20
	v_max_f32_e32 v211, 0, v21
	v_fmac_f32_e32 v50, v202, v210
	v_fmac_f32_e32 v51, v203, v211
	v_add_f32_e32 v50, v50, v51
	v_ashrrev_i32_e32 v51, 31, v50
	s_waitcnt lgkmcnt(0)
	v_mfma_f32_32x32x16_bf16 v[212:227], v[82:85], v[196:199], v[212:227]
	v_or_b32_e32 v51, 0x80000000, v51
	s_cmpk_gt_i32 s11, 112
	s_cselect_b64 vcc, -1, 0
	v_xor_b32_e32 v50, v51, v50
	v_cndmask_b32_e32 v50, v123, v50, vcc
	global_store_dword v243, v50, s[8:9]
	v_mfma_f32_32x32x16_bf16 v[6:21], v[86:89], v[38:41], 0
	s_add_i32 m0, s10, 65536
	s_nop 0
	global_load_lds_dwordx4 v102, s[6:7]
	s_add_i32 m0, s10, 66560
	s_nop 0
	global_load_lds_dwordx4 v110, s[6:7]
	s_add_i32 m0, s10, 67584
	s_nop 0
	global_load_lds_dwordx4 v112, s[6:7]
	s_add_i32 m0, s10, 68608
	s_nop 0
	global_load_lds_dwordx4 v193, s[6:7]
	s_add_u32 s6, s6, 0x8000
	s_addc_u32 s7, s7, 0
	v_max_f32_e32 v108, 0, v212
	v_max_f32_e32 v109, 0, v213
	v_mul_f32_e32 v0, v22, v108
	v_mul_f32_e32 v1, v23, v109
	v_max_f32_e32 v210, 0, v214
	v_max_f32_e32 v211, 0, v215
	v_fmac_f32_e32 v0, v24, v210
	v_fmac_f32_e32 v1, v25, v211
	v_max_f32_e32 v108, 0, v216
	v_max_f32_e32 v109, 0, v217
	v_fmac_f32_e32 v0, v26, v108
	v_fmac_f32_e32 v1, v27, v109
	v_mfma_f32_32x32x16_bf16 v[6:21], v[90:93], v[42:45], v[6:21]
	v_max_f32_e32 v210, 0, v218
	v_max_f32_e32 v211, 0, v219
	v_fmac_f32_e32 v0, v28, v210
	v_fmac_f32_e32 v1, v29, v211
	v_max_f32_e32 v108, 0, v220
	v_max_f32_e32 v109, 0, v221
	v_fmac_f32_e32 v0, v30, v108
	v_fmac_f32_e32 v1, v31, v109
	v_max_f32_e32 v210, 0, v222
	v_max_f32_e32 v211, 0, v223
	v_fmac_f32_e32 v0, v32, v210
	v_fmac_f32_e32 v1, v33, v211
	v_mfma_f32_32x32x16_bf16 v[6:21], v[94:97], v[46:49], v[6:21]
	v_max_f32_e32 v108, 0, v224
	v_max_f32_e32 v109, 0, v225
	v_fmac_f32_e32 v0, v34, v108
	v_fmac_f32_e32 v1, v35, v109
	v_max_f32_e32 v210, 0, v226
	v_max_f32_e32 v211, 0, v227
	v_fmac_f32_e32 v0, v36, v210
	v_fmac_f32_e32 v1, v37, v211
	v_add_f32_e32 v0, v0, v1
	v_ashrrev_i32_e32 v1, 31, v0
	v_mfma_f32_32x32x16_bf16 v[6:21], v[98:101], v[196:199], v[6:21]
	s_waitcnt vmcnt(10)
	ds_read_b128 v[38:41], v5 offset:10496
	ds_read_b128 v[42:45], v52 offset:10496
	ds_read_b128 v[46:49], v55 offset:10496
	ds_read_b128 v[196:199], v56 offset:10496
	v_or_b32_e32 v1, 0x80000000, v1
	s_cmpk_gt_i32 s11, 120
	s_cselect_b64 vcc, -1, 0
	v_xor_b32_e32 v0, v1, v0
	v_cndmask_b32_e32 v136, v123, v0, vcc
	s_nop 3
	v_max_f32_e32 v108, 0, v6
	v_max_f32_e32 v109, 0, v7
	v_mul_f32_e32 v50, v244, v108
	v_mul_f32_e32 v51, v245, v109
	v_max_f32_e32 v210, 0, v8
	v_max_f32_e32 v211, 0, v9
	v_fmac_f32_e32 v50, v246, v210
	v_fmac_f32_e32 v51, v247, v211
	v_max_f32_e32 v108, 0, v10
	v_max_f32_e32 v109, 0, v11
	v_fmac_f32_e32 v50, v248, v108
	v_fmac_f32_e32 v51, v249, v109
	v_max_f32_e32 v210, 0, v12
	v_max_f32_e32 v211, 0, v13
	v_fmac_f32_e32 v50, v250, v210
	v_fmac_f32_e32 v51, v251, v211
	v_max_f32_e32 v108, 0, v14
	v_max_f32_e32 v109, 0, v15
	v_fmac_f32_e32 v50, v252, v108
	v_fmac_f32_e32 v51, v253, v109
	v_max_f32_e32 v210, 0, v16
	v_max_f32_e32 v211, 0, v17
	v_fmac_f32_e32 v50, v254, v210
	v_fmac_f32_e32 v51, v255, v211
	v_max_f32_e32 v108, 0, v18
	v_max_f32_e32 v109, 0, v19
	v_fmac_f32_e32 v50, v200, v108
	v_fmac_f32_e32 v51, v201, v109
	v_max_f32_e32 v210, 0, v20
	v_max_f32_e32 v211, 0, v21
	v_fmac_f32_e32 v50, v202, v210
	v_fmac_f32_e32 v51, v203, v211
	v_add_f32_e32 v50, v50, v51
	v_ashrrev_i32_e32 v51, 31, v50
	v_or_b32_e32 v51, 0x80000000, v51
	s_cmpk_gt_i32 s11, 120
	s_cselect_b64 vcc, -1, 0
	v_xor_b32_e32 v50, v51, v50
	v_cndmask_b32_e32 v50, v123, v50, vcc
	global_store_dword v243, v50, s[8:9] offset:2048
	s_add_u32 s8, s8, 0x1000
	s_addc_u32 s9, s9, 0
	s_cmpk_gt_i32 s81, 16
	s_cbranch_scc0 .Lix_fill_2
	s_waitcnt lgkmcnt(3)
	v_mfma_f32_32x32x16_bf16 v[212:227], v[70:73], v[38:41], 0
	s_add_i32 m0, s10, 98304
	s_nop 0
	global_load_lds_dwordx4 v102, s[6:7]
	s_waitcnt lgkmcnt(2)
	v_mfma_f32_32x32x16_bf16 v[212:227], v[74:77], v[42:45], v[212:227]
	s_add_i32 m0, s10, 99328
	s_nop 0
	global_load_lds_dwordx4 v110, s[6:7]
	s_waitcnt lgkmcnt(1)
	v_mfma_f32_32x32x16_bf16 v[212:227], v[78:81], v[46:49], v[212:227]
	s_add_i32 m0, s10, 100352
	s_nop 0
	global_load_lds_dwordx4 v112, s[6:7]
	s_waitcnt lgkmcnt(0)
	v_mfma_f32_32x32x16_bf16 v[212:227], v[82:85], v[196:199], v[212:227]
	s_add_i32 m0, s10, 101376
	s_nop 0
	global_load_lds_dwordx4 v193, s[6:7]
	s_add_u32 s6, s6, 0x8000
	s_addc_u32 s7, s7, 0
	v_mfma_f32_32x32x16_bf16 v[6:21], v[86:89], v[38:41], 0
	s_nop 7
	s_nop 2
	v_max_f32_e32 v108, 0, v212
	v_max_f32_e32 v109, 0, v213
	v_mul_f32_e32 v0, v22, v108
	v_mul_f32_e32 v1, v23, v109
	v_max_f32_e32 v210, 0, v214
	v_max_f32_e32 v211, 0, v215
	v_fmac_f32_e32 v0, v24, v210
	v_fmac_f32_e32 v1, v25, v211
	v_max_f32_e32 v108, 0, v216
	v_max_f32_e32 v109, 0, v217
	v_fmac_f32_e32 v0, v26, v108
	v_fmac_f32_e32 v1, v27, v109
	v_mfma_f32_32x32x16_bf16 v[6:21], v[90:93], v[42:45], v[6:21]
	v_max_f32_e32 v210, 0, v218
	v_max_f32_e32 v211, 0, v219
	v_fmac_f32_e32 v0, v28, v210
	v_fmac_f32_e32 v1, v29, v211
	v_max_f32_e32 v108, 0, v220
	v_max_f32_e32 v109, 0, v221
	v_fmac_f32_e32 v0, v30, v108
	v_fmac_f32_e32 v1, v31, v109
	v_max_f32_e32 v210, 0, v222
	v_max_f32_e32 v211, 0, v223
	v_fmac_f32_e32 v0, v32, v210
	v_fmac_f32_e32 v1, v33, v211
	v_mfma_f32_32x32x16_bf16 v[6:21], v[94:97], v[46:49], v[6:21]
	v_max_f32_e32 v108, 0, v224
	v_max_f32_e32 v109, 0, v225
	v_fmac_f32_e32 v0, v34, v108
	v_fmac_f32_e32 v1, v35, v109
	v_max_f32_e32 v210, 0, v226
	v_max_f32_e32 v211, 0, v227
	v_fmac_f32_e32 v0, v36, v210
	v_fmac_f32_e32 v1, v37, v211
	v_add_f32_e32 v0, v0, v1
	v_ashrrev_i32_e32 v1, 31, v0
	v_mfma_f32_32x32x16_bf16 v[6:21], v[98:101], v[196:199], v[6:21]
	s_waitcnt vmcnt(10)
	ds_read_b128 v[38:41], v5 offset:43264
	ds_read_b128 v[42:45], v52 offset:43264
	ds_read_b128 v[46:49], v55 offset:43264
	ds_read_b128 v[196:199], v56 offset:43264
	v_or_b32_e32 v1, 0x80000000, v1
	s_cmpk_gt_i32 s11, 128
	s_cselect_b64 vcc, -1, 0
	v_xor_b32_e32 v0, v1, v0
	v_cndmask_b32_e32 v149, v123, v0, vcc
	s_nop 3
	s_waitcnt lgkmcnt(3)
	v_mfma_f32_32x32x16_bf16 v[212:227], v[70:73], v[38:41], 0
	v_max_f32_e32 v108, 0, v6
	v_max_f32_e32 v109, 0, v7
	v_mul_f32_e32 v50, v244, v108
	v_mul_f32_e32 v51, v245, v109
	v_max_f32_e32 v210, 0, v8
	v_max_f32_e32 v211, 0, v9
	v_fmac_f32_e32 v50, v246, v210
	v_fmac_f32_e32 v51, v247, v211
	v_max_f32_e32 v108, 0, v10
	v_max_f32_e32 v109, 0, v11
	v_fmac_f32_e32 v50, v248, v108
	v_fmac_f32_e32 v51, v249, v109
	s_waitcnt lgkmcnt(2)
	v_mfma_f32_32x32x16_bf16 v[212:227], v[74:77], v[42:45], v[212:227]
	v_max_f32_e32 v210, 0, v12
	v_max_f32_e32 v211, 0, v13
	v_fmac_f32_e32 v50, v250, v210
	v_fmac_f32_e32 v51, v251, v211
	v_max_f32_e32 v108, 0, v14
	v_max_f32_e32 v109, 0, v15
	v_fmac_f32_e32 v50, v252, v108
	v_fmac_f32_e32 v51, v253, v109
	v_max_f32_e32 v210, 0, v16
	v_max_f32_e32 v211, 0, v17
	v_fmac_f32_e32 v50, v254, v210
	v_fmac_f32_e32 v51, v255, v211
	s_waitcnt lgkmcnt(1)
	v_mfma_f32_32x32x16_bf16 v[212:227], v[78:81], v[46:49], v[212:227]
	v_max_f32_e32 v108, 0, v18
	v_max_f32_e32 v109, 0, v19
	v_fmac_f32_e32 v50, v200, v108
	v_fmac_f32_e32 v51, v201, v109
	v_max_f32_e32 v210, 0, v20
	v_max_f32_e32 v211, 0, v21
	v_fmac_f32_e32 v50, v202, v210
	v_fmac_f32_e32 v51, v203, v211
	v_add_f32_e32 v50, v50, v51
	v_ashrrev_i32_e32 v51, 31, v50
	s_waitcnt lgkmcnt(0)
	v_mfma_f32_32x32x16_bf16 v[212:227], v[82:85], v[196:199], v[212:227]
	v_or_b32_e32 v51, 0x80000000, v51
	s_cmpk_gt_i32 s11, 128
	s_cselect_b64 vcc, -1, 0
	v_xor_b32_e32 v50, v51, v50
	v_cndmask_b32_e32 v50, v123, v50, vcc
	global_store_dword v243, v50, s[8:9]
	v_mfma_f32_32x32x16_bf16 v[6:21], v[86:89], v[38:41], 0
	s_add_i32 m0, s10, 0
	s_nop 0
	global_load_lds_dwordx4 v102, s[6:7]
	s_add_i32 m0, s10, 1024
	s_nop 0
	global_load_lds_dwordx4 v110, s[6:7]
	s_add_i32 m0, s10, 2048
	s_nop 0
	global_load_lds_dwordx4 v112, s[6:7]
	s_add_i32 m0, s10, 3072
	s_nop 0
	global_load_lds_dwordx4 v193, s[6:7]
	s_add_u32 s6, s6, 0x8000
	s_addc_u32 s7, s7, 0
	v_max_f32_e32 v108, 0, v212
	v_max_f32_e32 v109, 0, v213
	v_mul_f32_e32 v0, v22, v108
	v_mul_f32_e32 v1, v23, v109
	v_max_f32_e32 v210, 0, v214
	v_max_f32_e32 v211, 0, v215
	v_fmac_f32_e32 v0, v24, v210
	v_fmac_f32_e32 v1, v25, v211
	v_max_f32_e32 v108, 0, v216
	v_max_f32_e32 v109, 0, v217
	v_fmac_f32_e32 v0, v26, v108
	v_fmac_f32_e32 v1, v27, v109
	v_mfma_f32_32x32x16_bf16 v[6:21], v[90:93], v[42:45], v[6:21]
	v_max_f32_e32 v210, 0, v218
	v_max_f32_e32 v211, 0, v219
	v_fmac_f32_e32 v0, v28, v210
	v_fmac_f32_e32 v1, v29, v211
	v_max_f32_e32 v108, 0, v220
	v_max_f32_e32 v109, 0, v221
	v_fmac_f32_e32 v0, v30, v108
	v_fmac_f32_e32 v1, v31, v109
	v_max_f32_e32 v210, 0, v222
	v_max_f32_e32 v211, 0, v223
	v_fmac_f32_e32 v0, v32, v210
	v_fmac_f32_e32 v1, v33, v211
	v_mfma_f32_32x32x16_bf16 v[6:21], v[94:97], v[46:49], v[6:21]
	v_max_f32_e32 v108, 0, v224
	v_max_f32_e32 v109, 0, v225
	v_fmac_f32_e32 v0, v34, v108
	v_fmac_f32_e32 v1, v35, v109
	v_max_f32_e32 v210, 0, v226
	v_max_f32_e32 v211, 0, v227
	v_fmac_f32_e32 v0, v36, v210
	v_fmac_f32_e32 v1, v37, v211
	v_add_f32_e32 v0, v0, v1
	v_ashrrev_i32_e32 v1, 31, v0
	v_mfma_f32_32x32x16_bf16 v[6:21], v[98:101], v[196:199], v[6:21]
	s_waitcnt vmcnt(10)
	v_add_u32_e32 v228, 0x10000, v5
	ds_read_b128 v[38:41], v228 offset:10496
	v_add_u32_e32 v228, 0x10000, v52
	ds_read_b128 v[42:45], v228 offset:10496
	v_add_u32_e32 v228, 0x10000, v55
	ds_read_b128 v[46:49], v228 offset:10496
	v_add_u32_e32 v228, 0x10000, v56
	ds_read_b128 v[196:199], v228 offset:10496
	v_or_b32_e32 v1, 0x80000000, v1
	s_cmpk_gt_i32 s11, 136
	s_cselect_b64 vcc, -1, 0
	v_xor_b32_e32 v0, v1, v0
	v_cndmask_b32_e32 v148, v123, v0, vcc
	s_nop 3
	s_waitcnt lgkmcnt(3)
	v_mfma_f32_32x32x16_bf16 v[212:227], v[70:73], v[38:41], 0
	v_max_f32_e32 v108, 0, v6
	v_max_f32_e32 v109, 0, v7
	v_mul_f32_e32 v50, v244, v108
	v_mul_f32_e32 v51, v245, v109
	v_max_f32_e32 v210, 0, v8
	v_max_f32_e32 v211, 0, v9
	v_fmac_f32_e32 v50, v246, v210
	v_fmac_f32_e32 v51, v247, v211
	v_max_f32_e32 v108, 0, v10
	v_max_f32_e32 v109, 0, v11
	v_fmac_f32_e32 v50, v248, v108
	v_fmac_f32_e32 v51, v249, v109
	s_waitcnt lgkmcnt(2)
	v_mfma_f32_32x32x16_bf16 v[212:227], v[74:77], v[42:45], v[212:227]
	v_max_f32_e32 v210, 0, v12
	v_max_f32_e32 v211, 0, v13
	v_fmac_f32_e32 v50, v250, v210
	v_fmac_f32_e32 v51, v251, v211
	v_max_f32_e32 v108, 0, v14
	v_max_f32_e32 v109, 0, v15
	v_fmac_f32_e32 v50, v252, v108
	v_fmac_f32_e32 v51, v253, v109
	v_max_f32_e32 v210, 0, v16
	v_max_f32_e32 v211, 0, v17
	v_fmac_f32_e32 v50, v254, v210
	v_fmac_f32_e32 v51, v255, v211
	s_waitcnt lgkmcnt(1)
	v_mfma_f32_32x32x16_bf16 v[212:227], v[78:81], v[46:49], v[212:227]
	v_max_f32_e32 v108, 0, v18
	v_max_f32_e32 v109, 0, v19
	v_fmac_f32_e32 v50, v200, v108
	v_fmac_f32_e32 v51, v201, v109
	v_max_f32_e32 v210, 0, v20
	v_max_f32_e32 v211, 0, v21
	v_fmac_f32_e32 v50, v202, v210
	v_fmac_f32_e32 v51, v203, v211
	v_add_f32_e32 v50, v50, v51
	v_ashrrev_i32_e32 v51, 31, v50
	s_waitcnt lgkmcnt(0)
	v_mfma_f32_32x32x16_bf16 v[212:227], v[82:85], v[196:199], v[212:227]
	v_or_b32_e32 v51, 0x80000000, v51
	s_cmpk_gt_i32 s11, 136
	s_cselect_b64 vcc, -1, 0
	v_xor_b32_e32 v50, v51, v50
	v_cndmask_b32_e32 v50, v123, v50, vcc
	global_store_dword v243, v50, s[8:9] offset:2048
	s_add_u32 s8, s8, 0x1000
	s_addc_u32 s9, s9, 0
	v_mfma_f32_32x32x16_bf16 v[6:21], v[86:89], v[38:41], 0
	s_add_i32 m0, s10, 32768
	s_nop 0
	global_load_lds_dwordx4 v102, s[6:7]
	s_add_i32 m0, s10, 33792
	s_nop 0
	global_load_lds_dwordx4 v110, s[6:7]
	s_add_i32 m0, s10, 34816
	s_nop 0
	global_load_lds_dwordx4 v112, s[6:7]
	s_add_i32 m0, s10, 35840
	s_nop 0
	global_load_lds_dwordx4 v193, s[6:7]
	s_add_u32 s6, s6, 0x8000
	s_addc_u32 s7, s7, 0
	v_max_f32_e32 v108, 0, v212
	v_max_f32_e32 v109, 0, v213
	v_mul_f32_e32 v0, v22, v108
	v_mul_f32_e32 v1, v23, v109
	v_max_f32_e32 v210, 0, v214
	v_max_f32_e32 v211, 0, v215
	v_fmac_f32_e32 v0, v24, v210
	v_fmac_f32_e32 v1, v25, v211
	v_max_f32_e32 v108, 0, v216
	v_max_f32_e32 v109, 0, v217
	v_fmac_f32_e32 v0, v26, v108
	v_fmac_f32_e32 v1, v27, v109
	v_mfma_f32_32x32x16_bf16 v[6:21], v[90:93], v[42:45], v[6:21]
	v_max_f32_e32 v210, 0, v218
	v_max_f32_e32 v211, 0, v219
	v_fmac_f32_e32 v0, v28, v210
	v_fmac_f32_e32 v1, v29, v211
	v_max_f32_e32 v108, 0, v220
	v_max_f32_e32 v109, 0, v221
	v_fmac_f32_e32 v0, v30, v108
	v_fmac_f32_e32 v1, v31, v109
	v_max_f32_e32 v210, 0, v222
	v_max_f32_e32 v211, 0, v223
	v_fmac_f32_e32 v0, v32, v210
	v_fmac_f32_e32 v1, v33, v211
	v_mfma_f32_32x32x16_bf16 v[6:21], v[94:97], v[46:49], v[6:21]
	v_max_f32_e32 v108, 0, v224
	v_max_f32_e32 v109, 0, v225
	v_fmac_f32_e32 v0, v34, v108
	v_fmac_f32_e32 v1, v35, v109
	v_max_f32_e32 v210, 0, v226
	v_max_f32_e32 v211, 0, v227
	v_fmac_f32_e32 v0, v36, v210
	v_fmac_f32_e32 v1, v37, v211
	v_add_f32_e32 v0, v0, v1
	v_ashrrev_i32_e32 v1, 31, v0
	v_mfma_f32_32x32x16_bf16 v[6:21], v[98:101], v[196:199], v[6:21]
	s_waitcnt vmcnt(10)
	v_add_u32_e32 v228, 0x10000, v5
	ds_read_b128 v[38:41], v228 offset:43264
	v_add_u32_e32 v228, 0x10000, v52
	ds_read_b128 v[42:45], v228 offset:43264
	v_add_u32_e32 v228, 0x10000, v55
	ds_read_b128 v[46:49], v228 offset:43264
	v_add_u32_e32 v228, 0x10000, v56
	ds_read_b128 v[196:199], v228 offset:43264
	v_or_b32_e32 v1, 0x80000000, v1
	s_cmpk_gt_i32 s11, 144
	s_cselect_b64 vcc, -1, 0
	v_xor_b32_e32 v0, v1, v0
	v_cndmask_b32_e32 v151, v123, v0, vcc
	s_nop 3
	s_waitcnt lgkmcnt(3)
	v_mfma_f32_32x32x16_bf16 v[212:227], v[70:73], v[38:41], 0
	v_max_f32_e32 v108, 0, v6
	v_max_f32_e32 v109, 0, v7
	v_mul_f32_e32 v50, v244, v108
	v_mul_f32_e32 v51, v245, v109
	v_max_f32_e32 v210, 0, v8
	v_max_f32_e32 v211, 0, v9
	v_fmac_f32_e32 v50, v246, v210
	v_fmac_f32_e32 v51, v247, v211
	v_max_f32_e32 v108, 0, v10
	v_max_f32_e32 v109, 0, v11
	v_fmac_f32_e32 v50, v248, v108
	v_fmac_f32_e32 v51, v249, v109
	s_waitcnt lgkmcnt(2)
	v_mfma_f32_32x32x16_bf16 v[212:227], v[74:77], v[42:45], v[212:227]
	v_max_f32_e32 v210, 0, v12
	v_max_f32_e32 v211, 0, v13
	v_fmac_f32_e32 v50, v250, v210
	v_fmac_f32_e32 v51, v251, v211
	v_max_f32_e32 v108, 0, v14
	v_max_f32_e32 v109, 0, v15
	v_fmac_f32_e32 v50, v252, v108
	v_fmac_f32_e32 v51, v253, v109
	v_max_f32_e32 v210, 0, v16
	v_max_f32_e32 v211, 0, v17
	v_fmac_f32_e32 v50, v254, v210
	v_fmac_f32_e32 v51, v255, v211
	s_waitcnt lgkmcnt(1)
	v_mfma_f32_32x32x16_bf16 v[212:227], v[78:81], v[46:49], v[212:227]
	v_max_f32_e32 v108, 0, v18
	v_max_f32_e32 v109, 0, v19
	v_fmac_f32_e32 v50, v200, v108
	v_fmac_f32_e32 v51, v201, v109
	v_max_f32_e32 v210, 0, v20
	v_max_f32_e32 v211, 0, v21
	v_fmac_f32_e32 v50, v202, v210
	v_fmac_f32_e32 v51, v203, v211
	v_add_f32_e32 v50, v50, v51
	v_ashrrev_i32_e32 v51, 31, v50
	s_waitcnt lgkmcnt(0)
	v_mfma_f32_32x32x16_bf16 v[212:227], v[82:85], v[196:199], v[212:227]
	v_or_b32_e32 v51, 0x80000000, v51
	s_cmpk_gt_i32 s11, 144
	s_cselect_b64 vcc, -1, 0
	v_xor_b32_e32 v50, v51, v50
	v_cndmask_b32_e32 v50, v123, v50, vcc
	global_store_dword v243, v50, s[8:9]
	v_mfma_f32_32x32x16_bf16 v[6:21], v[86:89], v[38:41], 0
	s_add_i32 m0, s10, 65536
	s_nop 0
	global_load_lds_dwordx4 v102, s[6:7]
	s_add_i32 m0, s10, 66560
	s_nop 0
	global_load_lds_dwordx4 v110, s[6:7]
	s_add_i32 m0, s10, 67584
	s_nop 0
	global_load_lds_dwordx4 v112, s[6:7]
	s_add_i32 m0, s10, 68608
	s_nop 0
	global_load_lds_dwordx4 v193, s[6:7]
	s_add_u32 s6, s6, 0x8000
	s_addc_u32 s7, s7, 0
	v_max_f32_e32 v108, 0, v212
	v_max_f32_e32 v109, 0, v213
	v_mul_f32_e32 v0, v22, v108
	v_mul_f32_e32 v1, v23, v109
	v_max_f32_e32 v210, 0, v214
	v_max_f32_e32 v211, 0, v215
	v_fmac_f32_e32 v0, v24, v210
	v_fmac_f32_e32 v1, v25, v211
	v_max_f32_e32 v108, 0, v216
	v_max_f32_e32 v109, 0, v217
	v_fmac_f32_e32 v0, v26, v108
	v_fmac_f32_e32 v1, v27, v109
	v_mfma_f32_32x32x16_bf16 v[6:21], v[90:93], v[42:45], v[6:21]
	v_max_f32_e32 v210, 0, v218
	v_max_f32_e32 v211, 0, v219
	v_fmac_f32_e32 v0, v28, v210
	v_fmac_f32_e32 v1, v29, v211
	v_max_f32_e32 v108, 0, v220
	v_max_f32_e32 v109, 0, v221
	v_fmac_f32_e32 v0, v30, v108
	v_fmac_f32_e32 v1, v31, v109
	v_max_f32_e32 v210, 0, v222
	v_max_f32_e32 v211, 0, v223
	v_fmac_f32_e32 v0, v32, v210
	v_fmac_f32_e32 v1, v33, v211
	v_mfma_f32_32x32x16_bf16 v[6:21], v[94:97], v[46:49], v[6:21]
	v_max_f32_e32 v108, 0, v224
	v_max_f32_e32 v109, 0, v225
	v_fmac_f32_e32 v0, v34, v108
	v_fmac_f32_e32 v1, v35, v109
	v_max_f32_e32 v210, 0, v226
	v_max_f32_e32 v211, 0, v227
	v_fmac_f32_e32 v0, v36, v210
	v_fmac_f32_e32 v1, v37, v211
	v_add_f32_e32 v0, v0, v1
	v_ashrrev_i32_e32 v1, 31, v0
	v_mfma_f32_32x32x16_bf16 v[6:21], v[98:101], v[196:199], v[6:21]
	s_waitcnt vmcnt(10)
	ds_read_b128 v[38:41], v5 offset:10496
	ds_read_b128 v[42:45], v52 offset:10496
	ds_read_b128 v[46:49], v55 offset:10496
	ds_read_b128 v[196:199], v56 offset:10496
	v_or_b32_e32 v1, 0x80000000, v1
	s_cmpk_gt_i32 s11, 152
	s_cselect_b64 vcc, -1, 0
	v_xor_b32_e32 v0, v1, v0
	v_cndmask_b32_e32 v150, v123, v0, vcc
	s_nop 3
	s_waitcnt lgkmcnt(3)
	v_mfma_f32_32x32x16_bf16 v[212:227], v[70:73], v[38:41], 0
	v_max_f32_e32 v108, 0, v6
	v_max_f32_e32 v109, 0, v7
	v_mul_f32_e32 v50, v244, v108
	v_mul_f32_e32 v51, v245, v109
	v_max_f32_e32 v210, 0, v8
	v_max_f32_e32 v211, 0, v9
	v_fmac_f32_e32 v50, v246, v210
	v_fmac_f32_e32 v51, v247, v211
	v_max_f32_e32 v108, 0, v10
	v_max_f32_e32 v109, 0, v11
	v_fmac_f32_e32 v50, v248, v108
	v_fmac_f32_e32 v51, v249, v109
	s_waitcnt lgkmcnt(2)
	v_mfma_f32_32x32x16_bf16 v[212:227], v[74:77], v[42:45], v[212:227]
	v_max_f32_e32 v210, 0, v12
	v_max_f32_e32 v211, 0, v13
	v_fmac_f32_e32 v50, v250, v210
	v_fmac_f32_e32 v51, v251, v211
	v_max_f32_e32 v108, 0, v14
	v_max_f32_e32 v109, 0, v15
	v_fmac_f32_e32 v50, v252, v108
	v_fmac_f32_e32 v51, v253, v109
	v_max_f32_e32 v210, 0, v16
	v_max_f32_e32 v211, 0, v17
	v_fmac_f32_e32 v50, v254, v210
	v_fmac_f32_e32 v51, v255, v211
	s_waitcnt lgkmcnt(1)
	v_mfma_f32_32x32x16_bf16 v[212:227], v[78:81], v[46:49], v[212:227]
	v_max_f32_e32 v108, 0, v18
	v_max_f32_e32 v109, 0, v19
	v_fmac_f32_e32 v50, v200, v108
	v_fmac_f32_e32 v51, v201, v109
	v_max_f32_e32 v210, 0, v20
	v_max_f32_e32 v211, 0, v21
	v_fmac_f32_e32 v50, v202, v210
	v_fmac_f32_e32 v51, v203, v211
	v_add_f32_e32 v50, v50, v51
	v_ashrrev_i32_e32 v51, 31, v50
	s_waitcnt lgkmcnt(0)
	v_mfma_f32_32x32x16_bf16 v[212:227], v[82:85], v[196:199], v[212:227]
	v_or_b32_e32 v51, 0x80000000, v51
	s_cmpk_gt_i32 s11, 152
	s_cselect_b64 vcc, -1, 0
	v_xor_b32_e32 v50, v51, v50
	v_cndmask_b32_e32 v50, v123, v50, vcc
	global_store_dword v243, v50, s[8:9] offset:2048
	s_add_u32 s8, s8, 0x1000
	s_addc_u32 s9, s9, 0
	v_mfma_f32_32x32x16_bf16 v[6:21], v[86:89], v[38:41], 0
	s_add_i32 m0, s10, 98304
	s_nop 0
	global_load_lds_dwordx4 v102, s[6:7]
	s_add_i32 m0, s10, 99328
	s_nop 0
	global_load_lds_dwordx4 v110, s[6:7]
	s_add_i32 m0, s10, 100352
	s_nop 0
	global_load_lds_dwordx4 v112, s[6:7]
	s_add_i32 m0, s10, 101376
	s_nop 0
	global_load_lds_dwordx4 v193, s[6:7]
	s_add_u32 s6, s6, 0x8000
	s_addc_u32 s7, s7, 0
	v_max_f32_e32 v108, 0, v212
	v_max_f32_e32 v109, 0, v213
	v_mul_f32_e32 v0, v22, v108
	v_mul_f32_e32 v1, v23, v109
	v_max_f32_e32 v210, 0, v214
	v_max_f32_e32 v211, 0, v215
	v_fmac_f32_e32 v0, v24, v210
	v_fmac_f32_e32 v1, v25, v211
	v_max_f32_e32 v108, 0, v216
	v_max_f32_e32 v109, 0, v217
	v_fmac_f32_e32 v0, v26, v108
	v_fmac_f32_e32 v1, v27, v109
	v_mfma_f32_32x32x16_bf16 v[6:21], v[90:93], v[42:45], v[6:21]
	v_max_f32_e32 v210, 0, v218
	v_max_f32_e32 v211, 0, v219
	v_fmac_f32_e32 v0, v28, v210
	v_fmac_f32_e32 v1, v29, v211
	v_max_f32_e32 v108, 0, v220
	v_max_f32_e32 v109, 0, v221
	v_fmac_f32_e32 v0, v30, v108
	v_fmac_f32_e32 v1, v31, v109
	v_max_f32_e32 v210, 0, v222
	v_max_f32_e32 v211, 0, v223
	v_fmac_f32_e32 v0, v32, v210
	v_fmac_f32_e32 v1, v33, v211
	v_mfma_f32_32x32x16_bf16 v[6:21], v[94:97], v[46:49], v[6:21]
	v_max_f32_e32 v108, 0, v224
	v_max_f32_e32 v109, 0, v225
	v_fmac_f32_e32 v0, v34, v108
	v_fmac_f32_e32 v1, v35, v109
	v_max_f32_e32 v210, 0, v226
	v_max_f32_e32 v211, 0, v227
	v_fmac_f32_e32 v0, v36, v210
	v_fmac_f32_e32 v1, v37, v211
	v_add_f32_e32 v0, v0, v1
	v_ashrrev_i32_e32 v1, 31, v0
	v_mfma_f32_32x32x16_bf16 v[6:21], v[98:101], v[196:199], v[6:21]
	s_waitcnt vmcnt(10)
	ds_read_b128 v[38:41], v5 offset:43264
	ds_read_b128 v[42:45], v52 offset:43264
	ds_read_b128 v[46:49], v55 offset:43264
	ds_read_b128 v[196:199], v56 offset:43264
	v_or_b32_e32 v1, 0x80000000, v1
	s_cmpk_gt_i32 s11, 160
	s_cselect_b64 vcc, -1, 0
	v_xor_b32_e32 v0, v1, v0
	v_cndmask_b32_e32 v154, v123, v0, vcc
	s_nop 3
	s_waitcnt lgkmcnt(3)
	v_mfma_f32_32x32x16_bf16 v[212:227], v[70:73], v[38:41], 0
	v_max_f32_e32 v108, 0, v6
	v_max_f32_e32 v109, 0, v7
	v_mul_f32_e32 v50, v244, v108
	v_mul_f32_e32 v51, v245, v109
	v_max_f32_e32 v210, 0, v8
	v_max_f32_e32 v211, 0, v9
	v_fmac_f32_e32 v50, v246, v210
	v_fmac_f32_e32 v51, v247, v211
	v_max_f32_e32 v108, 0, v10
	v_max_f32_e32 v109, 0, v11
	v_fmac_f32_e32 v50, v248, v108
	v_fmac_f32_e32 v51, v249, v109
	s_waitcnt lgkmcnt(2)
	v_mfma_f32_32x32x16_bf16 v[212:227], v[74:77], v[42:45], v[212:227]
	v_max_f32_e32 v210, 0, v12
	v_max_f32_e32 v211, 0, v13
	v_fmac_f32_e32 v50, v250, v210
	v_fmac_f32_e32 v51, v251, v211
	v_max_f32_e32 v108, 0, v14
	v_max_f32_e32 v109, 0, v15
	v_fmac_f32_e32 v50, v252, v108
	v_fmac_f32_e32 v51, v253, v109
	v_max_f32_e32 v210, 0, v16
	v_max_f32_e32 v211, 0, v17
	v_fmac_f32_e32 v50, v254, v210
	v_fmac_f32_e32 v51, v255, v211
	s_waitcnt lgkmcnt(1)
	v_mfma_f32_32x32x16_bf16 v[212:227], v[78:81], v[46:49], v[212:227]
	v_max_f32_e32 v108, 0, v18
	v_max_f32_e32 v109, 0, v19
	v_fmac_f32_e32 v50, v200, v108
	v_fmac_f32_e32 v51, v201, v109
	v_max_f32_e32 v210, 0, v20
	v_max_f32_e32 v211, 0, v21
	v_fmac_f32_e32 v50, v202, v210
	v_fmac_f32_e32 v51, v203, v211
	v_add_f32_e32 v50, v50, v51
	v_ashrrev_i32_e32 v51, 31, v50
	s_waitcnt lgkmcnt(0)
	v_mfma_f32_32x32x16_bf16 v[212:227], v[82:85], v[196:199], v[212:227]
	v_or_b32_e32 v51, 0x80000000, v51
	s_cmpk_gt_i32 s11, 160
	s_cselect_b64 vcc, -1, 0
	v_xor_b32_e32 v50, v51, v50
	v_cndmask_b32_e32 v50, v123, v50, vcc
	global_store_dword v243, v50, s[8:9]
	v_mfma_f32_32x32x16_bf16 v[6:21], v[86:89], v[38:41], 0
	s_add_i32 m0, s10, 0
	s_nop 0
	global_load_lds_dwordx4 v102, s[6:7]
	s_add_i32 m0, s10, 1024
	s_nop 0
	global_load_lds_dwordx4 v110, s[6:7]
	s_add_i32 m0, s10, 2048
	s_nop 0
	global_load_lds_dwordx4 v112, s[6:7]
	s_add_i32 m0, s10, 3072
	s_nop 0
	global_load_lds_dwordx4 v193, s[6:7]
	s_add_u32 s6, s6, 0x8000
	s_addc_u32 s7, s7, 0
	v_max_f32_e32 v108, 0, v212
	v_max_f32_e32 v109, 0, v213
	v_mul_f32_e32 v0, v22, v108
	v_mul_f32_e32 v1, v23, v109
	v_max_f32_e32 v210, 0, v214
	v_max_f32_e32 v211, 0, v215
	v_fmac_f32_e32 v0, v24, v210
	v_fmac_f32_e32 v1, v25, v211
	v_max_f32_e32 v108, 0, v216
	v_max_f32_e32 v109, 0, v217
	v_fmac_f32_e32 v0, v26, v108
	v_fmac_f32_e32 v1, v27, v109
	v_mfma_f32_32x32x16_bf16 v[6:21], v[90:93], v[42:45], v[6:21]
	v_max_f32_e32 v210, 0, v218
	v_max_f32_e32 v211, 0, v219
	v_fmac_f32_e32 v0, v28, v210
	v_fmac_f32_e32 v1, v29, v211
	v_max_f32_e32 v108, 0, v220
	v_max_f32_e32 v109, 0, v221
	v_fmac_f32_e32 v0, v30, v108
	v_fmac_f32_e32 v1, v31, v109
	v_max_f32_e32 v210, 0, v222
	v_max_f32_e32 v211, 0, v223
	v_fmac_f32_e32 v0, v32, v210
	v_fmac_f32_e32 v1, v33, v211
	v_mfma_f32_32x32x16_bf16 v[6:21], v[94:97], v[46:49], v[6:21]
	v_max_f32_e32 v108, 0, v224
	v_max_f32_e32 v109, 0, v225
	v_fmac_f32_e32 v0, v34, v108
	v_fmac_f32_e32 v1, v35, v109
	v_max_f32_e32 v210, 0, v226
	v_max_f32_e32 v211, 0, v227
	v_fmac_f32_e32 v0, v36, v210
	v_fmac_f32_e32 v1, v37, v211
	v_add_f32_e32 v0, v0, v1
	v_ashrrev_i32_e32 v1, 31, v0
	v_mfma_f32_32x32x16_bf16 v[6:21], v[98:101], v[196:199], v[6:21]
	s_waitcnt vmcnt(10)
	v_add_u32_e32 v228, 0x10000, v5
	ds_read_b128 v[38:41], v228 offset:10496
	v_add_u32_e32 v228, 0x10000, v52
	ds_read_b128 v[42:45], v228 offset:10496
	v_add_u32_e32 v228, 0x10000, v55
	ds_read_b128 v[46:49], v228 offset:10496
	v_add_u32_e32 v228, 0x10000, v56
	ds_read_b128 v[196:199], v228 offset:10496
	v_or_b32_e32 v1, 0x80000000, v1
	s_cmpk_gt_i32 s11, 168
	s_cselect_b64 vcc, -1, 0
	v_xor_b32_e32 v0, v1, v0
	v_cndmask_b32_e32 v153, v123, v0, vcc
	s_nop 3
	s_waitcnt lgkmcnt(3)
	v_mfma_f32_32x32x16_bf16 v[212:227], v[70:73], v[38:41], 0
	v_max_f32_e32 v108, 0, v6
	v_max_f32_e32 v109, 0, v7
	v_mul_f32_e32 v50, v244, v108
	v_mul_f32_e32 v51, v245, v109
	v_max_f32_e32 v210, 0, v8
	v_max_f32_e32 v211, 0, v9
	v_fmac_f32_e32 v50, v246, v210
	v_fmac_f32_e32 v51, v247, v211
	v_max_f32_e32 v108, 0, v10
	v_max_f32_e32 v109, 0, v11
	v_fmac_f32_e32 v50, v248, v108
	v_fmac_f32_e32 v51, v249, v109
	s_waitcnt lgkmcnt(2)
	v_mfma_f32_32x32x16_bf16 v[212:227], v[74:77], v[42:45], v[212:227]
	v_max_f32_e32 v210, 0, v12
	v_max_f32_e32 v211, 0, v13
	v_fmac_f32_e32 v50, v250, v210
	v_fmac_f32_e32 v51, v251, v211
	v_max_f32_e32 v108, 0, v14
	v_max_f32_e32 v109, 0, v15
	v_fmac_f32_e32 v50, v252, v108
	v_fmac_f32_e32 v51, v253, v109
	v_max_f32_e32 v210, 0, v16
	v_max_f32_e32 v211, 0, v17
	v_fmac_f32_e32 v50, v254, v210
	v_fmac_f32_e32 v51, v255, v211
	s_waitcnt lgkmcnt(1)
	v_mfma_f32_32x32x16_bf16 v[212:227], v[78:81], v[46:49], v[212:227]
	v_max_f32_e32 v108, 0, v18
	v_max_f32_e32 v109, 0, v19
	v_fmac_f32_e32 v50, v200, v108
	v_fmac_f32_e32 v51, v201, v109
	v_max_f32_e32 v210, 0, v20
	v_max_f32_e32 v211, 0, v21
	v_fmac_f32_e32 v50, v202, v210
	v_fmac_f32_e32 v51, v203, v211
	v_add_f32_e32 v50, v50, v51
	v_ashrrev_i32_e32 v51, 31, v50
	s_waitcnt lgkmcnt(0)
	v_mfma_f32_32x32x16_bf16 v[212:227], v[82:85], v[196:199], v[212:227]
	v_or_b32_e32 v51, 0x80000000, v51
	s_cmpk_gt_i32 s11, 168
	s_cselect_b64 vcc, -1, 0
	v_xor_b32_e32 v50, v51, v50
	v_cndmask_b32_e32 v50, v123, v50, vcc
	global_store_dword v243, v50, s[8:9] offset:2048
	s_add_u32 s8, s8, 0x1000
	s_addc_u32 s9, s9, 0
	v_mfma_f32_32x32x16_bf16 v[6:21], v[86:89], v[38:41], 0
	s_add_i32 m0, s10, 32768
	s_nop 0
	global_load_lds_dwordx4 v102, s[6:7]
	s_add_i32 m0, s10, 33792
	s_nop 0
	global_load_lds_dwordx4 v110, s[6:7]
	s_add_i32 m0, s10, 34816
	s_nop 0
	global_load_lds_dwordx4 v112, s[6:7]
	s_add_i32 m0, s10, 35840
	s_nop 0
	global_load_lds_dwordx4 v193, s[6:7]
	s_add_u32 s6, s6, 0x8000
	s_addc_u32 s7, s7, 0
	v_max_f32_e32 v108, 0, v212
	v_max_f32_e32 v109, 0, v213
	v_mul_f32_e32 v0, v22, v108
	v_mul_f32_e32 v1, v23, v109
	v_max_f32_e32 v210, 0, v214
	v_max_f32_e32 v211, 0, v215
	v_fmac_f32_e32 v0, v24, v210
	v_fmac_f32_e32 v1, v25, v211
	v_max_f32_e32 v108, 0, v216
	v_max_f32_e32 v109, 0, v217
	v_fmac_f32_e32 v0, v26, v108
	v_fmac_f32_e32 v1, v27, v109
	v_mfma_f32_32x32x16_bf16 v[6:21], v[90:93], v[42:45], v[6:21]
	v_max_f32_e32 v210, 0, v218
	v_max_f32_e32 v211, 0, v219
	v_fmac_f32_e32 v0, v28, v210
	v_fmac_f32_e32 v1, v29, v211
	v_max_f32_e32 v108, 0, v220
	v_max_f32_e32 v109, 0, v221
	v_fmac_f32_e32 v0, v30, v108
	v_fmac_f32_e32 v1, v31, v109
	v_max_f32_e32 v210, 0, v222
	v_max_f32_e32 v211, 0, v223
	v_fmac_f32_e32 v0, v32, v210
	v_fmac_f32_e32 v1, v33, v211
	v_mfma_f32_32x32x16_bf16 v[6:21], v[94:97], v[46:49], v[6:21]
	v_max_f32_e32 v108, 0, v224
	v_max_f32_e32 v109, 0, v225
	v_fmac_f32_e32 v0, v34, v108
	v_fmac_f32_e32 v1, v35, v109
	v_max_f32_e32 v210, 0, v226
	v_max_f32_e32 v211, 0, v227
	v_fmac_f32_e32 v0, v36, v210
	v_fmac_f32_e32 v1, v37, v211
	v_add_f32_e32 v0, v0, v1
	v_ashrrev_i32_e32 v1, 31, v0
	v_mfma_f32_32x32x16_bf16 v[6:21], v[98:101], v[196:199], v[6:21]
	s_waitcnt vmcnt(10)
	v_add_u32_e32 v228, 0x10000, v5
	ds_read_b128 v[38:41], v228 offset:43264
	v_add_u32_e32 v228, 0x10000, v52
	ds_read_b128 v[42:45], v228 offset:43264
	v_add_u32_e32 v228, 0x10000, v55
	ds_read_b128 v[46:49], v228 offset:43264
	v_add_u32_e32 v228, 0x10000, v56
	ds_read_b128 v[196:199], v228 offset:43264
	v_or_b32_e32 v1, 0x80000000, v1
	s_cmpk_gt_i32 s11, 176
	s_cselect_b64 vcc, -1, 0
	v_xor_b32_e32 v0, v1, v0
	v_cndmask_b32_e32 v156, v123, v0, vcc
	s_nop 3
	s_waitcnt lgkmcnt(3)
	v_mfma_f32_32x32x16_bf16 v[212:227], v[70:73], v[38:41], 0
	v_max_f32_e32 v108, 0, v6
	v_max_f32_e32 v109, 0, v7
	v_mul_f32_e32 v50, v244, v108
	v_mul_f32_e32 v51, v245, v109
	v_max_f32_e32 v210, 0, v8
	v_max_f32_e32 v211, 0, v9
	v_fmac_f32_e32 v50, v246, v210
	v_fmac_f32_e32 v51, v247, v211
	v_max_f32_e32 v108, 0, v10
	v_max_f32_e32 v109, 0, v11
	v_fmac_f32_e32 v50, v248, v108
	v_fmac_f32_e32 v51, v249, v109
	s_waitcnt lgkmcnt(2)
	v_mfma_f32_32x32x16_bf16 v[212:227], v[74:77], v[42:45], v[212:227]
	v_max_f32_e32 v210, 0, v12
	v_max_f32_e32 v211, 0, v13
	v_fmac_f32_e32 v50, v250, v210
	v_fmac_f32_e32 v51, v251, v211
	v_max_f32_e32 v108, 0, v14
	v_max_f32_e32 v109, 0, v15
	v_fmac_f32_e32 v50, v252, v108
	v_fmac_f32_e32 v51, v253, v109
	v_max_f32_e32 v210, 0, v16
	v_max_f32_e32 v211, 0, v17
	v_fmac_f32_e32 v50, v254, v210
	v_fmac_f32_e32 v51, v255, v211
	s_waitcnt lgkmcnt(1)
	v_mfma_f32_32x32x16_bf16 v[212:227], v[78:81], v[46:49], v[212:227]
	v_max_f32_e32 v108, 0, v18
	v_max_f32_e32 v109, 0, v19
	v_fmac_f32_e32 v50, v200, v108
	v_fmac_f32_e32 v51, v201, v109
	v_max_f32_e32 v210, 0, v20
	v_max_f32_e32 v211, 0, v21
	v_fmac_f32_e32 v50, v202, v210
	v_fmac_f32_e32 v51, v203, v211
	v_add_f32_e32 v50, v50, v51
	v_ashrrev_i32_e32 v51, 31, v50
	s_waitcnt lgkmcnt(0)
	v_mfma_f32_32x32x16_bf16 v[212:227], v[82:85], v[196:199], v[212:227]
	v_or_b32_e32 v51, 0x80000000, v51
	s_cmpk_gt_i32 s11, 176
	s_cselect_b64 vcc, -1, 0
	v_xor_b32_e32 v50, v51, v50
	v_cndmask_b32_e32 v50, v123, v50, vcc
	global_store_dword v243, v50, s[8:9]
	v_mfma_f32_32x32x16_bf16 v[6:21], v[86:89], v[38:41], 0
	s_add_i32 m0, s10, 65536
	s_nop 0
	global_load_lds_dwordx4 v102, s[6:7]
	s_add_i32 m0, s10, 66560
	s_nop 0
	global_load_lds_dwordx4 v110, s[6:7]
	s_add_i32 m0, s10, 67584
	s_nop 0
	global_load_lds_dwordx4 v112, s[6:7]
	s_add_i32 m0, s10, 68608
	s_nop 0
	global_load_lds_dwordx4 v193, s[6:7]
	s_add_u32 s6, s6, 0x8000
	s_addc_u32 s7, s7, 0
	v_max_f32_e32 v108, 0, v212
	v_max_f32_e32 v109, 0, v213
	v_mul_f32_e32 v0, v22, v108
	v_mul_f32_e32 v1, v23, v109
	v_max_f32_e32 v210, 0, v214
	v_max_f32_e32 v211, 0, v215
	v_fmac_f32_e32 v0, v24, v210
	v_fmac_f32_e32 v1, v25, v211
	v_max_f32_e32 v108, 0, v216
	v_max_f32_e32 v109, 0, v217
	v_fmac_f32_e32 v0, v26, v108
	v_fmac_f32_e32 v1, v27, v109
	v_mfma_f32_32x32x16_bf16 v[6:21], v[90:93], v[42:45], v[6:21]
	v_max_f32_e32 v210, 0, v218
	v_max_f32_e32 v211, 0, v219
	v_fmac_f32_e32 v0, v28, v210
	v_fmac_f32_e32 v1, v29, v211
	v_max_f32_e32 v108, 0, v220
	v_max_f32_e32 v109, 0, v221
	v_fmac_f32_e32 v0, v30, v108
	v_fmac_f32_e32 v1, v31, v109
	v_max_f32_e32 v210, 0, v222
	v_max_f32_e32 v211, 0, v223
	v_fmac_f32_e32 v0, v32, v210
	v_fmac_f32_e32 v1, v33, v211
	v_mfma_f32_32x32x16_bf16 v[6:21], v[94:97], v[46:49], v[6:21]
	v_max_f32_e32 v108, 0, v224
	v_max_f32_e32 v109, 0, v225
	v_fmac_f32_e32 v0, v34, v108
	v_fmac_f32_e32 v1, v35, v109
	v_max_f32_e32 v210, 0, v226
	v_max_f32_e32 v211, 0, v227
	v_fmac_f32_e32 v0, v36, v210
	v_fmac_f32_e32 v1, v37, v211
	v_add_f32_e32 v0, v0, v1
	v_ashrrev_i32_e32 v1, 31, v0
	v_mfma_f32_32x32x16_bf16 v[6:21], v[98:101], v[196:199], v[6:21]
	s_waitcnt vmcnt(10)
	ds_read_b128 v[38:41], v5 offset:10496
	ds_read_b128 v[42:45], v52 offset:10496
	ds_read_b128 v[46:49], v55 offset:10496
	ds_read_b128 v[196:199], v56 offset:10496
	v_or_b32_e32 v1, 0x80000000, v1
	s_cmpk_gt_i32 s11, 184
	s_cselect_b64 vcc, -1, 0
	v_xor_b32_e32 v0, v1, v0
	v_cndmask_b32_e32 v155, v123, v0, vcc
	s_nop 3
	v_max_f32_e32 v108, 0, v6
	v_max_f32_e32 v109, 0, v7
	v_mul_f32_e32 v50, v244, v108
	v_mul_f32_e32 v51, v245, v109
	v_max_f32_e32 v210, 0, v8
	v_max_f32_e32 v211, 0, v9
	v_fmac_f32_e32 v50, v246, v210
	v_fmac_f32_e32 v51, v247, v211
	v_max_f32_e32 v108, 0, v10
	v_max_f32_e32 v109, 0, v11
	v_fmac_f32_e32 v50, v248, v108
	v_fmac_f32_e32 v51, v249, v109
	v_max_f32_e32 v210, 0, v12
	v_max_f32_e32 v211, 0, v13
	v_fmac_f32_e32 v50, v250, v210
	v_fmac_f32_e32 v51, v251, v211
	v_max_f32_e32 v108, 0, v14
	v_max_f32_e32 v109, 0, v15
	v_fmac_f32_e32 v50, v252, v108
	v_fmac_f32_e32 v51, v253, v109
	v_max_f32_e32 v210, 0, v16
	v_max_f32_e32 v211, 0, v17
	v_fmac_f32_e32 v50, v254, v210
	v_fmac_f32_e32 v51, v255, v211
	v_max_f32_e32 v108, 0, v18
	v_max_f32_e32 v109, 0, v19
	v_fmac_f32_e32 v50, v200, v108
	v_fmac_f32_e32 v51, v201, v109
	v_max_f32_e32 v210, 0, v20
	v_max_f32_e32 v211, 0, v21
	v_fmac_f32_e32 v50, v202, v210
	v_fmac_f32_e32 v51, v203, v211
	v_add_f32_e32 v50, v50, v51
	v_ashrrev_i32_e32 v51, 31, v50
	v_or_b32_e32 v51, 0x80000000, v51
	s_cmpk_gt_i32 s11, 184
	s_cselect_b64 vcc, -1, 0
	v_xor_b32_e32 v50, v51, v50
	v_cndmask_b32_e32 v50, v123, v50, vcc
	global_store_dword v243, v50, s[8:9] offset:2048
	s_add_u32 s8, s8, 0x1000
	s_addc_u32 s9, s9, 0
	s_cmpk_gt_i32 s81, 24
	s_cbranch_scc0 .Lix_fill_3
	s_waitcnt lgkmcnt(3)
	v_mfma_f32_32x32x16_bf16 v[212:227], v[70:73], v[38:41], 0
	s_add_i32 m0, s10, 98304
	s_nop 0
	global_load_lds_dwordx4 v102, s[6:7]
	s_waitcnt lgkmcnt(2)
	v_mfma_f32_32x32x16_bf16 v[212:227], v[74:77], v[42:45], v[212:227]
	s_add_i32 m0, s10, 99328
	s_nop 0
	global_load_lds_dwordx4 v110, s[6:7]
	s_waitcnt lgkmcnt(1)
	v_mfma_f32_32x32x16_bf16 v[212:227], v[78:81], v[46:49], v[212:227]
	s_add_i32 m0, s10, 100352
	s_nop 0
	global_load_lds_dwordx4 v112, s[6:7]
	s_waitcnt lgkmcnt(0)
	v_mfma_f32_32x32x16_bf16 v[212:227], v[82:85], v[196:199], v[212:227]
	s_add_i32 m0, s10, 101376
	s_nop 0
	global_load_lds_dwordx4 v193, s[6:7]
	s_add_u32 s6, s6, 0x8000
	s_addc_u32 s7, s7, 0
	v_mfma_f32_32x32x16_bf16 v[6:21], v[86:89], v[38:41], 0
	s_nop 7
	s_nop 2
	v_max_f32_e32 v108, 0, v212
	v_max_f32_e32 v109, 0, v213
	v_mul_f32_e32 v0, v22, v108
	v_mul_f32_e32 v1, v23, v109
	v_max_f32_e32 v210, 0, v214
	v_max_f32_e32 v211, 0, v215
	v_fmac_f32_e32 v0, v24, v210
	v_fmac_f32_e32 v1, v25, v211
	v_max_f32_e32 v108, 0, v216
	v_max_f32_e32 v109, 0, v217
	v_fmac_f32_e32 v0, v26, v108
	v_fmac_f32_e32 v1, v27, v109
	v_mfma_f32_32x32x16_bf16 v[6:21], v[90:93], v[42:45], v[6:21]
	v_max_f32_e32 v210, 0, v218
	v_max_f32_e32 v211, 0, v219
	v_fmac_f32_e32 v0, v28, v210
	v_fmac_f32_e32 v1, v29, v211
	v_max_f32_e32 v108, 0, v220
	v_max_f32_e32 v109, 0, v221
	v_fmac_f32_e32 v0, v30, v108
	v_fmac_f32_e32 v1, v31, v109
	v_max_f32_e32 v210, 0, v222
	v_max_f32_e32 v211, 0, v223
	v_fmac_f32_e32 v0, v32, v210
	v_fmac_f32_e32 v1, v33, v211
	v_mfma_f32_32x32x16_bf16 v[6:21], v[94:97], v[46:49], v[6:21]
	v_max_f32_e32 v108, 0, v224
	v_max_f32_e32 v109, 0, v225
	v_fmac_f32_e32 v0, v34, v108
	v_fmac_f32_e32 v1, v35, v109
	v_max_f32_e32 v210, 0, v226
	v_max_f32_e32 v211, 0, v227
	v_fmac_f32_e32 v0, v36, v210
	v_fmac_f32_e32 v1, v37, v211
	v_add_f32_e32 v0, v0, v1
	v_ashrrev_i32_e32 v1, 31, v0
	v_mfma_f32_32x32x16_bf16 v[6:21], v[98:101], v[196:199], v[6:21]
	s_waitcnt vmcnt(10)
	ds_read_b128 v[38:41], v5 offset:43264
	ds_read_b128 v[42:45], v52 offset:43264
	ds_read_b128 v[46:49], v55 offset:43264
	ds_read_b128 v[196:199], v56 offset:43264
	v_or_b32_e32 v1, 0x80000000, v1
	s_cmpk_gt_i32 s11, 192
	s_cselect_b64 vcc, -1, 0
	v_xor_b32_e32 v0, v1, v0
	v_cndmask_b32_e32 v158, v123, v0, vcc
	s_nop 3
	s_waitcnt lgkmcnt(3)
	v_mfma_f32_32x32x16_bf16 v[212:227], v[70:73], v[38:41], 0
	v_max_f32_e32 v108, 0, v6
	v_max_f32_e32 v109, 0, v7
	v_mul_f32_e32 v50, v244, v108
	v_mul_f32_e32 v51, v245, v109
	v_max_f32_e32 v210, 0, v8
	v_max_f32_e32 v211, 0, v9
	v_fmac_f32_e32 v50, v246, v210
	v_fmac_f32_e32 v51, v247, v211
	v_max_f32_e32 v108, 0, v10
	v_max_f32_e32 v109, 0, v11
	v_fmac_f32_e32 v50, v248, v108
	v_fmac_f32_e32 v51, v249, v109
	s_waitcnt lgkmcnt(2)
	v_mfma_f32_32x32x16_bf16 v[212:227], v[74:77], v[42:45], v[212:227]
	v_max_f32_e32 v210, 0, v12
	v_max_f32_e32 v211, 0, v13
	v_fmac_f32_e32 v50, v250, v210
	v_fmac_f32_e32 v51, v251, v211
	v_max_f32_e32 v108, 0, v14
	v_max_f32_e32 v109, 0, v15
	v_fmac_f32_e32 v50, v252, v108
	v_fmac_f32_e32 v51, v253, v109
	v_max_f32_e32 v210, 0, v16
	v_max_f32_e32 v211, 0, v17
	v_fmac_f32_e32 v50, v254, v210
	v_fmac_f32_e32 v51, v255, v211
	s_waitcnt lgkmcnt(1)
	v_mfma_f32_32x32x16_bf16 v[212:227], v[78:81], v[46:49], v[212:227]
	v_max_f32_e32 v108, 0, v18
	v_max_f32_e32 v109, 0, v19
	v_fmac_f32_e32 v50, v200, v108
	v_fmac_f32_e32 v51, v201, v109
	v_max_f32_e32 v210, 0, v20
	v_max_f32_e32 v211, 0, v21
	v_fmac_f32_e32 v50, v202, v210
	v_fmac_f32_e32 v51, v203, v211
	v_add_f32_e32 v50, v50, v51
	v_ashrrev_i32_e32 v51, 31, v50
	s_waitcnt lgkmcnt(0)
	v_mfma_f32_32x32x16_bf16 v[212:227], v[82:85], v[196:199], v[212:227]
	v_or_b32_e32 v51, 0x80000000, v51
	s_cmpk_gt_i32 s11, 192
	s_cselect_b64 vcc, -1, 0
	v_xor_b32_e32 v50, v51, v50
	v_cndmask_b32_e32 v50, v123, v50, vcc
	global_store_dword v243, v50, s[8:9]
	v_mfma_f32_32x32x16_bf16 v[6:21], v[86:89], v[38:41], 0
	s_add_i32 m0, s10, 0
	s_nop 0
	global_load_lds_dwordx4 v102, s[6:7]
	s_add_i32 m0, s10, 1024
	s_nop 0
	global_load_lds_dwordx4 v110, s[6:7]
	s_add_i32 m0, s10, 2048
	s_nop 0
	global_load_lds_dwordx4 v112, s[6:7]
	s_add_i32 m0, s10, 3072
	s_nop 0
	global_load_lds_dwordx4 v193, s[6:7]
	s_add_u32 s6, s6, 0x8000
	s_addc_u32 s7, s7, 0
	v_max_f32_e32 v108, 0, v212
	v_max_f32_e32 v109, 0, v213
	v_mul_f32_e32 v0, v22, v108
	v_mul_f32_e32 v1, v23, v109
	v_max_f32_e32 v210, 0, v214
	v_max_f32_e32 v211, 0, v215
	v_fmac_f32_e32 v0, v24, v210
	v_fmac_f32_e32 v1, v25, v211
	v_max_f32_e32 v108, 0, v216
	v_max_f32_e32 v109, 0, v217
	v_fmac_f32_e32 v0, v26, v108
	v_fmac_f32_e32 v1, v27, v109
	v_mfma_f32_32x32x16_bf16 v[6:21], v[90:93], v[42:45], v[6:21]
	v_max_f32_e32 v210, 0, v218
	v_max_f32_e32 v211, 0, v219
	v_fmac_f32_e32 v0, v28, v210
	v_fmac_f32_e32 v1, v29, v211
	v_max_f32_e32 v108, 0, v220
	v_max_f32_e32 v109, 0, v221
	v_fmac_f32_e32 v0, v30, v108
	v_fmac_f32_e32 v1, v31, v109
	v_max_f32_e32 v210, 0, v222
	v_max_f32_e32 v211, 0, v223
	v_fmac_f32_e32 v0, v32, v210
	v_fmac_f32_e32 v1, v33, v211
	v_mfma_f32_32x32x16_bf16 v[6:21], v[94:97], v[46:49], v[6:21]
	v_max_f32_e32 v108, 0, v224
	v_max_f32_e32 v109, 0, v225
	v_fmac_f32_e32 v0, v34, v108
	v_fmac_f32_e32 v1, v35, v109
	v_max_f32_e32 v210, 0, v226
	v_max_f32_e32 v211, 0, v227
	v_fmac_f32_e32 v0, v36, v210
	v_fmac_f32_e32 v1, v37, v211
	v_add_f32_e32 v0, v0, v1
	v_ashrrev_i32_e32 v1, 31, v0
	v_mfma_f32_32x32x16_bf16 v[6:21], v[98:101], v[196:199], v[6:21]
	s_waitcnt vmcnt(10)
	v_add_u32_e32 v228, 0x10000, v5
	ds_read_b128 v[38:41], v228 offset:10496
	v_add_u32_e32 v228, 0x10000, v52
	ds_read_b128 v[42:45], v228 offset:10496
	v_add_u32_e32 v228, 0x10000, v55
	ds_read_b128 v[46:49], v228 offset:10496
	v_add_u32_e32 v228, 0x10000, v56
	ds_read_b128 v[196:199], v228 offset:10496
	v_or_b32_e32 v1, 0x80000000, v1
	s_cmpk_gt_i32 s11, 200
	s_cselect_b64 vcc, -1, 0
	v_xor_b32_e32 v0, v1, v0
	v_cndmask_b32_e32 v157, v123, v0, vcc
	s_nop 3
	s_waitcnt lgkmcnt(3)
	v_mfma_f32_32x32x16_bf16 v[212:227], v[70:73], v[38:41], 0
	v_max_f32_e32 v108, 0, v6
	v_max_f32_e32 v109, 0, v7
	v_mul_f32_e32 v50, v244, v108
	v_mul_f32_e32 v51, v245, v109
	v_max_f32_e32 v210, 0, v8
	v_max_f32_e32 v211, 0, v9
	v_fmac_f32_e32 v50, v246, v210
	v_fmac_f32_e32 v51, v247, v211
	v_max_f32_e32 v108, 0, v10
	v_max_f32_e32 v109, 0, v11
	v_fmac_f32_e32 v50, v248, v108
	v_fmac_f32_e32 v51, v249, v109
	s_waitcnt lgkmcnt(2)
	v_mfma_f32_32x32x16_bf16 v[212:227], v[74:77], v[42:45], v[212:227]
	v_max_f32_e32 v210, 0, v12
	v_max_f32_e32 v211, 0, v13
	v_fmac_f32_e32 v50, v250, v210
	v_fmac_f32_e32 v51, v251, v211
	v_max_f32_e32 v108, 0, v14
	v_max_f32_e32 v109, 0, v15
	v_fmac_f32_e32 v50, v252, v108
	v_fmac_f32_e32 v51, v253, v109
	v_max_f32_e32 v210, 0, v16
	v_max_f32_e32 v211, 0, v17
	v_fmac_f32_e32 v50, v254, v210
	v_fmac_f32_e32 v51, v255, v211
	s_waitcnt lgkmcnt(1)
	v_mfma_f32_32x32x16_bf16 v[212:227], v[78:81], v[46:49], v[212:227]
	v_max_f32_e32 v108, 0, v18
	v_max_f32_e32 v109, 0, v19
	v_fmac_f32_e32 v50, v200, v108
	v_fmac_f32_e32 v51, v201, v109
	v_max_f32_e32 v210, 0, v20
	v_max_f32_e32 v211, 0, v21
	v_fmac_f32_e32 v50, v202, v210
	v_fmac_f32_e32 v51, v203, v211
	v_add_f32_e32 v50, v50, v51
	v_ashrrev_i32_e32 v51, 31, v50
	s_waitcnt lgkmcnt(0)
	v_mfma_f32_32x32x16_bf16 v[212:227], v[82:85], v[196:199], v[212:227]
	v_or_b32_e32 v51, 0x80000000, v51
	s_cmpk_gt_i32 s11, 200
	s_cselect_b64 vcc, -1, 0
	v_xor_b32_e32 v50, v51, v50
	v_cndmask_b32_e32 v50, v123, v50, vcc
	global_store_dword v243, v50, s[8:9] offset:2048
	s_add_u32 s8, s8, 0x1000
	s_addc_u32 s9, s9, 0
	v_mfma_f32_32x32x16_bf16 v[6:21], v[86:89], v[38:41], 0
	s_add_i32 m0, s10, 32768
	s_nop 0
	global_load_lds_dwordx4 v102, s[6:7]
	s_add_i32 m0, s10, 33792
	s_nop 0
	global_load_lds_dwordx4 v110, s[6:7]
	s_add_i32 m0, s10, 34816
	s_nop 0
	global_load_lds_dwordx4 v112, s[6:7]
	s_add_i32 m0, s10, 35840
	s_nop 0
	global_load_lds_dwordx4 v193, s[6:7]
	s_add_u32 s6, s6, 0x8000
	s_addc_u32 s7, s7, 0
	v_max_f32_e32 v108, 0, v212
	v_max_f32_e32 v109, 0, v213
	v_mul_f32_e32 v0, v22, v108
	v_mul_f32_e32 v1, v23, v109
	v_max_f32_e32 v210, 0, v214
	v_max_f32_e32 v211, 0, v215
	v_fmac_f32_e32 v0, v24, v210
	v_fmac_f32_e32 v1, v25, v211
	v_max_f32_e32 v108, 0, v216
	v_max_f32_e32 v109, 0, v217
	v_fmac_f32_e32 v0, v26, v108
	v_fmac_f32_e32 v1, v27, v109
	v_mfma_f32_32x32x16_bf16 v[6:21], v[90:93], v[42:45], v[6:21]
	v_max_f32_e32 v210, 0, v218
	v_max_f32_e32 v211, 0, v219
	v_fmac_f32_e32 v0, v28, v210
	v_fmac_f32_e32 v1, v29, v211
	v_max_f32_e32 v108, 0, v220
	v_max_f32_e32 v109, 0, v221
	v_fmac_f32_e32 v0, v30, v108
	v_fmac_f32_e32 v1, v31, v109
	v_max_f32_e32 v210, 0, v222
	v_max_f32_e32 v211, 0, v223
	v_fmac_f32_e32 v0, v32, v210
	v_fmac_f32_e32 v1, v33, v211
	v_mfma_f32_32x32x16_bf16 v[6:21], v[94:97], v[46:49], v[6:21]
	v_max_f32_e32 v108, 0, v224
	v_max_f32_e32 v109, 0, v225
	v_fmac_f32_e32 v0, v34, v108
	v_fmac_f32_e32 v1, v35, v109
	v_max_f32_e32 v210, 0, v226
	v_max_f32_e32 v211, 0, v227
	v_fmac_f32_e32 v0, v36, v210
	v_fmac_f32_e32 v1, v37, v211
	v_add_f32_e32 v0, v0, v1
	v_ashrrev_i32_e32 v1, 31, v0
	v_mfma_f32_32x32x16_bf16 v[6:21], v[98:101], v[196:199], v[6:21]
	s_waitcnt vmcnt(10)
	v_add_u32_e32 v228, 0x10000, v5
	ds_read_b128 v[38:41], v228 offset:43264
	v_add_u32_e32 v228, 0x10000, v52
	ds_read_b128 v[42:45], v228 offset:43264
	v_add_u32_e32 v228, 0x10000, v55
	ds_read_b128 v[46:49], v228 offset:43264
	v_add_u32_e32 v228, 0x10000, v56
	ds_read_b128 v[196:199], v228 offset:43264
	v_or_b32_e32 v1, 0x80000000, v1
	s_cmpk_gt_i32 s11, 208
	s_cselect_b64 vcc, -1, 0
	v_xor_b32_e32 v0, v1, v0
	v_cndmask_b32_e32 v160, v123, v0, vcc
	s_nop 3
	s_waitcnt lgkmcnt(3)
	v_mfma_f32_32x32x16_bf16 v[212:227], v[70:73], v[38:41], 0
	v_max_f32_e32 v108, 0, v6
	v_max_f32_e32 v109, 0, v7
	v_mul_f32_e32 v50, v244, v108
	v_mul_f32_e32 v51, v245, v109
	v_max_f32_e32 v210, 0, v8
	v_max_f32_e32 v211, 0, v9
	v_fmac_f32_e32 v50, v246, v210
	v_fmac_f32_e32 v51, v247, v211
	v_max_f32_e32 v108, 0, v10
	v_max_f32_e32 v109, 0, v11
	v_fmac_f32_e32 v50, v248, v108
	v_fmac_f32_e32 v51, v249, v109
	s_waitcnt lgkmcnt(2)
	v_mfma_f32_32x32x16_bf16 v[212:227], v[74:77], v[42:45], v[212:227]
	v_max_f32_e32 v210, 0, v12
	v_max_f32_e32 v211, 0, v13
	v_fmac_f32_e32 v50, v250, v210
	v_fmac_f32_e32 v51, v251, v211
	v_max_f32_e32 v108, 0, v14
	v_max_f32_e32 v109, 0, v15
	v_fmac_f32_e32 v50, v252, v108
	v_fmac_f32_e32 v51, v253, v109
	v_max_f32_e32 v210, 0, v16
	v_max_f32_e32 v211, 0, v17
	v_fmac_f32_e32 v50, v254, v210
	v_fmac_f32_e32 v51, v255, v211
	s_waitcnt lgkmcnt(1)
	v_mfma_f32_32x32x16_bf16 v[212:227], v[78:81], v[46:49], v[212:227]
	v_max_f32_e32 v108, 0, v18
	v_max_f32_e32 v109, 0, v19
	v_fmac_f32_e32 v50, v200, v108
	v_fmac_f32_e32 v51, v201, v109
	v_max_f32_e32 v210, 0, v20
	v_max_f32_e32 v211, 0, v21
	v_fmac_f32_e32 v50, v202, v210
	v_fmac_f32_e32 v51, v203, v211
	v_add_f32_e32 v50, v50, v51
	v_ashrrev_i32_e32 v51, 31, v50
	s_waitcnt lgkmcnt(0)
	v_mfma_f32_32x32x16_bf16 v[212:227], v[82:85], v[196:199], v[212:227]
	v_or_b32_e32 v51, 0x80000000, v51
	s_cmpk_gt_i32 s11, 208
	s_cselect_b64 vcc, -1, 0
	v_xor_b32_e32 v50, v51, v50
	v_cndmask_b32_e32 v50, v123, v50, vcc
	global_store_dword v243, v50, s[8:9]
	v_mfma_f32_32x32x16_bf16 v[6:21], v[86:89], v[38:41], 0
	s_add_i32 m0, s10, 65536
	s_nop 0
	global_load_lds_dwordx4 v102, s[6:7]
	s_add_i32 m0, s10, 66560
	s_nop 0
	global_load_lds_dwordx4 v110, s[6:7]
	s_add_i32 m0, s10, 67584
	s_nop 0
	global_load_lds_dwordx4 v112, s[6:7]
	s_add_i32 m0, s10, 68608
	s_nop 0
	global_load_lds_dwordx4 v193, s[6:7]
	s_add_u32 s6, s6, 0x8000
	s_addc_u32 s7, s7, 0
	v_max_f32_e32 v108, 0, v212
	v_max_f32_e32 v109, 0, v213
	v_mul_f32_e32 v0, v22, v108
	v_mul_f32_e32 v1, v23, v109
	v_max_f32_e32 v210, 0, v214
	v_max_f32_e32 v211, 0, v215
	v_fmac_f32_e32 v0, v24, v210
	v_fmac_f32_e32 v1, v25, v211
	v_max_f32_e32 v108, 0, v216
	v_max_f32_e32 v109, 0, v217
	v_fmac_f32_e32 v0, v26, v108
	v_fmac_f32_e32 v1, v27, v109
	v_mfma_f32_32x32x16_bf16 v[6:21], v[90:93], v[42:45], v[6:21]
	v_max_f32_e32 v210, 0, v218
	v_max_f32_e32 v211, 0, v219
	v_fmac_f32_e32 v0, v28, v210
	v_fmac_f32_e32 v1, v29, v211
	v_max_f32_e32 v108, 0, v220
	v_max_f32_e32 v109, 0, v221
	v_fmac_f32_e32 v0, v30, v108
	v_fmac_f32_e32 v1, v31, v109
	v_max_f32_e32 v210, 0, v222
	v_max_f32_e32 v211, 0, v223
	v_fmac_f32_e32 v0, v32, v210
	v_fmac_f32_e32 v1, v33, v211
	v_mfma_f32_32x32x16_bf16 v[6:21], v[94:97], v[46:49], v[6:21]
	v_max_f32_e32 v108, 0, v224
	v_max_f32_e32 v109, 0, v225
	v_fmac_f32_e32 v0, v34, v108
	v_fmac_f32_e32 v1, v35, v109
	v_max_f32_e32 v210, 0, v226
	v_max_f32_e32 v211, 0, v227
	v_fmac_f32_e32 v0, v36, v210
	v_fmac_f32_e32 v1, v37, v211
	v_add_f32_e32 v0, v0, v1
	v_ashrrev_i32_e32 v1, 31, v0
	v_mfma_f32_32x32x16_bf16 v[6:21], v[98:101], v[196:199], v[6:21]
	s_waitcnt vmcnt(10)
	ds_read_b128 v[38:41], v5 offset:10496
	ds_read_b128 v[42:45], v52 offset:10496
	ds_read_b128 v[46:49], v55 offset:10496
	ds_read_b128 v[196:199], v56 offset:10496
	v_or_b32_e32 v1, 0x80000000, v1
	s_cmpk_gt_i32 s11, 216
	s_cselect_b64 vcc, -1, 0
	v_xor_b32_e32 v0, v1, v0
	v_cndmask_b32_e32 v159, v123, v0, vcc
	s_nop 3
	s_waitcnt lgkmcnt(3)
	v_mfma_f32_32x32x16_bf16 v[212:227], v[70:73], v[38:41], 0
	v_max_f32_e32 v108, 0, v6
	v_max_f32_e32 v109, 0, v7
	v_mul_f32_e32 v50, v244, v108
	v_mul_f32_e32 v51, v245, v109
	v_max_f32_e32 v210, 0, v8
	v_max_f32_e32 v211, 0, v9
	v_fmac_f32_e32 v50, v246, v210
	v_fmac_f32_e32 v51, v247, v211
	v_max_f32_e32 v108, 0, v10
	v_max_f32_e32 v109, 0, v11
	v_fmac_f32_e32 v50, v248, v108
	v_fmac_f32_e32 v51, v249, v109
	s_waitcnt lgkmcnt(2)
	v_mfma_f32_32x32x16_bf16 v[212:227], v[74:77], v[42:45], v[212:227]
	v_max_f32_e32 v210, 0, v12
	v_max_f32_e32 v211, 0, v13
	v_fmac_f32_e32 v50, v250, v210
	v_fmac_f32_e32 v51, v251, v211
	v_max_f32_e32 v108, 0, v14
	v_max_f32_e32 v109, 0, v15
	v_fmac_f32_e32 v50, v252, v108
	v_fmac_f32_e32 v51, v253, v109
	v_max_f32_e32 v210, 0, v16
	v_max_f32_e32 v211, 0, v17
	v_fmac_f32_e32 v50, v254, v210
	v_fmac_f32_e32 v51, v255, v211
	s_waitcnt lgkmcnt(1)
	v_mfma_f32_32x32x16_bf16 v[212:227], v[78:81], v[46:49], v[212:227]
	v_max_f32_e32 v108, 0, v18
	v_max_f32_e32 v109, 0, v19
	v_fmac_f32_e32 v50, v200, v108
	v_fmac_f32_e32 v51, v201, v109
	v_max_f32_e32 v210, 0, v20
	v_max_f32_e32 v211, 0, v21
	v_fmac_f32_e32 v50, v202, v210
	v_fmac_f32_e32 v51, v203, v211
	v_add_f32_e32 v50, v50, v51
	v_ashrrev_i32_e32 v51, 31, v50
	s_waitcnt lgkmcnt(0)
	v_mfma_f32_32x32x16_bf16 v[212:227], v[82:85], v[196:199], v[212:227]
	v_or_b32_e32 v51, 0x80000000, v51
	s_cmpk_gt_i32 s11, 216
	s_cselect_b64 vcc, -1, 0
	v_xor_b32_e32 v50, v51, v50
	v_cndmask_b32_e32 v50, v123, v50, vcc
	global_store_dword v243, v50, s[8:9] offset:2048
	s_add_u32 s8, s8, 0x1000
	s_addc_u32 s9, s9, 0
	v_mfma_f32_32x32x16_bf16 v[6:21], v[86:89], v[38:41], 0
	s_add_i32 m0, s10, 98304
	s_nop 0
	global_load_lds_dwordx4 v102, s[6:7]
	s_add_i32 m0, s10, 99328
	s_nop 0
	global_load_lds_dwordx4 v110, s[6:7]
	s_add_i32 m0, s10, 100352
	s_nop 0
	global_load_lds_dwordx4 v112, s[6:7]
	s_add_i32 m0, s10, 101376
	s_nop 0
	global_load_lds_dwordx4 v193, s[6:7]
	s_add_u32 s6, s6, 0x8000
	s_addc_u32 s7, s7, 0
	v_max_f32_e32 v108, 0, v212
	v_max_f32_e32 v109, 0, v213
	v_mul_f32_e32 v0, v22, v108
	v_mul_f32_e32 v1, v23, v109
	v_max_f32_e32 v210, 0, v214
	v_max_f32_e32 v211, 0, v215
	v_fmac_f32_e32 v0, v24, v210
	v_fmac_f32_e32 v1, v25, v211
	v_max_f32_e32 v108, 0, v216
	v_max_f32_e32 v109, 0, v217
	v_fmac_f32_e32 v0, v26, v108
	v_fmac_f32_e32 v1, v27, v109
	v_mfma_f32_32x32x16_bf16 v[6:21], v[90:93], v[42:45], v[6:21]
	v_max_f32_e32 v210, 0, v218
	v_max_f32_e32 v211, 0, v219
	v_fmac_f32_e32 v0, v28, v210
	v_fmac_f32_e32 v1, v29, v211
	v_max_f32_e32 v108, 0, v220
	v_max_f32_e32 v109, 0, v221
	v_fmac_f32_e32 v0, v30, v108
	v_fmac_f32_e32 v1, v31, v109
	v_max_f32_e32 v210, 0, v222
	v_max_f32_e32 v211, 0, v223
	v_fmac_f32_e32 v0, v32, v210
	v_fmac_f32_e32 v1, v33, v211
	v_mfma_f32_32x32x16_bf16 v[6:21], v[94:97], v[46:49], v[6:21]
	v_max_f32_e32 v108, 0, v224
	v_max_f32_e32 v109, 0, v225
	v_fmac_f32_e32 v0, v34, v108
	v_fmac_f32_e32 v1, v35, v109
	v_max_f32_e32 v210, 0, v226
	v_max_f32_e32 v211, 0, v227
	v_fmac_f32_e32 v0, v36, v210
	v_fmac_f32_e32 v1, v37, v211
	v_add_f32_e32 v0, v0, v1
	v_ashrrev_i32_e32 v1, 31, v0
	v_mfma_f32_32x32x16_bf16 v[6:21], v[98:101], v[196:199], v[6:21]
	s_waitcnt vmcnt(10)
	ds_read_b128 v[38:41], v5 offset:43264
	ds_read_b128 v[42:45], v52 offset:43264
	ds_read_b128 v[46:49], v55 offset:43264
	ds_read_b128 v[196:199], v56 offset:43264
	v_or_b32_e32 v1, 0x80000000, v1
	s_cmpk_gt_i32 s11, 224
	s_cselect_b64 vcc, -1, 0
	v_xor_b32_e32 v0, v1, v0
	v_cndmask_b32_e32 v162, v123, v0, vcc
	s_nop 3
	s_waitcnt lgkmcnt(3)
	v_mfma_f32_32x32x16_bf16 v[212:227], v[70:73], v[38:41], 0
	v_max_f32_e32 v108, 0, v6
	v_max_f32_e32 v109, 0, v7
	v_mul_f32_e32 v50, v244, v108
	v_mul_f32_e32 v51, v245, v109
	v_max_f32_e32 v210, 0, v8
	v_max_f32_e32 v211, 0, v9
	v_fmac_f32_e32 v50, v246, v210
	v_fmac_f32_e32 v51, v247, v211
	v_max_f32_e32 v108, 0, v10
	v_max_f32_e32 v109, 0, v11
	v_fmac_f32_e32 v50, v248, v108
	v_fmac_f32_e32 v51, v249, v109
	s_waitcnt lgkmcnt(2)
	v_mfma_f32_32x32x16_bf16 v[212:227], v[74:77], v[42:45], v[212:227]
	v_max_f32_e32 v210, 0, v12
	v_max_f32_e32 v211, 0, v13
	v_fmac_f32_e32 v50, v250, v210
	v_fmac_f32_e32 v51, v251, v211
	v_max_f32_e32 v108, 0, v14
	v_max_f32_e32 v109, 0, v15
	v_fmac_f32_e32 v50, v252, v108
	v_fmac_f32_e32 v51, v253, v109
	v_max_f32_e32 v210, 0, v16
	v_max_f32_e32 v211, 0, v17
	v_fmac_f32_e32 v50, v254, v210
	v_fmac_f32_e32 v51, v255, v211
	s_waitcnt lgkmcnt(1)
	v_mfma_f32_32x32x16_bf16 v[212:227], v[78:81], v[46:49], v[212:227]
	v_max_f32_e32 v108, 0, v18
	v_max_f32_e32 v109, 0, v19
	v_fmac_f32_e32 v50, v200, v108
	v_fmac_f32_e32 v51, v201, v109
	v_max_f32_e32 v210, 0, v20
	v_max_f32_e32 v211, 0, v21
	v_fmac_f32_e32 v50, v202, v210
	v_fmac_f32_e32 v51, v203, v211
	v_add_f32_e32 v50, v50, v51
	v_ashrrev_i32_e32 v51, 31, v50
	s_waitcnt lgkmcnt(0)
	v_mfma_f32_32x32x16_bf16 v[212:227], v[82:85], v[196:199], v[212:227]
	v_or_b32_e32 v51, 0x80000000, v51
	s_cmpk_gt_i32 s11, 224
	s_cselect_b64 vcc, -1, 0
	v_xor_b32_e32 v50, v51, v50
	v_cndmask_b32_e32 v50, v123, v50, vcc
	global_store_dword v243, v50, s[8:9]
	v_mfma_f32_32x32x16_bf16 v[6:21], v[86:89], v[38:41], 0
	s_add_i32 m0, s10, 0
	s_nop 0
	global_load_lds_dwordx4 v102, s[6:7]
	s_add_i32 m0, s10, 1024
	s_nop 0
	global_load_lds_dwordx4 v110, s[6:7]
	s_add_i32 m0, s10, 2048
	s_nop 0
	global_load_lds_dwordx4 v112, s[6:7]
	s_add_i32 m0, s10, 3072
	s_nop 0
	global_load_lds_dwordx4 v193, s[6:7]
	s_add_u32 s6, s6, 0x8000
	s_addc_u32 s7, s7, 0
	v_max_f32_e32 v108, 0, v212
	v_max_f32_e32 v109, 0, v213
	v_mul_f32_e32 v0, v22, v108
	v_mul_f32_e32 v1, v23, v109
	v_max_f32_e32 v210, 0, v214
	v_max_f32_e32 v211, 0, v215
	v_fmac_f32_e32 v0, v24, v210
	v_fmac_f32_e32 v1, v25, v211
	v_max_f32_e32 v108, 0, v216
	v_max_f32_e32 v109, 0, v217
	v_fmac_f32_e32 v0, v26, v108
	v_fmac_f32_e32 v1, v27, v109
	v_mfma_f32_32x32x16_bf16 v[6:21], v[90:93], v[42:45], v[6:21]
	v_max_f32_e32 v210, 0, v218
	v_max_f32_e32 v211, 0, v219
	v_fmac_f32_e32 v0, v28, v210
	v_fmac_f32_e32 v1, v29, v211
	v_max_f32_e32 v108, 0, v220
	v_max_f32_e32 v109, 0, v221
	v_fmac_f32_e32 v0, v30, v108
	v_fmac_f32_e32 v1, v31, v109
	v_max_f32_e32 v210, 0, v222
	v_max_f32_e32 v211, 0, v223
	v_fmac_f32_e32 v0, v32, v210
	v_fmac_f32_e32 v1, v33, v211
	v_mfma_f32_32x32x16_bf16 v[6:21], v[94:97], v[46:49], v[6:21]
	v_max_f32_e32 v108, 0, v224
	v_max_f32_e32 v109, 0, v225
	v_fmac_f32_e32 v0, v34, v108
	v_fmac_f32_e32 v1, v35, v109
	v_max_f32_e32 v210, 0, v226
	v_max_f32_e32 v211, 0, v227
	v_fmac_f32_e32 v0, v36, v210
	v_fmac_f32_e32 v1, v37, v211
	v_add_f32_e32 v0, v0, v1
	v_ashrrev_i32_e32 v1, 31, v0
	v_mfma_f32_32x32x16_bf16 v[6:21], v[98:101], v[196:199], v[6:21]
	s_waitcnt vmcnt(10)
	v_add_u32_e32 v228, 0x10000, v5
	ds_read_b128 v[38:41], v228 offset:10496
	v_add_u32_e32 v228, 0x10000, v52
	ds_read_b128 v[42:45], v228 offset:10496
	v_add_u32_e32 v228, 0x10000, v55
	ds_read_b128 v[46:49], v228 offset:10496
	v_add_u32_e32 v228, 0x10000, v56
	ds_read_b128 v[196:199], v228 offset:10496
	v_or_b32_e32 v1, 0x80000000, v1
	s_cmpk_gt_i32 s11, 232
	s_cselect_b64 vcc, -1, 0
	v_xor_b32_e32 v0, v1, v0
	v_cndmask_b32_e32 v161, v123, v0, vcc
	s_nop 3
	s_waitcnt lgkmcnt(3)
	v_mfma_f32_32x32x16_bf16 v[212:227], v[70:73], v[38:41], 0
	v_max_f32_e32 v108, 0, v6
	v_max_f32_e32 v109, 0, v7
	v_mul_f32_e32 v50, v244, v108
	v_mul_f32_e32 v51, v245, v109
	v_max_f32_e32 v210, 0, v8
	v_max_f32_e32 v211, 0, v9
	v_fmac_f32_e32 v50, v246, v210
	v_fmac_f32_e32 v51, v247, v211
	v_max_f32_e32 v108, 0, v10
	v_max_f32_e32 v109, 0, v11
	v_fmac_f32_e32 v50, v248, v108
	v_fmac_f32_e32 v51, v249, v109
	s_waitcnt lgkmcnt(2)
	v_mfma_f32_32x32x16_bf16 v[212:227], v[74:77], v[42:45], v[212:227]
	v_max_f32_e32 v210, 0, v12
	v_max_f32_e32 v211, 0, v13
	v_fmac_f32_e32 v50, v250, v210
	v_fmac_f32_e32 v51, v251, v211
	v_max_f32_e32 v108, 0, v14
	v_max_f32_e32 v109, 0, v15
	v_fmac_f32_e32 v50, v252, v108
	v_fmac_f32_e32 v51, v253, v109
	v_max_f32_e32 v210, 0, v16
	v_max_f32_e32 v211, 0, v17
	v_fmac_f32_e32 v50, v254, v210
	v_fmac_f32_e32 v51, v255, v211
	s_waitcnt lgkmcnt(1)
	v_mfma_f32_32x32x16_bf16 v[212:227], v[78:81], v[46:49], v[212:227]
	v_max_f32_e32 v108, 0, v18
	v_max_f32_e32 v109, 0, v19
	v_fmac_f32_e32 v50, v200, v108
	v_fmac_f32_e32 v51, v201, v109
	v_max_f32_e32 v210, 0, v20
	v_max_f32_e32 v211, 0, v21
	v_fmac_f32_e32 v50, v202, v210
	v_fmac_f32_e32 v51, v203, v211
	v_add_f32_e32 v50, v50, v51
	v_ashrrev_i32_e32 v51, 31, v50
	s_waitcnt lgkmcnt(0)
	v_mfma_f32_32x32x16_bf16 v[212:227], v[82:85], v[196:199], v[212:227]
	v_or_b32_e32 v51, 0x80000000, v51
	s_cmpk_gt_i32 s11, 232
	s_cselect_b64 vcc, -1, 0
	v_xor_b32_e32 v50, v51, v50
	v_cndmask_b32_e32 v50, v123, v50, vcc
	global_store_dword v243, v50, s[8:9] offset:2048
	s_add_u32 s8, s8, 0x1000
	s_addc_u32 s9, s9, 0
	v_mfma_f32_32x32x16_bf16 v[6:21], v[86:89], v[38:41], 0
	s_add_i32 m0, s10, 32768
	s_nop 0
	global_load_lds_dwordx4 v102, s[6:7]
	s_add_i32 m0, s10, 33792
	s_nop 0
	global_load_lds_dwordx4 v110, s[6:7]
	s_add_i32 m0, s10, 34816
	s_nop 0
	global_load_lds_dwordx4 v112, s[6:7]
	s_add_i32 m0, s10, 35840
	s_nop 0
	global_load_lds_dwordx4 v193, s[6:7]
	s_add_u32 s6, s6, 0x8000
	s_addc_u32 s7, s7, 0
	v_max_f32_e32 v108, 0, v212
	v_max_f32_e32 v109, 0, v213
	v_mul_f32_e32 v0, v22, v108
	v_mul_f32_e32 v1, v23, v109
	v_max_f32_e32 v210, 0, v214
	v_max_f32_e32 v211, 0, v215
	v_fmac_f32_e32 v0, v24, v210
	v_fmac_f32_e32 v1, v25, v211
	v_max_f32_e32 v108, 0, v216
	v_max_f32_e32 v109, 0, v217
	v_fmac_f32_e32 v0, v26, v108
	v_fmac_f32_e32 v1, v27, v109
	v_mfma_f32_32x32x16_bf16 v[6:21], v[90:93], v[42:45], v[6:21]
	v_max_f32_e32 v210, 0, v218
	v_max_f32_e32 v211, 0, v219
	v_fmac_f32_e32 v0, v28, v210
	v_fmac_f32_e32 v1, v29, v211
	v_max_f32_e32 v108, 0, v220
	v_max_f32_e32 v109, 0, v221
	v_fmac_f32_e32 v0, v30, v108
	v_fmac_f32_e32 v1, v31, v109
	v_max_f32_e32 v210, 0, v222
	v_max_f32_e32 v211, 0, v223
	v_fmac_f32_e32 v0, v32, v210
	v_fmac_f32_e32 v1, v33, v211
	v_mfma_f32_32x32x16_bf16 v[6:21], v[94:97], v[46:49], v[6:21]
	v_max_f32_e32 v108, 0, v224
	v_max_f32_e32 v109, 0, v225
	v_fmac_f32_e32 v0, v34, v108
	v_fmac_f32_e32 v1, v35, v109
	v_max_f32_e32 v210, 0, v226
	v_max_f32_e32 v211, 0, v227
	v_fmac_f32_e32 v0, v36, v210
	v_fmac_f32_e32 v1, v37, v211
	v_add_f32_e32 v0, v0, v1
	v_ashrrev_i32_e32 v1, 31, v0
	v_mfma_f32_32x32x16_bf16 v[6:21], v[98:101], v[196:199], v[6:21]
	s_waitcnt vmcnt(10)
	v_add_u32_e32 v228, 0x10000, v5
	ds_read_b128 v[38:41], v228 offset:43264
	v_add_u32_e32 v228, 0x10000, v52
	ds_read_b128 v[42:45], v228 offset:43264
	v_add_u32_e32 v228, 0x10000, v55
	ds_read_b128 v[46:49], v228 offset:43264
	v_add_u32_e32 v228, 0x10000, v56
	ds_read_b128 v[196:199], v228 offset:43264
	v_or_b32_e32 v1, 0x80000000, v1
	s_cmpk_gt_i32 s11, 240
	s_cselect_b64 vcc, -1, 0
	v_xor_b32_e32 v0, v1, v0
	v_cndmask_b32_e32 v163, v123, v0, vcc
	s_nop 3
	s_waitcnt lgkmcnt(3)
	v_mfma_f32_32x32x16_bf16 v[212:227], v[70:73], v[38:41], 0
	v_max_f32_e32 v108, 0, v6
	v_max_f32_e32 v109, 0, v7
	v_mul_f32_e32 v50, v244, v108
	v_mul_f32_e32 v51, v245, v109
	v_max_f32_e32 v210, 0, v8
	v_max_f32_e32 v211, 0, v9
	v_fmac_f32_e32 v50, v246, v210
	v_fmac_f32_e32 v51, v247, v211
	v_max_f32_e32 v108, 0, v10
	v_max_f32_e32 v109, 0, v11
	v_fmac_f32_e32 v50, v248, v108
	v_fmac_f32_e32 v51, v249, v109
	s_waitcnt lgkmcnt(2)
	v_mfma_f32_32x32x16_bf16 v[212:227], v[74:77], v[42:45], v[212:227]
	v_max_f32_e32 v210, 0, v12
	v_max_f32_e32 v211, 0, v13
	v_fmac_f32_e32 v50, v250, v210
	v_fmac_f32_e32 v51, v251, v211
	v_max_f32_e32 v108, 0, v14
	v_max_f32_e32 v109, 0, v15
	v_fmac_f32_e32 v50, v252, v108
	v_fmac_f32_e32 v51, v253, v109
	v_max_f32_e32 v210, 0, v16
	v_max_f32_e32 v211, 0, v17
	v_fmac_f32_e32 v50, v254, v210
	v_fmac_f32_e32 v51, v255, v211
	s_waitcnt lgkmcnt(1)
	v_mfma_f32_32x32x16_bf16 v[212:227], v[78:81], v[46:49], v[212:227]
	v_max_f32_e32 v108, 0, v18
	v_max_f32_e32 v109, 0, v19
	v_fmac_f32_e32 v50, v200, v108
	v_fmac_f32_e32 v51, v201, v109
	v_max_f32_e32 v210, 0, v20
	v_max_f32_e32 v211, 0, v21
	v_fmac_f32_e32 v50, v202, v210
	v_fmac_f32_e32 v51, v203, v211
	v_add_f32_e32 v50, v50, v51
	v_ashrrev_i32_e32 v51, 31, v50
	s_waitcnt lgkmcnt(0)
	v_mfma_f32_32x32x16_bf16 v[212:227], v[82:85], v[196:199], v[212:227]
	v_or_b32_e32 v51, 0x80000000, v51
	s_cmpk_gt_i32 s11, 240
	s_cselect_b64 vcc, -1, 0
	v_xor_b32_e32 v50, v51, v50
	v_cndmask_b32_e32 v50, v123, v50, vcc
	global_store_dword v243, v50, s[8:9]
	v_mfma_f32_32x32x16_bf16 v[6:21], v[86:89], v[38:41], 0
	s_add_i32 m0, s10, 65536
	s_nop 0
	global_load_lds_dwordx4 v102, s[6:7]
	s_add_i32 m0, s10, 66560
	s_nop 0
	global_load_lds_dwordx4 v110, s[6:7]
	s_add_i32 m0, s10, 67584
	s_nop 0
	global_load_lds_dwordx4 v112, s[6:7]
	s_add_i32 m0, s10, 68608
	s_nop 0
	global_load_lds_dwordx4 v193, s[6:7]
	s_add_u32 s6, s6, 0x8000
	s_addc_u32 s7, s7, 0
	v_max_f32_e32 v108, 0, v212
	v_max_f32_e32 v109, 0, v213
	v_mul_f32_e32 v0, v22, v108
	v_mul_f32_e32 v1, v23, v109
	v_max_f32_e32 v210, 0, v214
	v_max_f32_e32 v211, 0, v215
	v_fmac_f32_e32 v0, v24, v210
	v_fmac_f32_e32 v1, v25, v211
	v_max_f32_e32 v108, 0, v216
	v_max_f32_e32 v109, 0, v217
	v_fmac_f32_e32 v0, v26, v108
	v_fmac_f32_e32 v1, v27, v109
	v_mfma_f32_32x32x16_bf16 v[6:21], v[90:93], v[42:45], v[6:21]
	v_max_f32_e32 v210, 0, v218
	v_max_f32_e32 v211, 0, v219
	v_fmac_f32_e32 v0, v28, v210
	v_fmac_f32_e32 v1, v29, v211
	v_max_f32_e32 v108, 0, v220
	v_max_f32_e32 v109, 0, v221
	v_fmac_f32_e32 v0, v30, v108
	v_fmac_f32_e32 v1, v31, v109
	v_max_f32_e32 v210, 0, v222
	v_max_f32_e32 v211, 0, v223
	v_fmac_f32_e32 v0, v32, v210
	v_fmac_f32_e32 v1, v33, v211
	v_mfma_f32_32x32x16_bf16 v[6:21], v[94:97], v[46:49], v[6:21]
	v_max_f32_e32 v108, 0, v224
	v_max_f32_e32 v109, 0, v225
	v_fmac_f32_e32 v0, v34, v108
	v_fmac_f32_e32 v1, v35, v109
	v_max_f32_e32 v210, 0, v226
	v_max_f32_e32 v211, 0, v227
	v_fmac_f32_e32 v0, v36, v210
	v_fmac_f32_e32 v1, v37, v211
	v_add_f32_e32 v0, v0, v1
	v_ashrrev_i32_e32 v1, 31, v0
	v_mfma_f32_32x32x16_bf16 v[6:21], v[98:101], v[196:199], v[6:21]
	s_waitcnt vmcnt(10)
	ds_read_b128 v[38:41], v5 offset:10496
	ds_read_b128 v[42:45], v52 offset:10496
	ds_read_b128 v[46:49], v55 offset:10496
	ds_read_b128 v[196:199], v56 offset:10496
	v_or_b32_e32 v1, 0x80000000, v1
	s_cmpk_gt_i32 s11, 248
	s_cselect_b64 vcc, -1, 0
	v_xor_b32_e32 v0, v1, v0
	v_cndmask_b32_e32 v152, v123, v0, vcc
	s_nop 3
	v_max_f32_e32 v108, 0, v6
	v_max_f32_e32 v109, 0, v7
	v_mul_f32_e32 v50, v244, v108
	v_mul_f32_e32 v51, v245, v109
	v_max_f32_e32 v210, 0, v8
	v_max_f32_e32 v211, 0, v9
	v_fmac_f32_e32 v50, v246, v210
	v_fmac_f32_e32 v51, v247, v211
	v_max_f32_e32 v108, 0, v10
	v_max_f32_e32 v109, 0, v11
	v_fmac_f32_e32 v50, v248, v108
	v_fmac_f32_e32 v51, v249, v109
	v_max_f32_e32 v210, 0, v12
	v_max_f32_e32 v211, 0, v13
	v_fmac_f32_e32 v50, v250, v210
	v_fmac_f32_e32 v51, v251, v211
	v_max_f32_e32 v108, 0, v14
	v_max_f32_e32 v109, 0, v15
	v_fmac_f32_e32 v50, v252, v108
	v_fmac_f32_e32 v51, v253, v109
	v_max_f32_e32 v210, 0, v16
	v_max_f32_e32 v211, 0, v17
	v_fmac_f32_e32 v50, v254, v210
	v_fmac_f32_e32 v51, v255, v211
	v_max_f32_e32 v108, 0, v18
	v_max_f32_e32 v109, 0, v19
	v_fmac_f32_e32 v50, v200, v108
	v_fmac_f32_e32 v51, v201, v109
	v_max_f32_e32 v210, 0, v20
	v_max_f32_e32 v211, 0, v21
	v_fmac_f32_e32 v50, v202, v210
	v_fmac_f32_e32 v51, v203, v211
	v_add_f32_e32 v50, v50, v51
	v_ashrrev_i32_e32 v51, 31, v50
	v_or_b32_e32 v51, 0x80000000, v51
	s_cmpk_gt_i32 s11, 248
	s_cselect_b64 vcc, -1, 0
	v_xor_b32_e32 v50, v51, v50
	v_cndmask_b32_e32 v50, v123, v50, vcc
	global_store_dword v243, v50, s[8:9] offset:2048
	s_add_u32 s8, s8, 0x1000
	s_addc_u32 s9, s9, 0
	s_cmpk_gt_i32 s81, 32
	s_cbranch_scc0 .Lix_fill_4
	s_waitcnt lgkmcnt(3)
	v_mfma_f32_32x32x16_bf16 v[212:227], v[70:73], v[38:41], 0
	s_add_i32 m0, s10, 98304
	s_nop 0
	global_load_lds_dwordx4 v102, s[6:7]
	s_waitcnt lgkmcnt(2)
	v_mfma_f32_32x32x16_bf16 v[212:227], v[74:77], v[42:45], v[212:227]
	s_add_i32 m0, s10, 99328
	s_nop 0
	global_load_lds_dwordx4 v110, s[6:7]
	s_waitcnt lgkmcnt(1)
	v_mfma_f32_32x32x16_bf16 v[212:227], v[78:81], v[46:49], v[212:227]
	s_add_i32 m0, s10, 100352
	s_nop 0
	global_load_lds_dwordx4 v112, s[6:7]
	s_waitcnt lgkmcnt(0)
	v_mfma_f32_32x32x16_bf16 v[212:227], v[82:85], v[196:199], v[212:227]
	s_add_i32 m0, s10, 101376
	s_nop 0
	global_load_lds_dwordx4 v193, s[6:7]
	s_add_u32 s6, s6, 0x8000
	s_addc_u32 s7, s7, 0
	v_mfma_f32_32x32x16_bf16 v[6:21], v[86:89], v[38:41], 0
	s_nop 7
	s_nop 2
	v_max_f32_e32 v108, 0, v212
	v_max_f32_e32 v109, 0, v213
	v_mul_f32_e32 v0, v22, v108
	v_mul_f32_e32 v1, v23, v109
	v_max_f32_e32 v210, 0, v214
	v_max_f32_e32 v211, 0, v215
	v_fmac_f32_e32 v0, v24, v210
	v_fmac_f32_e32 v1, v25, v211
	v_max_f32_e32 v108, 0, v216
	v_max_f32_e32 v109, 0, v217
	v_fmac_f32_e32 v0, v26, v108
	v_fmac_f32_e32 v1, v27, v109
	v_mfma_f32_32x32x16_bf16 v[6:21], v[90:93], v[42:45], v[6:21]
	v_max_f32_e32 v210, 0, v218
	v_max_f32_e32 v211, 0, v219
	v_fmac_f32_e32 v0, v28, v210
	v_fmac_f32_e32 v1, v29, v211
	v_max_f32_e32 v108, 0, v220
	v_max_f32_e32 v109, 0, v221
	v_fmac_f32_e32 v0, v30, v108
	v_fmac_f32_e32 v1, v31, v109
	v_max_f32_e32 v210, 0, v222
	v_max_f32_e32 v211, 0, v223
	v_fmac_f32_e32 v0, v32, v210
	v_fmac_f32_e32 v1, v33, v211
	v_mfma_f32_32x32x16_bf16 v[6:21], v[94:97], v[46:49], v[6:21]
	v_max_f32_e32 v108, 0, v224
	v_max_f32_e32 v109, 0, v225
	v_fmac_f32_e32 v0, v34, v108
	v_fmac_f32_e32 v1, v35, v109
	v_max_f32_e32 v210, 0, v226
	v_max_f32_e32 v211, 0, v227
	v_fmac_f32_e32 v0, v36, v210
	v_fmac_f32_e32 v1, v37, v211
	v_add_f32_e32 v0, v0, v1
	v_ashrrev_i32_e32 v1, 31, v0
	v_mfma_f32_32x32x16_bf16 v[6:21], v[98:101], v[196:199], v[6:21]
	s_waitcnt vmcnt(10)
	ds_read_b128 v[38:41], v5 offset:43264
	ds_read_b128 v[42:45], v52 offset:43264
	ds_read_b128 v[46:49], v55 offset:43264
	ds_read_b128 v[196:199], v56 offset:43264
	v_or_b32_e32 v1, 0x80000000, v1
	s_cmpk_gt_i32 s11, 256
	s_cselect_b64 vcc, -1, 0
	v_xor_b32_e32 v0, v1, v0
	v_cndmask_b32_e32 v165, v123, v0, vcc
	s_nop 3
	s_waitcnt lgkmcnt(3)
	v_mfma_f32_32x32x16_bf16 v[212:227], v[70:73], v[38:41], 0
	v_max_f32_e32 v108, 0, v6
	v_max_f32_e32 v109, 0, v7
	v_mul_f32_e32 v50, v244, v108
	v_mul_f32_e32 v51, v245, v109
	v_max_f32_e32 v210, 0, v8
	v_max_f32_e32 v211, 0, v9
	v_fmac_f32_e32 v50, v246, v210
	v_fmac_f32_e32 v51, v247, v211
	v_max_f32_e32 v108, 0, v10
	v_max_f32_e32 v109, 0, v11
	v_fmac_f32_e32 v50, v248, v108
	v_fmac_f32_e32 v51, v249, v109
	s_waitcnt lgkmcnt(2)
	v_mfma_f32_32x32x16_bf16 v[212:227], v[74:77], v[42:45], v[212:227]
	v_max_f32_e32 v210, 0, v12
	v_max_f32_e32 v211, 0, v13
	v_fmac_f32_e32 v50, v250, v210
	v_fmac_f32_e32 v51, v251, v211
	v_max_f32_e32 v108, 0, v14
	v_max_f32_e32 v109, 0, v15
	v_fmac_f32_e32 v50, v252, v108
	v_fmac_f32_e32 v51, v253, v109
	v_max_f32_e32 v210, 0, v16
	v_max_f32_e32 v211, 0, v17
	v_fmac_f32_e32 v50, v254, v210
	v_fmac_f32_e32 v51, v255, v211
	s_waitcnt lgkmcnt(1)
	v_mfma_f32_32x32x16_bf16 v[212:227], v[78:81], v[46:49], v[212:227]
	v_max_f32_e32 v108, 0, v18
	v_max_f32_e32 v109, 0, v19
	v_fmac_f32_e32 v50, v200, v108
	v_fmac_f32_e32 v51, v201, v109
	v_max_f32_e32 v210, 0, v20
	v_max_f32_e32 v211, 0, v21
	v_fmac_f32_e32 v50, v202, v210
	v_fmac_f32_e32 v51, v203, v211
	v_add_f32_e32 v50, v50, v51
	v_ashrrev_i32_e32 v51, 31, v50
	s_waitcnt lgkmcnt(0)
	v_mfma_f32_32x32x16_bf16 v[212:227], v[82:85], v[196:199], v[212:227]
	v_or_b32_e32 v51, 0x80000000, v51
	s_cmpk_gt_i32 s11, 256
	s_cselect_b64 vcc, -1, 0
	v_xor_b32_e32 v50, v51, v50
	v_cndmask_b32_e32 v50, v123, v50, vcc
	global_store_dword v243, v50, s[8:9]
	v_mfma_f32_32x32x16_bf16 v[6:21], v[86:89], v[38:41], 0
	s_add_i32 m0, s10, 0
	s_nop 0
	global_load_lds_dwordx4 v102, s[6:7]
	s_add_i32 m0, s10, 1024
	s_nop 0
	global_load_lds_dwordx4 v110, s[6:7]
	s_add_i32 m0, s10, 2048
	s_nop 0
	global_load_lds_dwordx4 v112, s[6:7]
	s_add_i32 m0, s10, 3072
	s_nop 0
	global_load_lds_dwordx4 v193, s[6:7]
	s_add_u32 s6, s6, 0x8000
	s_addc_u32 s7, s7, 0
	v_max_f32_e32 v108, 0, v212
	v_max_f32_e32 v109, 0, v213
	v_mul_f32_e32 v0, v22, v108
	v_mul_f32_e32 v1, v23, v109
	v_max_f32_e32 v210, 0, v214
	v_max_f32_e32 v211, 0, v215
	v_fmac_f32_e32 v0, v24, v210
	v_fmac_f32_e32 v1, v25, v211
	v_max_f32_e32 v108, 0, v216
	v_max_f32_e32 v109, 0, v217
	v_fmac_f32_e32 v0, v26, v108
	v_fmac_f32_e32 v1, v27, v109
	v_mfma_f32_32x32x16_bf16 v[6:21], v[90:93], v[42:45], v[6:21]
	v_max_f32_e32 v210, 0, v218
	v_max_f32_e32 v211, 0, v219
	v_fmac_f32_e32 v0, v28, v210
	v_fmac_f32_e32 v1, v29, v211
	v_max_f32_e32 v108, 0, v220
	v_max_f32_e32 v109, 0, v221
	v_fmac_f32_e32 v0, v30, v108
	v_fmac_f32_e32 v1, v31, v109
	v_max_f32_e32 v210, 0, v222
	v_max_f32_e32 v211, 0, v223
	v_fmac_f32_e32 v0, v32, v210
	v_fmac_f32_e32 v1, v33, v211
	v_mfma_f32_32x32x16_bf16 v[6:21], v[94:97], v[46:49], v[6:21]
	v_max_f32_e32 v108, 0, v224
	v_max_f32_e32 v109, 0, v225
	v_fmac_f32_e32 v0, v34, v108
	v_fmac_f32_e32 v1, v35, v109
	v_max_f32_e32 v210, 0, v226
	v_max_f32_e32 v211, 0, v227
	v_fmac_f32_e32 v0, v36, v210
	v_fmac_f32_e32 v1, v37, v211
	v_add_f32_e32 v0, v0, v1
	v_ashrrev_i32_e32 v1, 31, v0
	v_mfma_f32_32x32x16_bf16 v[6:21], v[98:101], v[196:199], v[6:21]
	s_waitcnt vmcnt(10)
	v_add_u32_e32 v228, 0x10000, v5
	ds_read_b128 v[38:41], v228 offset:10496
	v_add_u32_e32 v228, 0x10000, v52
	ds_read_b128 v[42:45], v228 offset:10496
	v_add_u32_e32 v228, 0x10000, v55
	ds_read_b128 v[46:49], v228 offset:10496
	v_add_u32_e32 v228, 0x10000, v56
	ds_read_b128 v[196:199], v228 offset:10496
	v_or_b32_e32 v1, 0x80000000, v1
	s_cmpk_gt_i32 s11, 264
	s_cselect_b64 vcc, -1, 0
	v_xor_b32_e32 v0, v1, v0
	v_cndmask_b32_e32 v164, v123, v0, vcc
	s_nop 3
	s_waitcnt lgkmcnt(3)
	v_mfma_f32_32x32x16_bf16 v[212:227], v[70:73], v[38:41], 0
	v_max_f32_e32 v108, 0, v6
	v_max_f32_e32 v109, 0, v7
	v_mul_f32_e32 v50, v244, v108
	v_mul_f32_e32 v51, v245, v109
	v_max_f32_e32 v210, 0, v8
	v_max_f32_e32 v211, 0, v9
	v_fmac_f32_e32 v50, v246, v210
	v_fmac_f32_e32 v51, v247, v211
	v_max_f32_e32 v108, 0, v10
	v_max_f32_e32 v109, 0, v11
	v_fmac_f32_e32 v50, v248, v108
	v_fmac_f32_e32 v51, v249, v109
	s_waitcnt lgkmcnt(2)
	v_mfma_f32_32x32x16_bf16 v[212:227], v[74:77], v[42:45], v[212:227]
	v_max_f32_e32 v210, 0, v12
	v_max_f32_e32 v211, 0, v13
	v_fmac_f32_e32 v50, v250, v210
	v_fmac_f32_e32 v51, v251, v211
	v_max_f32_e32 v108, 0, v14
	v_max_f32_e32 v109, 0, v15
	v_fmac_f32_e32 v50, v252, v108
	v_fmac_f32_e32 v51, v253, v109
	v_max_f32_e32 v210, 0, v16
	v_max_f32_e32 v211, 0, v17
	v_fmac_f32_e32 v50, v254, v210
	v_fmac_f32_e32 v51, v255, v211
	s_waitcnt lgkmcnt(1)
	v_mfma_f32_32x32x16_bf16 v[212:227], v[78:81], v[46:49], v[212:227]
	v_max_f32_e32 v108, 0, v18
	v_max_f32_e32 v109, 0, v19
	v_fmac_f32_e32 v50, v200, v108
	v_fmac_f32_e32 v51, v201, v109
	v_max_f32_e32 v210, 0, v20
	v_max_f32_e32 v211, 0, v21
	v_fmac_f32_e32 v50, v202, v210
	v_fmac_f32_e32 v51, v203, v211
	v_add_f32_e32 v50, v50, v51
	v_ashrrev_i32_e32 v51, 31, v50
	s_waitcnt lgkmcnt(0)
	v_mfma_f32_32x32x16_bf16 v[212:227], v[82:85], v[196:199], v[212:227]
	v_or_b32_e32 v51, 0x80000000, v51
	s_cmpk_gt_i32 s11, 264
	s_cselect_b64 vcc, -1, 0
	v_xor_b32_e32 v50, v51, v50
	v_cndmask_b32_e32 v50, v123, v50, vcc
	global_store_dword v243, v50, s[8:9] offset:2048
	s_add_u32 s8, s8, 0x1000
	s_addc_u32 s9, s9, 0
	v_mfma_f32_32x32x16_bf16 v[6:21], v[86:89], v[38:41], 0
	s_add_i32 m0, s10, 32768
	s_nop 0
	global_load_lds_dwordx4 v102, s[6:7]
	s_add_i32 m0, s10, 33792
	s_nop 0
	global_load_lds_dwordx4 v110, s[6:7]
	s_add_i32 m0, s10, 34816
	s_nop 0
	global_load_lds_dwordx4 v112, s[6:7]
	s_add_i32 m0, s10, 35840
	s_nop 0
	global_load_lds_dwordx4 v193, s[6:7]
	s_add_u32 s6, s6, 0x8000
	s_addc_u32 s7, s7, 0
	v_max_f32_e32 v108, 0, v212
	v_max_f32_e32 v109, 0, v213
	v_mul_f32_e32 v0, v22, v108
	v_mul_f32_e32 v1, v23, v109
	v_max_f32_e32 v210, 0, v214
	v_max_f32_e32 v211, 0, v215
	v_fmac_f32_e32 v0, v24, v210
	v_fmac_f32_e32 v1, v25, v211
	v_max_f32_e32 v108, 0, v216
	v_max_f32_e32 v109, 0, v217
	v_fmac_f32_e32 v0, v26, v108
	v_fmac_f32_e32 v1, v27, v109
	v_mfma_f32_32x32x16_bf16 v[6:21], v[90:93], v[42:45], v[6:21]
	v_max_f32_e32 v210, 0, v218
	v_max_f32_e32 v211, 0, v219
	v_fmac_f32_e32 v0, v28, v210
	v_fmac_f32_e32 v1, v29, v211
	v_max_f32_e32 v108, 0, v220
	v_max_f32_e32 v109, 0, v221
	v_fmac_f32_e32 v0, v30, v108
	v_fmac_f32_e32 v1, v31, v109
	v_max_f32_e32 v210, 0, v222
	v_max_f32_e32 v211, 0, v223
	v_fmac_f32_e32 v0, v32, v210
	v_fmac_f32_e32 v1, v33, v211
	v_mfma_f32_32x32x16_bf16 v[6:21], v[94:97], v[46:49], v[6:21]
	v_max_f32_e32 v108, 0, v224
	v_max_f32_e32 v109, 0, v225
	v_fmac_f32_e32 v0, v34, v108
	v_fmac_f32_e32 v1, v35, v109
	v_max_f32_e32 v210, 0, v226
	v_max_f32_e32 v211, 0, v227
	v_fmac_f32_e32 v0, v36, v210
	v_fmac_f32_e32 v1, v37, v211
	v_add_f32_e32 v0, v0, v1
	v_ashrrev_i32_e32 v1, 31, v0
	v_mfma_f32_32x32x16_bf16 v[6:21], v[98:101], v[196:199], v[6:21]
	s_waitcnt vmcnt(10)
	v_add_u32_e32 v228, 0x10000, v5
	ds_read_b128 v[38:41], v228 offset:43264
	v_add_u32_e32 v228, 0x10000, v52
	ds_read_b128 v[42:45], v228 offset:43264
	v_add_u32_e32 v228, 0x10000, v55
	ds_read_b128 v[46:49], v228 offset:43264
	v_add_u32_e32 v228, 0x10000, v56
	ds_read_b128 v[196:199], v228 offset:43264
	v_or_b32_e32 v1, 0x80000000, v1
	s_cmpk_gt_i32 s11, 272
	s_cselect_b64 vcc, -1, 0
	v_xor_b32_e32 v0, v1, v0
	v_cndmask_b32_e32 v167, v123, v0, vcc
	s_nop 3
	s_waitcnt lgkmcnt(3)
	v_mfma_f32_32x32x16_bf16 v[212:227], v[70:73], v[38:41], 0
	v_max_f32_e32 v108, 0, v6
	v_max_f32_e32 v109, 0, v7
	v_mul_f32_e32 v50, v244, v108
	v_mul_f32_e32 v51, v245, v109
	v_max_f32_e32 v210, 0, v8
	v_max_f32_e32 v211, 0, v9
	v_fmac_f32_e32 v50, v246, v210
	v_fmac_f32_e32 v51, v247, v211
	v_max_f32_e32 v108, 0, v10
	v_max_f32_e32 v109, 0, v11
	v_fmac_f32_e32 v50, v248, v108
	v_fmac_f32_e32 v51, v249, v109
	s_waitcnt lgkmcnt(2)
	v_mfma_f32_32x32x16_bf16 v[212:227], v[74:77], v[42:45], v[212:227]
	v_max_f32_e32 v210, 0, v12
	v_max_f32_e32 v211, 0, v13
	v_fmac_f32_e32 v50, v250, v210
	v_fmac_f32_e32 v51, v251, v211
	v_max_f32_e32 v108, 0, v14
	v_max_f32_e32 v109, 0, v15
	v_fmac_f32_e32 v50, v252, v108
	v_fmac_f32_e32 v51, v253, v109
	v_max_f32_e32 v210, 0, v16
	v_max_f32_e32 v211, 0, v17
	v_fmac_f32_e32 v50, v254, v210
	v_fmac_f32_e32 v51, v255, v211
	s_waitcnt lgkmcnt(1)
	v_mfma_f32_32x32x16_bf16 v[212:227], v[78:81], v[46:49], v[212:227]
	v_max_f32_e32 v108, 0, v18
	v_max_f32_e32 v109, 0, v19
	v_fmac_f32_e32 v50, v200, v108
	v_fmac_f32_e32 v51, v201, v109
	v_max_f32_e32 v210, 0, v20
	v_max_f32_e32 v211, 0, v21
	v_fmac_f32_e32 v50, v202, v210
	v_fmac_f32_e32 v51, v203, v211
	v_add_f32_e32 v50, v50, v51
	v_ashrrev_i32_e32 v51, 31, v50
	s_waitcnt lgkmcnt(0)
	v_mfma_f32_32x32x16_bf16 v[212:227], v[82:85], v[196:199], v[212:227]
	v_or_b32_e32 v51, 0x80000000, v51
	s_cmpk_gt_i32 s11, 272
	s_cselect_b64 vcc, -1, 0
	v_xor_b32_e32 v50, v51, v50
	v_cndmask_b32_e32 v50, v123, v50, vcc
	global_store_dword v243, v50, s[8:9]
	v_mfma_f32_32x32x16_bf16 v[6:21], v[86:89], v[38:41], 0
	s_add_i32 m0, s10, 65536
	s_nop 0
	global_load_lds_dwordx4 v102, s[6:7]
	s_add_i32 m0, s10, 66560
	s_nop 0
	global_load_lds_dwordx4 v110, s[6:7]
	s_add_i32 m0, s10, 67584
	s_nop 0
	global_load_lds_dwordx4 v112, s[6:7]
	s_add_i32 m0, s10, 68608
	s_nop 0
	global_load_lds_dwordx4 v193, s[6:7]
	s_add_u32 s6, s6, 0x8000
	s_addc_u32 s7, s7, 0
	v_max_f32_e32 v108, 0, v212
	v_max_f32_e32 v109, 0, v213
	v_mul_f32_e32 v0, v22, v108
	v_mul_f32_e32 v1, v23, v109
	v_max_f32_e32 v210, 0, v214
	v_max_f32_e32 v211, 0, v215
	v_fmac_f32_e32 v0, v24, v210
	v_fmac_f32_e32 v1, v25, v211
	v_max_f32_e32 v108, 0, v216
	v_max_f32_e32 v109, 0, v217
	v_fmac_f32_e32 v0, v26, v108
	v_fmac_f32_e32 v1, v27, v109
	v_mfma_f32_32x32x16_bf16 v[6:21], v[90:93], v[42:45], v[6:21]
	v_max_f32_e32 v210, 0, v218
	v_max_f32_e32 v211, 0, v219
	v_fmac_f32_e32 v0, v28, v210
	v_fmac_f32_e32 v1, v29, v211
	v_max_f32_e32 v108, 0, v220
	v_max_f32_e32 v109, 0, v221
	v_fmac_f32_e32 v0, v30, v108
	v_fmac_f32_e32 v1, v31, v109
	v_max_f32_e32 v210, 0, v222
	v_max_f32_e32 v211, 0, v223
	v_fmac_f32_e32 v0, v32, v210
	v_fmac_f32_e32 v1, v33, v211
	v_mfma_f32_32x32x16_bf16 v[6:21], v[94:97], v[46:49], v[6:21]
	v_max_f32_e32 v108, 0, v224
	v_max_f32_e32 v109, 0, v225
	v_fmac_f32_e32 v0, v34, v108
	v_fmac_f32_e32 v1, v35, v109
	v_max_f32_e32 v210, 0, v226
	v_max_f32_e32 v211, 0, v227
	v_fmac_f32_e32 v0, v36, v210
	v_fmac_f32_e32 v1, v37, v211
	v_add_f32_e32 v0, v0, v1
	v_ashrrev_i32_e32 v1, 31, v0
	v_mfma_f32_32x32x16_bf16 v[6:21], v[98:101], v[196:199], v[6:21]
	s_waitcnt vmcnt(10)
	ds_read_b128 v[38:41], v5 offset:10496
	ds_read_b128 v[42:45], v52 offset:10496
	ds_read_b128 v[46:49], v55 offset:10496
	ds_read_b128 v[196:199], v56 offset:10496
	v_or_b32_e32 v1, 0x80000000, v1
	s_cmpk_gt_i32 s11, 280
	s_cselect_b64 vcc, -1, 0
	v_xor_b32_e32 v0, v1, v0
	v_cndmask_b32_e32 v166, v123, v0, vcc
	s_nop 3
	s_waitcnt lgkmcnt(3)
	v_mfma_f32_32x32x16_bf16 v[212:227], v[70:73], v[38:41], 0
	v_max_f32_e32 v108, 0, v6
	v_max_f32_e32 v109, 0, v7
	v_mul_f32_e32 v50, v244, v108
	v_mul_f32_e32 v51, v245, v109
	v_max_f32_e32 v210, 0, v8
	v_max_f32_e32 v211, 0, v9
	v_fmac_f32_e32 v50, v246, v210
	v_fmac_f32_e32 v51, v247, v211
	v_max_f32_e32 v108, 0, v10
	v_max_f32_e32 v109, 0, v11
	v_fmac_f32_e32 v50, v248, v108
	v_fmac_f32_e32 v51, v249, v109
	s_waitcnt lgkmcnt(2)
	v_mfma_f32_32x32x16_bf16 v[212:227], v[74:77], v[42:45], v[212:227]
	v_max_f32_e32 v210, 0, v12
	v_max_f32_e32 v211, 0, v13
	v_fmac_f32_e32 v50, v250, v210
	v_fmac_f32_e32 v51, v251, v211
	v_max_f32_e32 v108, 0, v14
	v_max_f32_e32 v109, 0, v15
	v_fmac_f32_e32 v50, v252, v108
	v_fmac_f32_e32 v51, v253, v109
	v_max_f32_e32 v210, 0, v16
	v_max_f32_e32 v211, 0, v17
	v_fmac_f32_e32 v50, v254, v210
	v_fmac_f32_e32 v51, v255, v211
	s_waitcnt lgkmcnt(1)
	v_mfma_f32_32x32x16_bf16 v[212:227], v[78:81], v[46:49], v[212:227]
	v_max_f32_e32 v108, 0, v18
	v_max_f32_e32 v109, 0, v19
	v_fmac_f32_e32 v50, v200, v108
	v_fmac_f32_e32 v51, v201, v109
	v_max_f32_e32 v210, 0, v20
	v_max_f32_e32 v211, 0, v21
	v_fmac_f32_e32 v50, v202, v210
	v_fmac_f32_e32 v51, v203, v211
	v_add_f32_e32 v50, v50, v51
	v_ashrrev_i32_e32 v51, 31, v50
	s_waitcnt lgkmcnt(0)
	v_mfma_f32_32x32x16_bf16 v[212:227], v[82:85], v[196:199], v[212:227]
	v_or_b32_e32 v51, 0x80000000, v51
	s_cmpk_gt_i32 s11, 280
	s_cselect_b64 vcc, -1, 0
	v_xor_b32_e32 v50, v51, v50
	v_cndmask_b32_e32 v50, v123, v50, vcc
	global_store_dword v243, v50, s[8:9] offset:2048
	s_add_u32 s8, s8, 0x1000
	s_addc_u32 s9, s9, 0
	v_mfma_f32_32x32x16_bf16 v[6:21], v[86:89], v[38:41], 0
	s_add_i32 m0, s10, 98304
	s_nop 0
	global_load_lds_dwordx4 v102, s[6:7]
	s_add_i32 m0, s10, 99328
	s_nop 0
	global_load_lds_dwordx4 v110, s[6:7]
	s_add_i32 m0, s10, 100352
	s_nop 0
	global_load_lds_dwordx4 v112, s[6:7]
	s_add_i32 m0, s10, 101376
	s_nop 0
	global_load_lds_dwordx4 v193, s[6:7]
	s_add_u32 s6, s6, 0x8000
	s_addc_u32 s7, s7, 0
	v_max_f32_e32 v108, 0, v212
	v_max_f32_e32 v109, 0, v213
	v_mul_f32_e32 v0, v22, v108
	v_mul_f32_e32 v1, v23, v109
	v_max_f32_e32 v210, 0, v214
	v_max_f32_e32 v211, 0, v215
	v_fmac_f32_e32 v0, v24, v210
	v_fmac_f32_e32 v1, v25, v211
	v_max_f32_e32 v108, 0, v216
	v_max_f32_e32 v109, 0, v217
	v_fmac_f32_e32 v0, v26, v108
	v_fmac_f32_e32 v1, v27, v109
	v_mfma_f32_32x32x16_bf16 v[6:21], v[90:93], v[42:45], v[6:21]
	v_max_f32_e32 v210, 0, v218
	v_max_f32_e32 v211, 0, v219
	v_fmac_f32_e32 v0, v28, v210
	v_fmac_f32_e32 v1, v29, v211
	v_max_f32_e32 v108, 0, v220
	v_max_f32_e32 v109, 0, v221
	v_fmac_f32_e32 v0, v30, v108
	v_fmac_f32_e32 v1, v31, v109
	v_max_f32_e32 v210, 0, v222
	v_max_f32_e32 v211, 0, v223
	v_fmac_f32_e32 v0, v32, v210
	v_fmac_f32_e32 v1, v33, v211
	v_mfma_f32_32x32x16_bf16 v[6:21], v[94:97], v[46:49], v[6:21]
	v_max_f32_e32 v108, 0, v224
	v_max_f32_e32 v109, 0, v225
	v_fmac_f32_e32 v0, v34, v108
	v_fmac_f32_e32 v1, v35, v109
	v_max_f32_e32 v210, 0, v226
	v_max_f32_e32 v211, 0, v227
	v_fmac_f32_e32 v0, v36, v210
	v_fmac_f32_e32 v1, v37, v211
	v_add_f32_e32 v0, v0, v1
	v_ashrrev_i32_e32 v1, 31, v0
	v_mfma_f32_32x32x16_bf16 v[6:21], v[98:101], v[196:199], v[6:21]
	s_waitcnt vmcnt(10)
	ds_read_b128 v[38:41], v5 offset:43264
	ds_read_b128 v[42:45], v52 offset:43264
	ds_read_b128 v[46:49], v55 offset:43264
	ds_read_b128 v[196:199], v56 offset:43264
	v_or_b32_e32 v1, 0x80000000, v1
	s_cmpk_gt_i32 s11, 288
	s_cselect_b64 vcc, -1, 0
	v_xor_b32_e32 v0, v1, v0
	v_cndmask_b32_e32 v170, v123, v0, vcc
	s_nop 3
	s_waitcnt lgkmcnt(3)
	v_mfma_f32_32x32x16_bf16 v[212:227], v[70:73], v[38:41], 0
	v_max_f32_e32 v108, 0, v6
	v_max_f32_e32 v109, 0, v7
	v_mul_f32_e32 v50, v244, v108
	v_mul_f32_e32 v51, v245, v109
	v_max_f32_e32 v210, 0, v8
	v_max_f32_e32 v211, 0, v9
	v_fmac_f32_e32 v50, v246, v210
	v_fmac_f32_e32 v51, v247, v211
	v_max_f32_e32 v108, 0, v10
	v_max_f32_e32 v109, 0, v11
	v_fmac_f32_e32 v50, v248, v108
	v_fmac_f32_e32 v51, v249, v109
	s_waitcnt lgkmcnt(2)
	v_mfma_f32_32x32x16_bf16 v[212:227], v[74:77], v[42:45], v[212:227]
	v_max_f32_e32 v210, 0, v12
	v_max_f32_e32 v211, 0, v13
	v_fmac_f32_e32 v50, v250, v210
	v_fmac_f32_e32 v51, v251, v211
	v_max_f32_e32 v108, 0, v14
	v_max_f32_e32 v109, 0, v15
	v_fmac_f32_e32 v50, v252, v108
	v_fmac_f32_e32 v51, v253, v109
	v_max_f32_e32 v210, 0, v16
	v_max_f32_e32 v211, 0, v17
	v_fmac_f32_e32 v50, v254, v210
	v_fmac_f32_e32 v51, v255, v211
	s_waitcnt lgkmcnt(1)
	v_mfma_f32_32x32x16_bf16 v[212:227], v[78:81], v[46:49], v[212:227]
	v_max_f32_e32 v108, 0, v18
	v_max_f32_e32 v109, 0, v19
	v_fmac_f32_e32 v50, v200, v108
	v_fmac_f32_e32 v51, v201, v109
	v_max_f32_e32 v210, 0, v20
	v_max_f32_e32 v211, 0, v21
	v_fmac_f32_e32 v50, v202, v210
	v_fmac_f32_e32 v51, v203, v211
	v_add_f32_e32 v50, v50, v51
	v_ashrrev_i32_e32 v51, 31, v50
	s_waitcnt lgkmcnt(0)
	v_mfma_f32_32x32x16_bf16 v[212:227], v[82:85], v[196:199], v[212:227]
	v_or_b32_e32 v51, 0x80000000, v51
	s_cmpk_gt_i32 s11, 288
	s_cselect_b64 vcc, -1, 0
	v_xor_b32_e32 v50, v51, v50
	v_cndmask_b32_e32 v50, v123, v50, vcc
	global_store_dword v243, v50, s[8:9]
	v_mfma_f32_32x32x16_bf16 v[6:21], v[86:89], v[38:41], 0
	s_add_i32 m0, s10, 0
	s_nop 0
	global_load_lds_dwordx4 v102, s[6:7]
	s_add_i32 m0, s10, 1024
	s_nop 0
	global_load_lds_dwordx4 v110, s[6:7]
	s_add_i32 m0, s10, 2048
	s_nop 0
	global_load_lds_dwordx4 v112, s[6:7]
	s_add_i32 m0, s10, 3072
	s_nop 0
	global_load_lds_dwordx4 v193, s[6:7]
	s_add_u32 s6, s6, 0x8000
	s_addc_u32 s7, s7, 0
	v_max_f32_e32 v108, 0, v212
	v_max_f32_e32 v109, 0, v213
	v_mul_f32_e32 v0, v22, v108
	v_mul_f32_e32 v1, v23, v109
	v_max_f32_e32 v210, 0, v214
	v_max_f32_e32 v211, 0, v215
	v_fmac_f32_e32 v0, v24, v210
	v_fmac_f32_e32 v1, v25, v211
	v_max_f32_e32 v108, 0, v216
	v_max_f32_e32 v109, 0, v217
	v_fmac_f32_e32 v0, v26, v108
	v_fmac_f32_e32 v1, v27, v109
	v_mfma_f32_32x32x16_bf16 v[6:21], v[90:93], v[42:45], v[6:21]
	v_max_f32_e32 v210, 0, v218
	v_max_f32_e32 v211, 0, v219
	v_fmac_f32_e32 v0, v28, v210
	v_fmac_f32_e32 v1, v29, v211
	v_max_f32_e32 v108, 0, v220
	v_max_f32_e32 v109, 0, v221
	v_fmac_f32_e32 v0, v30, v108
	v_fmac_f32_e32 v1, v31, v109
	v_max_f32_e32 v210, 0, v222
	v_max_f32_e32 v211, 0, v223
	v_fmac_f32_e32 v0, v32, v210
	v_fmac_f32_e32 v1, v33, v211
	v_mfma_f32_32x32x16_bf16 v[6:21], v[94:97], v[46:49], v[6:21]
	v_max_f32_e32 v108, 0, v224
	v_max_f32_e32 v109, 0, v225
	v_fmac_f32_e32 v0, v34, v108
	v_fmac_f32_e32 v1, v35, v109
	v_max_f32_e32 v210, 0, v226
	v_max_f32_e32 v211, 0, v227
	v_fmac_f32_e32 v0, v36, v210
	v_fmac_f32_e32 v1, v37, v211
	v_add_f32_e32 v0, v0, v1
	v_ashrrev_i32_e32 v1, 31, v0
	v_mfma_f32_32x32x16_bf16 v[6:21], v[98:101], v[196:199], v[6:21]
	s_waitcnt vmcnt(10)
	v_add_u32_e32 v228, 0x10000, v5
	ds_read_b128 v[38:41], v228 offset:10496
	v_add_u32_e32 v228, 0x10000, v52
	ds_read_b128 v[42:45], v228 offset:10496
	v_add_u32_e32 v228, 0x10000, v55
	ds_read_b128 v[46:49], v228 offset:10496
	v_add_u32_e32 v228, 0x10000, v56
	ds_read_b128 v[196:199], v228 offset:10496
	v_or_b32_e32 v1, 0x80000000, v1
	s_cmpk_gt_i32 s11, 296
	s_cselect_b64 vcc, -1, 0
	v_xor_b32_e32 v0, v1, v0
	v_cndmask_b32_e32 v169, v123, v0, vcc
	s_nop 3
	s_waitcnt lgkmcnt(3)
	v_mfma_f32_32x32x16_bf16 v[212:227], v[70:73], v[38:41], 0
	v_max_f32_e32 v108, 0, v6
	v_max_f32_e32 v109, 0, v7
	v_mul_f32_e32 v50, v244, v108
	v_mul_f32_e32 v51, v245, v109
	v_max_f32_e32 v210, 0, v8
	v_max_f32_e32 v211, 0, v9
	v_fmac_f32_e32 v50, v246, v210
	v_fmac_f32_e32 v51, v247, v211
	v_max_f32_e32 v108, 0, v10
	v_max_f32_e32 v109, 0, v11
	v_fmac_f32_e32 v50, v248, v108
	v_fmac_f32_e32 v51, v249, v109
	s_waitcnt lgkmcnt(2)
	v_mfma_f32_32x32x16_bf16 v[212:227], v[74:77], v[42:45], v[212:227]
	v_max_f32_e32 v210, 0, v12
	v_max_f32_e32 v211, 0, v13
	v_fmac_f32_e32 v50, v250, v210
	v_fmac_f32_e32 v51, v251, v211
	v_max_f32_e32 v108, 0, v14
	v_max_f32_e32 v109, 0, v15
	v_fmac_f32_e32 v50, v252, v108
	v_fmac_f32_e32 v51, v253, v109
	v_max_f32_e32 v210, 0, v16
	v_max_f32_e32 v211, 0, v17
	v_fmac_f32_e32 v50, v254, v210
	v_fmac_f32_e32 v51, v255, v211
	s_waitcnt lgkmcnt(1)
	v_mfma_f32_32x32x16_bf16 v[212:227], v[78:81], v[46:49], v[212:227]
	v_max_f32_e32 v108, 0, v18
	v_max_f32_e32 v109, 0, v19
	v_fmac_f32_e32 v50, v200, v108
	v_fmac_f32_e32 v51, v201, v109
	v_max_f32_e32 v210, 0, v20
	v_max_f32_e32 v211, 0, v21
	v_fmac_f32_e32 v50, v202, v210
	v_fmac_f32_e32 v51, v203, v211
	v_add_f32_e32 v50, v50, v51
	v_ashrrev_i32_e32 v51, 31, v50
	s_waitcnt lgkmcnt(0)
	v_mfma_f32_32x32x16_bf16 v[212:227], v[82:85], v[196:199], v[212:227]
	v_or_b32_e32 v51, 0x80000000, v51
	s_cmpk_gt_i32 s11, 296
	s_cselect_b64 vcc, -1, 0
	v_xor_b32_e32 v50, v51, v50
	v_cndmask_b32_e32 v50, v123, v50, vcc
	global_store_dword v243, v50, s[8:9] offset:2048
	s_add_u32 s8, s8, 0x1000
	s_addc_u32 s9, s9, 0
	v_mfma_f32_32x32x16_bf16 v[6:21], v[86:89], v[38:41], 0
	s_add_i32 m0, s10, 32768
	s_nop 0
	global_load_lds_dwordx4 v102, s[6:7]
	s_add_i32 m0, s10, 33792
	s_nop 0
	global_load_lds_dwordx4 v110, s[6:7]
	s_add_i32 m0, s10, 34816
	s_nop 0
	global_load_lds_dwordx4 v112, s[6:7]
	s_add_i32 m0, s10, 35840
	s_nop 0
	global_load_lds_dwordx4 v193, s[6:7]
	s_add_u32 s6, s6, 0x8000
	s_addc_u32 s7, s7, 0
	v_max_f32_e32 v108, 0, v212
	v_max_f32_e32 v109, 0, v213
	v_mul_f32_e32 v0, v22, v108
	v_mul_f32_e32 v1, v23, v109
	v_max_f32_e32 v210, 0, v214
	v_max_f32_e32 v211, 0, v215
	v_fmac_f32_e32 v0, v24, v210
	v_fmac_f32_e32 v1, v25, v211
	v_max_f32_e32 v108, 0, v216
	v_max_f32_e32 v109, 0, v217
	v_fmac_f32_e32 v0, v26, v108
	v_fmac_f32_e32 v1, v27, v109
	v_mfma_f32_32x32x16_bf16 v[6:21], v[90:93], v[42:45], v[6:21]
	v_max_f32_e32 v210, 0, v218
	v_max_f32_e32 v211, 0, v219
	v_fmac_f32_e32 v0, v28, v210
	v_fmac_f32_e32 v1, v29, v211
	v_max_f32_e32 v108, 0, v220
	v_max_f32_e32 v109, 0, v221
	v_fmac_f32_e32 v0, v30, v108
	v_fmac_f32_e32 v1, v31, v109
	v_max_f32_e32 v210, 0, v222
	v_max_f32_e32 v211, 0, v223
	v_fmac_f32_e32 v0, v32, v210
	v_fmac_f32_e32 v1, v33, v211
	v_mfma_f32_32x32x16_bf16 v[6:21], v[94:97], v[46:49], v[6:21]
	v_max_f32_e32 v108, 0, v224
	v_max_f32_e32 v109, 0, v225
	v_fmac_f32_e32 v0, v34, v108
	v_fmac_f32_e32 v1, v35, v109
	v_max_f32_e32 v210, 0, v226
	v_max_f32_e32 v211, 0, v227
	v_fmac_f32_e32 v0, v36, v210
	v_fmac_f32_e32 v1, v37, v211
	v_add_f32_e32 v0, v0, v1
	v_ashrrev_i32_e32 v1, 31, v0
	v_mfma_f32_32x32x16_bf16 v[6:21], v[98:101], v[196:199], v[6:21]
	s_waitcnt vmcnt(10)
	v_add_u32_e32 v228, 0x10000, v5
	ds_read_b128 v[38:41], v228 offset:43264
	v_add_u32_e32 v228, 0x10000, v52
	ds_read_b128 v[42:45], v228 offset:43264
	v_add_u32_e32 v228, 0x10000, v55
	ds_read_b128 v[46:49], v228 offset:43264
	v_add_u32_e32 v228, 0x10000, v56
	ds_read_b128 v[196:199], v228 offset:43264
	v_or_b32_e32 v1, 0x80000000, v1
	s_cmpk_gt_i32 s11, 304
	s_cselect_b64 vcc, -1, 0
	v_xor_b32_e32 v0, v1, v0
	v_cndmask_b32_e32 v172, v123, v0, vcc
	s_nop 3
	s_waitcnt lgkmcnt(3)
	v_mfma_f32_32x32x16_bf16 v[212:227], v[70:73], v[38:41], 0
	v_max_f32_e32 v108, 0, v6
	v_max_f32_e32 v109, 0, v7
	v_mul_f32_e32 v50, v244, v108
	v_mul_f32_e32 v51, v245, v109
	v_max_f32_e32 v210, 0, v8
	v_max_f32_e32 v211, 0, v9
	v_fmac_f32_e32 v50, v246, v210
	v_fmac_f32_e32 v51, v247, v211
	v_max_f32_e32 v108, 0, v10
	v_max_f32_e32 v109, 0, v11
	v_fmac_f32_e32 v50, v248, v108
	v_fmac_f32_e32 v51, v249, v109
	s_waitcnt lgkmcnt(2)
	v_mfma_f32_32x32x16_bf16 v[212:227], v[74:77], v[42:45], v[212:227]
	v_max_f32_e32 v210, 0, v12
	v_max_f32_e32 v211, 0, v13
	v_fmac_f32_e32 v50, v250, v210
	v_fmac_f32_e32 v51, v251, v211
	v_max_f32_e32 v108, 0, v14
	v_max_f32_e32 v109, 0, v15
	v_fmac_f32_e32 v50, v252, v108
	v_fmac_f32_e32 v51, v253, v109
	v_max_f32_e32 v210, 0, v16
	v_max_f32_e32 v211, 0, v17
	v_fmac_f32_e32 v50, v254, v210
	v_fmac_f32_e32 v51, v255, v211
	s_waitcnt lgkmcnt(1)
	v_mfma_f32_32x32x16_bf16 v[212:227], v[78:81], v[46:49], v[212:227]
	v_max_f32_e32 v108, 0, v18
	v_max_f32_e32 v109, 0, v19
	v_fmac_f32_e32 v50, v200, v108
	v_fmac_f32_e32 v51, v201, v109
	v_max_f32_e32 v210, 0, v20
	v_max_f32_e32 v211, 0, v21
	v_fmac_f32_e32 v50, v202, v210
	v_fmac_f32_e32 v51, v203, v211
	v_add_f32_e32 v50, v50, v51
	v_ashrrev_i32_e32 v51, 31, v50
	s_waitcnt lgkmcnt(0)
	v_mfma_f32_32x32x16_bf16 v[212:227], v[82:85], v[196:199], v[212:227]
	v_or_b32_e32 v51, 0x80000000, v51
	s_cmpk_gt_i32 s11, 304
	s_cselect_b64 vcc, -1, 0
	v_xor_b32_e32 v50, v51, v50
	v_cndmask_b32_e32 v50, v123, v50, vcc
	global_store_dword v243, v50, s[8:9]
	v_mfma_f32_32x32x16_bf16 v[6:21], v[86:89], v[38:41], 0
	s_add_i32 m0, s10, 65536
	s_nop 0
	global_load_lds_dwordx4 v102, s[6:7]
	s_add_i32 m0, s10, 66560
	s_nop 0
	global_load_lds_dwordx4 v110, s[6:7]
	s_add_i32 m0, s10, 67584
	s_nop 0
	global_load_lds_dwordx4 v112, s[6:7]
	s_add_i32 m0, s10, 68608
	s_nop 0
	global_load_lds_dwordx4 v193, s[6:7]
	s_add_u32 s6, s6, 0x8000
	s_addc_u32 s7, s7, 0
	v_max_f32_e32 v108, 0, v212
	v_max_f32_e32 v109, 0, v213
	v_mul_f32_e32 v0, v22, v108
	v_mul_f32_e32 v1, v23, v109
	v_max_f32_e32 v210, 0, v214
	v_max_f32_e32 v211, 0, v215
	v_fmac_f32_e32 v0, v24, v210
	v_fmac_f32_e32 v1, v25, v211
	v_max_f32_e32 v108, 0, v216
	v_max_f32_e32 v109, 0, v217
	v_fmac_f32_e32 v0, v26, v108
	v_fmac_f32_e32 v1, v27, v109
	v_mfma_f32_32x32x16_bf16 v[6:21], v[90:93], v[42:45], v[6:21]
	v_max_f32_e32 v210, 0, v218
	v_max_f32_e32 v211, 0, v219
	v_fmac_f32_e32 v0, v28, v210
	v_fmac_f32_e32 v1, v29, v211
	v_max_f32_e32 v108, 0, v220
	v_max_f32_e32 v109, 0, v221
	v_fmac_f32_e32 v0, v30, v108
	v_fmac_f32_e32 v1, v31, v109
	v_max_f32_e32 v210, 0, v222
	v_max_f32_e32 v211, 0, v223
	v_fmac_f32_e32 v0, v32, v210
	v_fmac_f32_e32 v1, v33, v211
	v_mfma_f32_32x32x16_bf16 v[6:21], v[94:97], v[46:49], v[6:21]
	v_max_f32_e32 v108, 0, v224
	v_max_f32_e32 v109, 0, v225
	v_fmac_f32_e32 v0, v34, v108
	v_fmac_f32_e32 v1, v35, v109
	v_max_f32_e32 v210, 0, v226
	v_max_f32_e32 v211, 0, v227
	v_fmac_f32_e32 v0, v36, v210
	v_fmac_f32_e32 v1, v37, v211
	v_add_f32_e32 v0, v0, v1
	v_ashrrev_i32_e32 v1, 31, v0
	v_mfma_f32_32x32x16_bf16 v[6:21], v[98:101], v[196:199], v[6:21]
	s_waitcnt vmcnt(10)
	ds_read_b128 v[38:41], v5 offset:10496
	ds_read_b128 v[42:45], v52 offset:10496
	ds_read_b128 v[46:49], v55 offset:10496
	ds_read_b128 v[196:199], v56 offset:10496
	v_or_b32_e32 v1, 0x80000000, v1
	s_cmpk_gt_i32 s11, 312
	s_cselect_b64 vcc, -1, 0
	v_xor_b32_e32 v0, v1, v0
	v_cndmask_b32_e32 v171, v123, v0, vcc
	s_nop 3
	v_max_f32_e32 v108, 0, v6
	v_max_f32_e32 v109, 0, v7
	v_mul_f32_e32 v50, v244, v108
	v_mul_f32_e32 v51, v245, v109
	v_max_f32_e32 v210, 0, v8
	v_max_f32_e32 v211, 0, v9
	v_fmac_f32_e32 v50, v246, v210
	v_fmac_f32_e32 v51, v247, v211
	v_max_f32_e32 v108, 0, v10
	v_max_f32_e32 v109, 0, v11
	v_fmac_f32_e32 v50, v248, v108
	v_fmac_f32_e32 v51, v249, v109
	v_max_f32_e32 v210, 0, v12
	v_max_f32_e32 v211, 0, v13
	v_fmac_f32_e32 v50, v250, v210
	v_fmac_f32_e32 v51, v251, v211
	v_max_f32_e32 v108, 0, v14
	v_max_f32_e32 v109, 0, v15
	v_fmac_f32_e32 v50, v252, v108
	v_fmac_f32_e32 v51, v253, v109
	v_max_f32_e32 v210, 0, v16
	v_max_f32_e32 v211, 0, v17
	v_fmac_f32_e32 v50, v254, v210
	v_fmac_f32_e32 v51, v255, v211
	v_max_f32_e32 v108, 0, v18
	v_max_f32_e32 v109, 0, v19
	v_fmac_f32_e32 v50, v200, v108
	v_fmac_f32_e32 v51, v201, v109
	v_max_f32_e32 v210, 0, v20
	v_max_f32_e32 v211, 0, v21
	v_fmac_f32_e32 v50, v202, v210
	v_fmac_f32_e32 v51, v203, v211
	v_add_f32_e32 v50, v50, v51
	v_ashrrev_i32_e32 v51, 31, v50
	v_or_b32_e32 v51, 0x80000000, v51
	s_cmpk_gt_i32 s11, 312
	s_cselect_b64 vcc, -1, 0
	v_xor_b32_e32 v50, v51, v50
	v_cndmask_b32_e32 v50, v123, v50, vcc
	global_store_dword v243, v50, s[8:9] offset:2048
	s_add_u32 s8, s8, 0x1000
	s_addc_u32 s9, s9, 0
	s_cmpk_gt_i32 s81, 40
	s_cbranch_scc0 .Lix_fill_5
	s_waitcnt lgkmcnt(3)
	v_mfma_f32_32x32x16_bf16 v[212:227], v[70:73], v[38:41], 0
	s_add_i32 m0, s10, 98304
	s_nop 0
	global_load_lds_dwordx4 v102, s[6:7]
	s_waitcnt lgkmcnt(2)
	v_mfma_f32_32x32x16_bf16 v[212:227], v[74:77], v[42:45], v[212:227]
	s_add_i32 m0, s10, 99328
	s_nop 0
	global_load_lds_dwordx4 v110, s[6:7]
	s_waitcnt lgkmcnt(1)
	v_mfma_f32_32x32x16_bf16 v[212:227], v[78:81], v[46:49], v[212:227]
	s_add_i32 m0, s10, 100352
	s_nop 0
	global_load_lds_dwordx4 v112, s[6:7]
	s_waitcnt lgkmcnt(0)
	v_mfma_f32_32x32x16_bf16 v[212:227], v[82:85], v[196:199], v[212:227]
	s_add_i32 m0, s10, 101376
	s_nop 0
	global_load_lds_dwordx4 v193, s[6:7]
	s_add_u32 s6, s6, 0x8000
	s_addc_u32 s7, s7, 0
	v_mfma_f32_32x32x16_bf16 v[6:21], v[86:89], v[38:41], 0
	s_nop 7
	s_nop 2
	v_max_f32_e32 v108, 0, v212
	v_max_f32_e32 v109, 0, v213
	v_mul_f32_e32 v0, v22, v108
	v_mul_f32_e32 v1, v23, v109
	v_max_f32_e32 v210, 0, v214
	v_max_f32_e32 v211, 0, v215
	v_fmac_f32_e32 v0, v24, v210
	v_fmac_f32_e32 v1, v25, v211
	v_max_f32_e32 v108, 0, v216
	v_max_f32_e32 v109, 0, v217
	v_fmac_f32_e32 v0, v26, v108
	v_fmac_f32_e32 v1, v27, v109
	v_mfma_f32_32x32x16_bf16 v[6:21], v[90:93], v[42:45], v[6:21]
	v_max_f32_e32 v210, 0, v218
	v_max_f32_e32 v211, 0, v219
	v_fmac_f32_e32 v0, v28, v210
	v_fmac_f32_e32 v1, v29, v211
	v_max_f32_e32 v108, 0, v220
	v_max_f32_e32 v109, 0, v221
	v_fmac_f32_e32 v0, v30, v108
	v_fmac_f32_e32 v1, v31, v109
	v_max_f32_e32 v210, 0, v222
	v_max_f32_e32 v211, 0, v223
	v_fmac_f32_e32 v0, v32, v210
	v_fmac_f32_e32 v1, v33, v211
	v_mfma_f32_32x32x16_bf16 v[6:21], v[94:97], v[46:49], v[6:21]
	v_max_f32_e32 v108, 0, v224
	v_max_f32_e32 v109, 0, v225
	v_fmac_f32_e32 v0, v34, v108
	v_fmac_f32_e32 v1, v35, v109
	v_max_f32_e32 v210, 0, v226
	v_max_f32_e32 v211, 0, v227
	v_fmac_f32_e32 v0, v36, v210
	v_fmac_f32_e32 v1, v37, v211
	v_add_f32_e32 v0, v0, v1
	v_ashrrev_i32_e32 v1, 31, v0
	v_mfma_f32_32x32x16_bf16 v[6:21], v[98:101], v[196:199], v[6:21]
	s_waitcnt vmcnt(10)
	ds_read_b128 v[38:41], v5 offset:43264
	ds_read_b128 v[42:45], v52 offset:43264
	ds_read_b128 v[46:49], v55 offset:43264
	ds_read_b128 v[196:199], v56 offset:43264
	v_or_b32_e32 v1, 0x80000000, v1
	s_cmpk_gt_i32 s11, 320
	s_cselect_b64 vcc, -1, 0
	v_xor_b32_e32 v0, v1, v0
	v_cndmask_b32_e32 v174, v123, v0, vcc
	s_nop 3
	s_waitcnt lgkmcnt(3)
	v_mfma_f32_32x32x16_bf16 v[212:227], v[70:73], v[38:41], 0
	v_max_f32_e32 v108, 0, v6
	v_max_f32_e32 v109, 0, v7
	v_mul_f32_e32 v50, v244, v108
	v_mul_f32_e32 v51, v245, v109
	v_max_f32_e32 v210, 0, v8
	v_max_f32_e32 v211, 0, v9
	v_fmac_f32_e32 v50, v246, v210
	v_fmac_f32_e32 v51, v247, v211
	v_max_f32_e32 v108, 0, v10
	v_max_f32_e32 v109, 0, v11
	v_fmac_f32_e32 v50, v248, v108
	v_fmac_f32_e32 v51, v249, v109
	s_waitcnt lgkmcnt(2)
	v_mfma_f32_32x32x16_bf16 v[212:227], v[74:77], v[42:45], v[212:227]
	v_max_f32_e32 v210, 0, v12
	v_max_f32_e32 v211, 0, v13
	v_fmac_f32_e32 v50, v250, v210
	v_fmac_f32_e32 v51, v251, v211
	v_max_f32_e32 v108, 0, v14
	v_max_f32_e32 v109, 0, v15
	v_fmac_f32_e32 v50, v252, v108
	v_fmac_f32_e32 v51, v253, v109
	v_max_f32_e32 v210, 0, v16
	v_max_f32_e32 v211, 0, v17
	v_fmac_f32_e32 v50, v254, v210
	v_fmac_f32_e32 v51, v255, v211
	s_waitcnt lgkmcnt(1)
	v_mfma_f32_32x32x16_bf16 v[212:227], v[78:81], v[46:49], v[212:227]
	v_max_f32_e32 v108, 0, v18
	v_max_f32_e32 v109, 0, v19
	v_fmac_f32_e32 v50, v200, v108
	v_fmac_f32_e32 v51, v201, v109
	v_max_f32_e32 v210, 0, v20
	v_max_f32_e32 v211, 0, v21
	v_fmac_f32_e32 v50, v202, v210
	v_fmac_f32_e32 v51, v203, v211
	v_add_f32_e32 v50, v50, v51
	v_ashrrev_i32_e32 v51, 31, v50
	s_waitcnt lgkmcnt(0)
	v_mfma_f32_32x32x16_bf16 v[212:227], v[82:85], v[196:199], v[212:227]
	v_or_b32_e32 v51, 0x80000000, v51
	s_cmpk_gt_i32 s11, 320
	s_cselect_b64 vcc, -1, 0
	v_xor_b32_e32 v50, v51, v50
	v_cndmask_b32_e32 v50, v123, v50, vcc
	global_store_dword v243, v50, s[8:9]
	v_mfma_f32_32x32x16_bf16 v[6:21], v[86:89], v[38:41], 0
	s_add_i32 m0, s10, 0
	s_nop 0
	global_load_lds_dwordx4 v102, s[6:7]
	s_add_i32 m0, s10, 1024
	s_nop 0
	global_load_lds_dwordx4 v110, s[6:7]
	s_add_i32 m0, s10, 2048
	s_nop 0
	global_load_lds_dwordx4 v112, s[6:7]
	s_add_i32 m0, s10, 3072
	s_nop 0
	global_load_lds_dwordx4 v193, s[6:7]
	s_add_u32 s6, s6, 0x8000
	s_addc_u32 s7, s7, 0
	v_max_f32_e32 v108, 0, v212
	v_max_f32_e32 v109, 0, v213
	v_mul_f32_e32 v0, v22, v108
	v_mul_f32_e32 v1, v23, v109
	v_max_f32_e32 v210, 0, v214
	v_max_f32_e32 v211, 0, v215
	v_fmac_f32_e32 v0, v24, v210
	v_fmac_f32_e32 v1, v25, v211
	v_max_f32_e32 v108, 0, v216
	v_max_f32_e32 v109, 0, v217
	v_fmac_f32_e32 v0, v26, v108
	v_fmac_f32_e32 v1, v27, v109
	v_mfma_f32_32x32x16_bf16 v[6:21], v[90:93], v[42:45], v[6:21]
	v_max_f32_e32 v210, 0, v218
	v_max_f32_e32 v211, 0, v219
	v_fmac_f32_e32 v0, v28, v210
	v_fmac_f32_e32 v1, v29, v211
	v_max_f32_e32 v108, 0, v220
	v_max_f32_e32 v109, 0, v221
	v_fmac_f32_e32 v0, v30, v108
	v_fmac_f32_e32 v1, v31, v109
	v_max_f32_e32 v210, 0, v222
	v_max_f32_e32 v211, 0, v223
	v_fmac_f32_e32 v0, v32, v210
	v_fmac_f32_e32 v1, v33, v211
	v_mfma_f32_32x32x16_bf16 v[6:21], v[94:97], v[46:49], v[6:21]
	v_max_f32_e32 v108, 0, v224
	v_max_f32_e32 v109, 0, v225
	v_fmac_f32_e32 v0, v34, v108
	v_fmac_f32_e32 v1, v35, v109
	v_max_f32_e32 v210, 0, v226
	v_max_f32_e32 v211, 0, v227
	v_fmac_f32_e32 v0, v36, v210
	v_fmac_f32_e32 v1, v37, v211
	v_add_f32_e32 v0, v0, v1
	v_ashrrev_i32_e32 v1, 31, v0
	v_mfma_f32_32x32x16_bf16 v[6:21], v[98:101], v[196:199], v[6:21]
	s_waitcnt vmcnt(10)
	v_add_u32_e32 v228, 0x10000, v5
	ds_read_b128 v[38:41], v228 offset:10496
	v_add_u32_e32 v228, 0x10000, v52
	ds_read_b128 v[42:45], v228 offset:10496
	v_add_u32_e32 v228, 0x10000, v55
	ds_read_b128 v[46:49], v228 offset:10496
	v_add_u32_e32 v228, 0x10000, v56
	ds_read_b128 v[196:199], v228 offset:10496
	v_or_b32_e32 v1, 0x80000000, v1
	s_cmpk_gt_i32 s11, 328
	s_cselect_b64 vcc, -1, 0
	v_xor_b32_e32 v0, v1, v0
	v_cndmask_b32_e32 v173, v123, v0, vcc
	s_nop 3
	s_waitcnt lgkmcnt(3)
	v_mfma_f32_32x32x16_bf16 v[212:227], v[70:73], v[38:41], 0
	v_max_f32_e32 v108, 0, v6
	v_max_f32_e32 v109, 0, v7
	v_mul_f32_e32 v50, v244, v108
	v_mul_f32_e32 v51, v245, v109
	v_max_f32_e32 v210, 0, v8
	v_max_f32_e32 v211, 0, v9
	v_fmac_f32_e32 v50, v246, v210
	v_fmac_f32_e32 v51, v247, v211
	v_max_f32_e32 v108, 0, v10
	v_max_f32_e32 v109, 0, v11
	v_fmac_f32_e32 v50, v248, v108
	v_fmac_f32_e32 v51, v249, v109
	s_waitcnt lgkmcnt(2)
	v_mfma_f32_32x32x16_bf16 v[212:227], v[74:77], v[42:45], v[212:227]
	v_max_f32_e32 v210, 0, v12
	v_max_f32_e32 v211, 0, v13
	v_fmac_f32_e32 v50, v250, v210
	v_fmac_f32_e32 v51, v251, v211
	v_max_f32_e32 v108, 0, v14
	v_max_f32_e32 v109, 0, v15
	v_fmac_f32_e32 v50, v252, v108
	v_fmac_f32_e32 v51, v253, v109
	v_max_f32_e32 v210, 0, v16
	v_max_f32_e32 v211, 0, v17
	v_fmac_f32_e32 v50, v254, v210
	v_fmac_f32_e32 v51, v255, v211
	s_waitcnt lgkmcnt(1)
	v_mfma_f32_32x32x16_bf16 v[212:227], v[78:81], v[46:49], v[212:227]
	v_max_f32_e32 v108, 0, v18
	v_max_f32_e32 v109, 0, v19
	v_fmac_f32_e32 v50, v200, v108
	v_fmac_f32_e32 v51, v201, v109
	v_max_f32_e32 v210, 0, v20
	v_max_f32_e32 v211, 0, v21
	v_fmac_f32_e32 v50, v202, v210
	v_fmac_f32_e32 v51, v203, v211
	v_add_f32_e32 v50, v50, v51
	v_ashrrev_i32_e32 v51, 31, v50
	s_waitcnt lgkmcnt(0)
	v_mfma_f32_32x32x16_bf16 v[212:227], v[82:85], v[196:199], v[212:227]
	v_or_b32_e32 v51, 0x80000000, v51
	s_cmpk_gt_i32 s11, 328
	s_cselect_b64 vcc, -1, 0
	v_xor_b32_e32 v50, v51, v50
	v_cndmask_b32_e32 v50, v123, v50, vcc
	global_store_dword v243, v50, s[8:9] offset:2048
	s_add_u32 s8, s8, 0x1000
	s_addc_u32 s9, s9, 0
	v_mfma_f32_32x32x16_bf16 v[6:21], v[86:89], v[38:41], 0
	s_add_i32 m0, s10, 32768
	s_nop 0
	global_load_lds_dwordx4 v102, s[6:7]
	s_add_i32 m0, s10, 33792
	s_nop 0
	global_load_lds_dwordx4 v110, s[6:7]
	s_add_i32 m0, s10, 34816
	s_nop 0
	global_load_lds_dwordx4 v112, s[6:7]
	s_add_i32 m0, s10, 35840
	s_nop 0
	global_load_lds_dwordx4 v193, s[6:7]
	s_add_u32 s6, s6, 0x8000
	s_addc_u32 s7, s7, 0
	v_max_f32_e32 v108, 0, v212
	v_max_f32_e32 v109, 0, v213
	v_mul_f32_e32 v0, v22, v108
	v_mul_f32_e32 v1, v23, v109
	v_max_f32_e32 v210, 0, v214
	v_max_f32_e32 v211, 0, v215
	v_fmac_f32_e32 v0, v24, v210
	v_fmac_f32_e32 v1, v25, v211
	v_max_f32_e32 v108, 0, v216
	v_max_f32_e32 v109, 0, v217
	v_fmac_f32_e32 v0, v26, v108
	v_fmac_f32_e32 v1, v27, v109
	v_mfma_f32_32x32x16_bf16 v[6:21], v[90:93], v[42:45], v[6:21]
	v_max_f32_e32 v210, 0, v218
	v_max_f32_e32 v211, 0, v219
	v_fmac_f32_e32 v0, v28, v210
	v_fmac_f32_e32 v1, v29, v211
	v_max_f32_e32 v108, 0, v220
	v_max_f32_e32 v109, 0, v221
	v_fmac_f32_e32 v0, v30, v108
	v_fmac_f32_e32 v1, v31, v109
	v_max_f32_e32 v210, 0, v222
	v_max_f32_e32 v211, 0, v223
	v_fmac_f32_e32 v0, v32, v210
	v_fmac_f32_e32 v1, v33, v211
	v_mfma_f32_32x32x16_bf16 v[6:21], v[94:97], v[46:49], v[6:21]
	v_max_f32_e32 v108, 0, v224
	v_max_f32_e32 v109, 0, v225
	v_fmac_f32_e32 v0, v34, v108
	v_fmac_f32_e32 v1, v35, v109
	v_max_f32_e32 v210, 0, v226
	v_max_f32_e32 v211, 0, v227
	v_fmac_f32_e32 v0, v36, v210
	v_fmac_f32_e32 v1, v37, v211
	v_add_f32_e32 v0, v0, v1
	v_ashrrev_i32_e32 v1, 31, v0
	v_mfma_f32_32x32x16_bf16 v[6:21], v[98:101], v[196:199], v[6:21]
	s_waitcnt vmcnt(10)
	v_add_u32_e32 v228, 0x10000, v5
	ds_read_b128 v[38:41], v228 offset:43264
	v_add_u32_e32 v228, 0x10000, v52
	ds_read_b128 v[42:45], v228 offset:43264
	v_add_u32_e32 v228, 0x10000, v55
	ds_read_b128 v[46:49], v228 offset:43264
	v_add_u32_e32 v228, 0x10000, v56
	ds_read_b128 v[196:199], v228 offset:43264
	v_or_b32_e32 v1, 0x80000000, v1
	s_cmpk_gt_i32 s11, 336
	s_cselect_b64 vcc, -1, 0
	v_xor_b32_e32 v0, v1, v0
	v_cndmask_b32_e32 v176, v123, v0, vcc
	s_nop 3
	s_waitcnt lgkmcnt(3)
	v_mfma_f32_32x32x16_bf16 v[212:227], v[70:73], v[38:41], 0
	v_max_f32_e32 v108, 0, v6
	v_max_f32_e32 v109, 0, v7
	v_mul_f32_e32 v50, v244, v108
	v_mul_f32_e32 v51, v245, v109
	v_max_f32_e32 v210, 0, v8
	v_max_f32_e32 v211, 0, v9
	v_fmac_f32_e32 v50, v246, v210
	v_fmac_f32_e32 v51, v247, v211
	v_max_f32_e32 v108, 0, v10
	v_max_f32_e32 v109, 0, v11
	v_fmac_f32_e32 v50, v248, v108
	v_fmac_f32_e32 v51, v249, v109
	s_waitcnt lgkmcnt(2)
	v_mfma_f32_32x32x16_bf16 v[212:227], v[74:77], v[42:45], v[212:227]
	v_max_f32_e32 v210, 0, v12
	v_max_f32_e32 v211, 0, v13
	v_fmac_f32_e32 v50, v250, v210
	v_fmac_f32_e32 v51, v251, v211
	v_max_f32_e32 v108, 0, v14
	v_max_f32_e32 v109, 0, v15
	v_fmac_f32_e32 v50, v252, v108
	v_fmac_f32_e32 v51, v253, v109
	v_max_f32_e32 v210, 0, v16
	v_max_f32_e32 v211, 0, v17
	v_fmac_f32_e32 v50, v254, v210
	v_fmac_f32_e32 v51, v255, v211
	s_waitcnt lgkmcnt(1)
	v_mfma_f32_32x32x16_bf16 v[212:227], v[78:81], v[46:49], v[212:227]
	v_max_f32_e32 v108, 0, v18
	v_max_f32_e32 v109, 0, v19
	v_fmac_f32_e32 v50, v200, v108
	v_fmac_f32_e32 v51, v201, v109
	v_max_f32_e32 v210, 0, v20
	v_max_f32_e32 v211, 0, v21
	v_fmac_f32_e32 v50, v202, v210
	v_fmac_f32_e32 v51, v203, v211
	v_add_f32_e32 v50, v50, v51
	v_ashrrev_i32_e32 v51, 31, v50
	s_waitcnt lgkmcnt(0)
	v_mfma_f32_32x32x16_bf16 v[212:227], v[82:85], v[196:199], v[212:227]
	v_or_b32_e32 v51, 0x80000000, v51
	s_cmpk_gt_i32 s11, 336
	s_cselect_b64 vcc, -1, 0
	v_xor_b32_e32 v50, v51, v50
	v_cndmask_b32_e32 v50, v123, v50, vcc
	global_store_dword v243, v50, s[8:9]
	v_mfma_f32_32x32x16_bf16 v[6:21], v[86:89], v[38:41], 0
	s_add_i32 m0, s10, 65536
	s_nop 0
	global_load_lds_dwordx4 v102, s[6:7]
	s_add_i32 m0, s10, 66560
	s_nop 0
	global_load_lds_dwordx4 v110, s[6:7]
	s_add_i32 m0, s10, 67584
	s_nop 0
	global_load_lds_dwordx4 v112, s[6:7]
	s_add_i32 m0, s10, 68608
	s_nop 0
	global_load_lds_dwordx4 v193, s[6:7]
	s_add_u32 s6, s6, 0x8000
	s_addc_u32 s7, s7, 0
	v_max_f32_e32 v108, 0, v212
	v_max_f32_e32 v109, 0, v213
	v_mul_f32_e32 v0, v22, v108
	v_mul_f32_e32 v1, v23, v109
	v_max_f32_e32 v210, 0, v214
	v_max_f32_e32 v211, 0, v215
	v_fmac_f32_e32 v0, v24, v210
	v_fmac_f32_e32 v1, v25, v211
	v_max_f32_e32 v108, 0, v216
	v_max_f32_e32 v109, 0, v217
	v_fmac_f32_e32 v0, v26, v108
	v_fmac_f32_e32 v1, v27, v109
	v_mfma_f32_32x32x16_bf16 v[6:21], v[90:93], v[42:45], v[6:21]
	v_max_f32_e32 v210, 0, v218
	v_max_f32_e32 v211, 0, v219
	v_fmac_f32_e32 v0, v28, v210
	v_fmac_f32_e32 v1, v29, v211
	v_max_f32_e32 v108, 0, v220
	v_max_f32_e32 v109, 0, v221
	v_fmac_f32_e32 v0, v30, v108
	v_fmac_f32_e32 v1, v31, v109
	v_max_f32_e32 v210, 0, v222
	v_max_f32_e32 v211, 0, v223
	v_fmac_f32_e32 v0, v32, v210
	v_fmac_f32_e32 v1, v33, v211
	v_mfma_f32_32x32x16_bf16 v[6:21], v[94:97], v[46:49], v[6:21]
	v_max_f32_e32 v108, 0, v224
	v_max_f32_e32 v109, 0, v225
	v_fmac_f32_e32 v0, v34, v108
	v_fmac_f32_e32 v1, v35, v109
	v_max_f32_e32 v210, 0, v226
	v_max_f32_e32 v211, 0, v227
	v_fmac_f32_e32 v0, v36, v210
	v_fmac_f32_e32 v1, v37, v211
	v_add_f32_e32 v0, v0, v1
	v_ashrrev_i32_e32 v1, 31, v0
	v_mfma_f32_32x32x16_bf16 v[6:21], v[98:101], v[196:199], v[6:21]
	s_waitcnt vmcnt(10)
	ds_read_b128 v[38:41], v5 offset:10496
	ds_read_b128 v[42:45], v52 offset:10496
	ds_read_b128 v[46:49], v55 offset:10496
	ds_read_b128 v[196:199], v56 offset:10496
	v_or_b32_e32 v1, 0x80000000, v1
	s_cmpk_gt_i32 s11, 344
	s_cselect_b64 vcc, -1, 0
	v_xor_b32_e32 v0, v1, v0
	v_cndmask_b32_e32 v175, v123, v0, vcc
	s_nop 3
	s_waitcnt lgkmcnt(3)
	v_mfma_f32_32x32x16_bf16 v[212:227], v[70:73], v[38:41], 0
	v_max_f32_e32 v108, 0, v6
	v_max_f32_e32 v109, 0, v7
	v_mul_f32_e32 v50, v244, v108
	v_mul_f32_e32 v51, v245, v109
	v_max_f32_e32 v210, 0, v8
	v_max_f32_e32 v211, 0, v9
	v_fmac_f32_e32 v50, v246, v210
	v_fmac_f32_e32 v51, v247, v211
	v_max_f32_e32 v108, 0, v10
	v_max_f32_e32 v109, 0, v11
	v_fmac_f32_e32 v50, v248, v108
	v_fmac_f32_e32 v51, v249, v109
	s_waitcnt lgkmcnt(2)
	v_mfma_f32_32x32x16_bf16 v[212:227], v[74:77], v[42:45], v[212:227]
	v_max_f32_e32 v210, 0, v12
	v_max_f32_e32 v211, 0, v13
	v_fmac_f32_e32 v50, v250, v210
	v_fmac_f32_e32 v51, v251, v211
	v_max_f32_e32 v108, 0, v14
	v_max_f32_e32 v109, 0, v15
	v_fmac_f32_e32 v50, v252, v108
	v_fmac_f32_e32 v51, v253, v109
	v_max_f32_e32 v210, 0, v16
	v_max_f32_e32 v211, 0, v17
	v_fmac_f32_e32 v50, v254, v210
	v_fmac_f32_e32 v51, v255, v211
	s_waitcnt lgkmcnt(1)
	v_mfma_f32_32x32x16_bf16 v[212:227], v[78:81], v[46:49], v[212:227]
	v_max_f32_e32 v108, 0, v18
	v_max_f32_e32 v109, 0, v19
	v_fmac_f32_e32 v50, v200, v108
	v_fmac_f32_e32 v51, v201, v109
	v_max_f32_e32 v210, 0, v20
	v_max_f32_e32 v211, 0, v21
	v_fmac_f32_e32 v50, v202, v210
	v_fmac_f32_e32 v51, v203, v211
	v_add_f32_e32 v50, v50, v51
	v_ashrrev_i32_e32 v51, 31, v50
	s_waitcnt lgkmcnt(0)
	v_mfma_f32_32x32x16_bf16 v[212:227], v[82:85], v[196:199], v[212:227]
	v_or_b32_e32 v51, 0x80000000, v51
	s_cmpk_gt_i32 s11, 344
	s_cselect_b64 vcc, -1, 0
	v_xor_b32_e32 v50, v51, v50
	v_cndmask_b32_e32 v50, v123, v50, vcc
	global_store_dword v243, v50, s[8:9] offset:2048
	s_add_u32 s8, s8, 0x1000
	s_addc_u32 s9, s9, 0
	v_mfma_f32_32x32x16_bf16 v[6:21], v[86:89], v[38:41], 0
	s_add_i32 m0, s10, 98304
	s_nop 0
	global_load_lds_dwordx4 v102, s[6:7]
	s_add_i32 m0, s10, 99328
	s_nop 0
	global_load_lds_dwordx4 v110, s[6:7]
	s_add_i32 m0, s10, 100352
	s_nop 0
	global_load_lds_dwordx4 v112, s[6:7]
	s_add_i32 m0, s10, 101376
	s_nop 0
	global_load_lds_dwordx4 v193, s[6:7]
	s_add_u32 s6, s6, 0x8000
	s_addc_u32 s7, s7, 0
	v_max_f32_e32 v108, 0, v212
	v_max_f32_e32 v109, 0, v213
	v_mul_f32_e32 v0, v22, v108
	v_mul_f32_e32 v1, v23, v109
	v_max_f32_e32 v210, 0, v214
	v_max_f32_e32 v211, 0, v215
	v_fmac_f32_e32 v0, v24, v210
	v_fmac_f32_e32 v1, v25, v211
	v_max_f32_e32 v108, 0, v216
	v_max_f32_e32 v109, 0, v217
	v_fmac_f32_e32 v0, v26, v108
	v_fmac_f32_e32 v1, v27, v109
	v_mfma_f32_32x32x16_bf16 v[6:21], v[90:93], v[42:45], v[6:21]
	v_max_f32_e32 v210, 0, v218
	v_max_f32_e32 v211, 0, v219
	v_fmac_f32_e32 v0, v28, v210
	v_fmac_f32_e32 v1, v29, v211
	v_max_f32_e32 v108, 0, v220
	v_max_f32_e32 v109, 0, v221
	v_fmac_f32_e32 v0, v30, v108
	v_fmac_f32_e32 v1, v31, v109
	v_max_f32_e32 v210, 0, v222
	v_max_f32_e32 v211, 0, v223
	v_fmac_f32_e32 v0, v32, v210
	v_fmac_f32_e32 v1, v33, v211
	v_mfma_f32_32x32x16_bf16 v[6:21], v[94:97], v[46:49], v[6:21]
	v_max_f32_e32 v108, 0, v224
	v_max_f32_e32 v109, 0, v225
	v_fmac_f32_e32 v0, v34, v108
	v_fmac_f32_e32 v1, v35, v109
	v_max_f32_e32 v210, 0, v226
	v_max_f32_e32 v211, 0, v227
	v_fmac_f32_e32 v0, v36, v210
	v_fmac_f32_e32 v1, v37, v211
	v_add_f32_e32 v0, v0, v1
	v_ashrrev_i32_e32 v1, 31, v0
	v_mfma_f32_32x32x16_bf16 v[6:21], v[98:101], v[196:199], v[6:21]
	s_waitcnt vmcnt(10)
	ds_read_b128 v[38:41], v5 offset:43264
	ds_read_b128 v[42:45], v52 offset:43264
	ds_read_b128 v[46:49], v55 offset:43264
	ds_read_b128 v[196:199], v56 offset:43264
	v_or_b32_e32 v1, 0x80000000, v1
	s_cmpk_gt_i32 s11, 352
	s_cselect_b64 vcc, -1, 0
	v_xor_b32_e32 v0, v1, v0
	v_cndmask_b32_e32 v178, v123, v0, vcc
	s_nop 3
	s_waitcnt lgkmcnt(3)
	v_mfma_f32_32x32x16_bf16 v[212:227], v[70:73], v[38:41], 0
	v_max_f32_e32 v108, 0, v6
	v_max_f32_e32 v109, 0, v7
	v_mul_f32_e32 v50, v244, v108
	v_mul_f32_e32 v51, v245, v109
	v_max_f32_e32 v210, 0, v8
	v_max_f32_e32 v211, 0, v9
	v_fmac_f32_e32 v50, v246, v210
	v_fmac_f32_e32 v51, v247, v211
	v_max_f32_e32 v108, 0, v10
	v_max_f32_e32 v109, 0, v11
	v_fmac_f32_e32 v50, v248, v108
	v_fmac_f32_e32 v51, v249, v109
	s_waitcnt lgkmcnt(2)
	v_mfma_f32_32x32x16_bf16 v[212:227], v[74:77], v[42:45], v[212:227]
	v_max_f32_e32 v210, 0, v12
	v_max_f32_e32 v211, 0, v13
	v_fmac_f32_e32 v50, v250, v210
	v_fmac_f32_e32 v51, v251, v211
	v_max_f32_e32 v108, 0, v14
	v_max_f32_e32 v109, 0, v15
	v_fmac_f32_e32 v50, v252, v108
	v_fmac_f32_e32 v51, v253, v109
	v_max_f32_e32 v210, 0, v16
	v_max_f32_e32 v211, 0, v17
	v_fmac_f32_e32 v50, v254, v210
	v_fmac_f32_e32 v51, v255, v211
	s_waitcnt lgkmcnt(1)
	v_mfma_f32_32x32x16_bf16 v[212:227], v[78:81], v[46:49], v[212:227]
	v_max_f32_e32 v108, 0, v18
	v_max_f32_e32 v109, 0, v19
	v_fmac_f32_e32 v50, v200, v108
	v_fmac_f32_e32 v51, v201, v109
	v_max_f32_e32 v210, 0, v20
	v_max_f32_e32 v211, 0, v21
	v_fmac_f32_e32 v50, v202, v210
	v_fmac_f32_e32 v51, v203, v211
	v_add_f32_e32 v50, v50, v51
	v_ashrrev_i32_e32 v51, 31, v50
	s_waitcnt lgkmcnt(0)
	v_mfma_f32_32x32x16_bf16 v[212:227], v[82:85], v[196:199], v[212:227]
	v_or_b32_e32 v51, 0x80000000, v51
	s_cmpk_gt_i32 s11, 352
	s_cselect_b64 vcc, -1, 0
	v_xor_b32_e32 v50, v51, v50
	v_cndmask_b32_e32 v50, v123, v50, vcc
	global_store_dword v243, v50, s[8:9]
	v_mfma_f32_32x32x16_bf16 v[6:21], v[86:89], v[38:41], 0
	s_add_i32 m0, s10, 0
	s_nop 0
	global_load_lds_dwordx4 v102, s[6:7]
	s_add_i32 m0, s10, 1024
	s_nop 0
	global_load_lds_dwordx4 v110, s[6:7]
	s_add_i32 m0, s10, 2048
	s_nop 0
	global_load_lds_dwordx4 v112, s[6:7]
	s_add_i32 m0, s10, 3072
	s_nop 0
	global_load_lds_dwordx4 v193, s[6:7]
	s_add_u32 s6, s6, 0x8000
	s_addc_u32 s7, s7, 0
	v_max_f32_e32 v108, 0, v212
	v_max_f32_e32 v109, 0, v213
	v_mul_f32_e32 v0, v22, v108
	v_mul_f32_e32 v1, v23, v109
	v_max_f32_e32 v210, 0, v214
	v_max_f32_e32 v211, 0, v215
	v_fmac_f32_e32 v0, v24, v210
	v_fmac_f32_e32 v1, v25, v211
	v_max_f32_e32 v108, 0, v216
	v_max_f32_e32 v109, 0, v217
	v_fmac_f32_e32 v0, v26, v108
	v_fmac_f32_e32 v1, v27, v109
	v_mfma_f32_32x32x16_bf16 v[6:21], v[90:93], v[42:45], v[6:21]
	v_max_f32_e32 v210, 0, v218
	v_max_f32_e32 v211, 0, v219
	v_fmac_f32_e32 v0, v28, v210
	v_fmac_f32_e32 v1, v29, v211
	v_max_f32_e32 v108, 0, v220
	v_max_f32_e32 v109, 0, v221
	v_fmac_f32_e32 v0, v30, v108
	v_fmac_f32_e32 v1, v31, v109
	v_max_f32_e32 v210, 0, v222
	v_max_f32_e32 v211, 0, v223
	v_fmac_f32_e32 v0, v32, v210
	v_fmac_f32_e32 v1, v33, v211
	v_mfma_f32_32x32x16_bf16 v[6:21], v[94:97], v[46:49], v[6:21]
	v_max_f32_e32 v108, 0, v224
	v_max_f32_e32 v109, 0, v225
	v_fmac_f32_e32 v0, v34, v108
	v_fmac_f32_e32 v1, v35, v109
	v_max_f32_e32 v210, 0, v226
	v_max_f32_e32 v211, 0, v227
	v_fmac_f32_e32 v0, v36, v210
	v_fmac_f32_e32 v1, v37, v211
	v_add_f32_e32 v0, v0, v1
	v_ashrrev_i32_e32 v1, 31, v0
	v_mfma_f32_32x32x16_bf16 v[6:21], v[98:101], v[196:199], v[6:21]
	s_waitcnt vmcnt(10)
	v_add_u32_e32 v228, 0x10000, v5
	ds_read_b128 v[38:41], v228 offset:10496
	v_add_u32_e32 v228, 0x10000, v52
	ds_read_b128 v[42:45], v228 offset:10496
	v_add_u32_e32 v228, 0x10000, v55
	ds_read_b128 v[46:49], v228 offset:10496
	v_add_u32_e32 v228, 0x10000, v56
	ds_read_b128 v[196:199], v228 offset:10496
	v_or_b32_e32 v1, 0x80000000, v1
	s_cmpk_gt_i32 s11, 360
	s_cselect_b64 vcc, -1, 0
	v_xor_b32_e32 v0, v1, v0
	v_cndmask_b32_e32 v177, v123, v0, vcc
	s_nop 3
	s_waitcnt lgkmcnt(3)
	v_mfma_f32_32x32x16_bf16 v[212:227], v[70:73], v[38:41], 0
	v_max_f32_e32 v108, 0, v6
	v_max_f32_e32 v109, 0, v7
	v_mul_f32_e32 v50, v244, v108
	v_mul_f32_e32 v51, v245, v109
	v_max_f32_e32 v210, 0, v8
	v_max_f32_e32 v211, 0, v9
	v_fmac_f32_e32 v50, v246, v210
	v_fmac_f32_e32 v51, v247, v211
	v_max_f32_e32 v108, 0, v10
	v_max_f32_e32 v109, 0, v11
	v_fmac_f32_e32 v50, v248, v108
	v_fmac_f32_e32 v51, v249, v109
	s_waitcnt lgkmcnt(2)
	v_mfma_f32_32x32x16_bf16 v[212:227], v[74:77], v[42:45], v[212:227]
	v_max_f32_e32 v210, 0, v12
	v_max_f32_e32 v211, 0, v13
	v_fmac_f32_e32 v50, v250, v210
	v_fmac_f32_e32 v51, v251, v211
	v_max_f32_e32 v108, 0, v14
	v_max_f32_e32 v109, 0, v15
	v_fmac_f32_e32 v50, v252, v108
	v_fmac_f32_e32 v51, v253, v109
	v_max_f32_e32 v210, 0, v16
	v_max_f32_e32 v211, 0, v17
	v_fmac_f32_e32 v50, v254, v210
	v_fmac_f32_e32 v51, v255, v211
	s_waitcnt lgkmcnt(1)
	v_mfma_f32_32x32x16_bf16 v[212:227], v[78:81], v[46:49], v[212:227]
	v_max_f32_e32 v108, 0, v18
	v_max_f32_e32 v109, 0, v19
	v_fmac_f32_e32 v50, v200, v108
	v_fmac_f32_e32 v51, v201, v109
	v_max_f32_e32 v210, 0, v20
	v_max_f32_e32 v211, 0, v21
	v_fmac_f32_e32 v50, v202, v210
	v_fmac_f32_e32 v51, v203, v211
	v_add_f32_e32 v50, v50, v51
	v_ashrrev_i32_e32 v51, 31, v50
	s_waitcnt lgkmcnt(0)
	v_mfma_f32_32x32x16_bf16 v[212:227], v[82:85], v[196:199], v[212:227]
	v_or_b32_e32 v51, 0x80000000, v51
	s_cmpk_gt_i32 s11, 360
	s_cselect_b64 vcc, -1, 0
	v_xor_b32_e32 v50, v51, v50
	v_cndmask_b32_e32 v50, v123, v50, vcc
	global_store_dword v243, v50, s[8:9] offset:2048
	s_add_u32 s8, s8, 0x1000
	s_addc_u32 s9, s9, 0
	v_mfma_f32_32x32x16_bf16 v[6:21], v[86:89], v[38:41], 0
	s_add_i32 m0, s10, 32768
	s_nop 0
	global_load_lds_dwordx4 v102, s[6:7]
	s_add_i32 m0, s10, 33792
	s_nop 0
	global_load_lds_dwordx4 v110, s[6:7]
	s_add_i32 m0, s10, 34816
	s_nop 0
	global_load_lds_dwordx4 v112, s[6:7]
	s_add_i32 m0, s10, 35840
	s_nop 0
	global_load_lds_dwordx4 v193, s[6:7]
	s_add_u32 s6, s6, 0x8000
	s_addc_u32 s7, s7, 0
	v_max_f32_e32 v108, 0, v212
	v_max_f32_e32 v109, 0, v213
	v_mul_f32_e32 v0, v22, v108
	v_mul_f32_e32 v1, v23, v109
	v_max_f32_e32 v210, 0, v214
	v_max_f32_e32 v211, 0, v215
	v_fmac_f32_e32 v0, v24, v210
	v_fmac_f32_e32 v1, v25, v211
	v_max_f32_e32 v108, 0, v216
	v_max_f32_e32 v109, 0, v217
	v_fmac_f32_e32 v0, v26, v108
	v_fmac_f32_e32 v1, v27, v109
	v_mfma_f32_32x32x16_bf16 v[6:21], v[90:93], v[42:45], v[6:21]
	v_max_f32_e32 v210, 0, v218
	v_max_f32_e32 v211, 0, v219
	v_fmac_f32_e32 v0, v28, v210
	v_fmac_f32_e32 v1, v29, v211
	v_max_f32_e32 v108, 0, v220
	v_max_f32_e32 v109, 0, v221
	v_fmac_f32_e32 v0, v30, v108
	v_fmac_f32_e32 v1, v31, v109
	v_max_f32_e32 v210, 0, v222
	v_max_f32_e32 v211, 0, v223
	v_fmac_f32_e32 v0, v32, v210
	v_fmac_f32_e32 v1, v33, v211
	v_mfma_f32_32x32x16_bf16 v[6:21], v[94:97], v[46:49], v[6:21]
	v_max_f32_e32 v108, 0, v224
	v_max_f32_e32 v109, 0, v225
	v_fmac_f32_e32 v0, v34, v108
	v_fmac_f32_e32 v1, v35, v109
	v_max_f32_e32 v210, 0, v226
	v_max_f32_e32 v211, 0, v227
	v_fmac_f32_e32 v0, v36, v210
	v_fmac_f32_e32 v1, v37, v211
	v_add_f32_e32 v0, v0, v1
	v_ashrrev_i32_e32 v1, 31, v0
	v_mfma_f32_32x32x16_bf16 v[6:21], v[98:101], v[196:199], v[6:21]
	s_waitcnt vmcnt(10)
	v_add_u32_e32 v228, 0x10000, v5
	ds_read_b128 v[38:41], v228 offset:43264
	v_add_u32_e32 v228, 0x10000, v52
	ds_read_b128 v[42:45], v228 offset:43264
	v_add_u32_e32 v228, 0x10000, v55
	ds_read_b128 v[46:49], v228 offset:43264
	v_add_u32_e32 v228, 0x10000, v56
	ds_read_b128 v[196:199], v228 offset:43264
	v_or_b32_e32 v1, 0x80000000, v1
	s_cmpk_gt_i32 s11, 368
	s_cselect_b64 vcc, -1, 0
	v_xor_b32_e32 v0, v1, v0
	v_cndmask_b32_e32 v179, v123, v0, vcc
	s_nop 3
	s_waitcnt lgkmcnt(3)
	v_mfma_f32_32x32x16_bf16 v[212:227], v[70:73], v[38:41], 0
	v_max_f32_e32 v108, 0, v6
	v_max_f32_e32 v109, 0, v7
	v_mul_f32_e32 v50, v244, v108
	v_mul_f32_e32 v51, v245, v109
	v_max_f32_e32 v210, 0, v8
	v_max_f32_e32 v211, 0, v9
	v_fmac_f32_e32 v50, v246, v210
	v_fmac_f32_e32 v51, v247, v211
	v_max_f32_e32 v108, 0, v10
	v_max_f32_e32 v109, 0, v11
	v_fmac_f32_e32 v50, v248, v108
	v_fmac_f32_e32 v51, v249, v109
	s_waitcnt lgkmcnt(2)
	v_mfma_f32_32x32x16_bf16 v[212:227], v[74:77], v[42:45], v[212:227]
	v_max_f32_e32 v210, 0, v12
	v_max_f32_e32 v211, 0, v13
	v_fmac_f32_e32 v50, v250, v210
	v_fmac_f32_e32 v51, v251, v211
	v_max_f32_e32 v108, 0, v14
	v_max_f32_e32 v109, 0, v15
	v_fmac_f32_e32 v50, v252, v108
	v_fmac_f32_e32 v51, v253, v109
	v_max_f32_e32 v210, 0, v16
	v_max_f32_e32 v211, 0, v17
	v_fmac_f32_e32 v50, v254, v210
	v_fmac_f32_e32 v51, v255, v211
	s_waitcnt lgkmcnt(1)
	v_mfma_f32_32x32x16_bf16 v[212:227], v[78:81], v[46:49], v[212:227]
	v_max_f32_e32 v108, 0, v18
	v_max_f32_e32 v109, 0, v19
	v_fmac_f32_e32 v50, v200, v108
	v_fmac_f32_e32 v51, v201, v109
	v_max_f32_e32 v210, 0, v20
	v_max_f32_e32 v211, 0, v21
	v_fmac_f32_e32 v50, v202, v210
	v_fmac_f32_e32 v51, v203, v211
	v_add_f32_e32 v50, v50, v51
	v_ashrrev_i32_e32 v51, 31, v50
	s_waitcnt lgkmcnt(0)
	v_mfma_f32_32x32x16_bf16 v[212:227], v[82:85], v[196:199], v[212:227]
	v_or_b32_e32 v51, 0x80000000, v51
	s_cmpk_gt_i32 s11, 368
	s_cselect_b64 vcc, -1, 0
	v_xor_b32_e32 v50, v51, v50
	v_cndmask_b32_e32 v50, v123, v50, vcc
	global_store_dword v243, v50, s[8:9]
	v_mfma_f32_32x32x16_bf16 v[6:21], v[86:89], v[38:41], 0
	s_add_i32 m0, s10, 65536
	s_nop 0
	global_load_lds_dwordx4 v102, s[6:7]
	s_add_i32 m0, s10, 66560
	s_nop 0
	global_load_lds_dwordx4 v110, s[6:7]
	s_add_i32 m0, s10, 67584
	s_nop 0
	global_load_lds_dwordx4 v112, s[6:7]
	s_add_i32 m0, s10, 68608
	s_nop 0
	global_load_lds_dwordx4 v193, s[6:7]
	s_add_u32 s6, s6, 0x8000
	s_addc_u32 s7, s7, 0
	v_max_f32_e32 v108, 0, v212
	v_max_f32_e32 v109, 0, v213
	v_mul_f32_e32 v0, v22, v108
	v_mul_f32_e32 v1, v23, v109
	v_max_f32_e32 v210, 0, v214
	v_max_f32_e32 v211, 0, v215
	v_fmac_f32_e32 v0, v24, v210
	v_fmac_f32_e32 v1, v25, v211
	v_max_f32_e32 v108, 0, v216
	v_max_f32_e32 v109, 0, v217
	v_fmac_f32_e32 v0, v26, v108
	v_fmac_f32_e32 v1, v27, v109
	v_mfma_f32_32x32x16_bf16 v[6:21], v[90:93], v[42:45], v[6:21]
	v_max_f32_e32 v210, 0, v218
	v_max_f32_e32 v211, 0, v219
	v_fmac_f32_e32 v0, v28, v210
	v_fmac_f32_e32 v1, v29, v211
	v_max_f32_e32 v108, 0, v220
	v_max_f32_e32 v109, 0, v221
	v_fmac_f32_e32 v0, v30, v108
	v_fmac_f32_e32 v1, v31, v109
	v_max_f32_e32 v210, 0, v222
	v_max_f32_e32 v211, 0, v223
	v_fmac_f32_e32 v0, v32, v210
	v_fmac_f32_e32 v1, v33, v211
	v_mfma_f32_32x32x16_bf16 v[6:21], v[94:97], v[46:49], v[6:21]
	v_max_f32_e32 v108, 0, v224
	v_max_f32_e32 v109, 0, v225
	v_fmac_f32_e32 v0, v34, v108
	v_fmac_f32_e32 v1, v35, v109
	v_max_f32_e32 v210, 0, v226
	v_max_f32_e32 v211, 0, v227
	v_fmac_f32_e32 v0, v36, v210
	v_fmac_f32_e32 v1, v37, v211
	v_add_f32_e32 v0, v0, v1
	v_ashrrev_i32_e32 v1, 31, v0
	v_mfma_f32_32x32x16_bf16 v[6:21], v[98:101], v[196:199], v[6:21]
	s_waitcnt vmcnt(10)
	ds_read_b128 v[38:41], v5 offset:10496
	ds_read_b128 v[42:45], v52 offset:10496
	ds_read_b128 v[46:49], v55 offset:10496
	ds_read_b128 v[196:199], v56 offset:10496
	v_or_b32_e32 v1, 0x80000000, v1
	s_cmpk_gt_i32 s11, 376
	s_cselect_b64 vcc, -1, 0
	v_xor_b32_e32 v0, v1, v0
	v_cndmask_b32_e32 v168, v123, v0, vcc
	s_nop 3
	v_max_f32_e32 v108, 0, v6
	v_max_f32_e32 v109, 0, v7
	v_mul_f32_e32 v50, v244, v108
	v_mul_f32_e32 v51, v245, v109
	v_max_f32_e32 v210, 0, v8
	v_max_f32_e32 v211, 0, v9
	v_fmac_f32_e32 v50, v246, v210
	v_fmac_f32_e32 v51, v247, v211
	v_max_f32_e32 v108, 0, v10
	v_max_f32_e32 v109, 0, v11
	v_fmac_f32_e32 v50, v248, v108
	v_fmac_f32_e32 v51, v249, v109
	v_max_f32_e32 v210, 0, v12
	v_max_f32_e32 v211, 0, v13
	v_fmac_f32_e32 v50, v250, v210
	v_fmac_f32_e32 v51, v251, v211
	v_max_f32_e32 v108, 0, v14
	v_max_f32_e32 v109, 0, v15
	v_fmac_f32_e32 v50, v252, v108
	v_fmac_f32_e32 v51, v253, v109
	v_max_f32_e32 v210, 0, v16
	v_max_f32_e32 v211, 0, v17
	v_fmac_f32_e32 v50, v254, v210
	v_fmac_f32_e32 v51, v255, v211
	v_max_f32_e32 v108, 0, v18
	v_max_f32_e32 v109, 0, v19
	v_fmac_f32_e32 v50, v200, v108
	v_fmac_f32_e32 v51, v201, v109
	v_max_f32_e32 v210, 0, v20
	v_max_f32_e32 v211, 0, v21
	v_fmac_f32_e32 v50, v202, v210
	v_fmac_f32_e32 v51, v203, v211
	v_add_f32_e32 v50, v50, v51
	v_ashrrev_i32_e32 v51, 31, v50
	v_or_b32_e32 v51, 0x80000000, v51
	s_cmpk_gt_i32 s11, 376
	s_cselect_b64 vcc, -1, 0
	v_xor_b32_e32 v50, v51, v50
	v_cndmask_b32_e32 v50, v123, v50, vcc
	global_store_dword v243, v50, s[8:9] offset:2048
	s_add_u32 s8, s8, 0x1000
	s_addc_u32 s9, s9, 0
	s_cmpk_gt_i32 s81, 48
	s_cbranch_scc0 .Lix_fill_6
	s_waitcnt lgkmcnt(3)
	v_mfma_f32_32x32x16_bf16 v[212:227], v[70:73], v[38:41], 0
	s_add_i32 m0, s10, 98304
	s_nop 0
	global_load_lds_dwordx4 v102, s[6:7]
	s_waitcnt lgkmcnt(2)
	v_mfma_f32_32x32x16_bf16 v[212:227], v[74:77], v[42:45], v[212:227]
	s_add_i32 m0, s10, 99328
	s_nop 0
	global_load_lds_dwordx4 v110, s[6:7]
	s_waitcnt lgkmcnt(1)
	v_mfma_f32_32x32x16_bf16 v[212:227], v[78:81], v[46:49], v[212:227]
	s_add_i32 m0, s10, 100352
	s_nop 0
	global_load_lds_dwordx4 v112, s[6:7]
	s_waitcnt lgkmcnt(0)
	v_mfma_f32_32x32x16_bf16 v[212:227], v[82:85], v[196:199], v[212:227]
	s_add_i32 m0, s10, 101376
	s_nop 0
	global_load_lds_dwordx4 v193, s[6:7]
	s_add_u32 s6, s6, 0x8000
	s_addc_u32 s7, s7, 0
	v_mfma_f32_32x32x16_bf16 v[6:21], v[86:89], v[38:41], 0
	s_nop 7
	s_nop 2
	v_max_f32_e32 v108, 0, v212
	v_max_f32_e32 v109, 0, v213
	v_mul_f32_e32 v0, v22, v108
	v_mul_f32_e32 v1, v23, v109
	v_max_f32_e32 v210, 0, v214
	v_max_f32_e32 v211, 0, v215
	v_fmac_f32_e32 v0, v24, v210
	v_fmac_f32_e32 v1, v25, v211
	v_max_f32_e32 v108, 0, v216
	v_max_f32_e32 v109, 0, v217
	v_fmac_f32_e32 v0, v26, v108
	v_fmac_f32_e32 v1, v27, v109
	v_mfma_f32_32x32x16_bf16 v[6:21], v[90:93], v[42:45], v[6:21]
	v_max_f32_e32 v210, 0, v218
	v_max_f32_e32 v211, 0, v219
	v_fmac_f32_e32 v0, v28, v210
	v_fmac_f32_e32 v1, v29, v211
	v_max_f32_e32 v108, 0, v220
	v_max_f32_e32 v109, 0, v221
	v_fmac_f32_e32 v0, v30, v108
	v_fmac_f32_e32 v1, v31, v109
	v_max_f32_e32 v210, 0, v222
	v_max_f32_e32 v211, 0, v223
	v_fmac_f32_e32 v0, v32, v210
	v_fmac_f32_e32 v1, v33, v211
	v_mfma_f32_32x32x16_bf16 v[6:21], v[94:97], v[46:49], v[6:21]
	v_max_f32_e32 v108, 0, v224
	v_max_f32_e32 v109, 0, v225
	v_fmac_f32_e32 v0, v34, v108
	v_fmac_f32_e32 v1, v35, v109
	v_max_f32_e32 v210, 0, v226
	v_max_f32_e32 v211, 0, v227
	v_fmac_f32_e32 v0, v36, v210
	v_fmac_f32_e32 v1, v37, v211
	v_add_f32_e32 v0, v0, v1
	v_ashrrev_i32_e32 v1, 31, v0
	v_mfma_f32_32x32x16_bf16 v[6:21], v[98:101], v[196:199], v[6:21]
	s_waitcnt vmcnt(10)
	ds_read_b128 v[38:41], v5 offset:43264
	ds_read_b128 v[42:45], v52 offset:43264
	ds_read_b128 v[46:49], v55 offset:43264
	ds_read_b128 v[196:199], v56 offset:43264
	v_or_b32_e32 v1, 0x80000000, v1
	s_cmpk_gt_i32 s11, 384
	s_cselect_b64 vcc, -1, 0
	v_xor_b32_e32 v0, v1, v0
	v_cndmask_b32_e32 v182, v123, v0, vcc
	s_nop 3
	s_waitcnt lgkmcnt(3)
	v_mfma_f32_32x32x16_bf16 v[212:227], v[70:73], v[38:41], 0
	v_max_f32_e32 v108, 0, v6
	v_max_f32_e32 v109, 0, v7
	v_mul_f32_e32 v50, v244, v108
	v_mul_f32_e32 v51, v245, v109
	v_max_f32_e32 v210, 0, v8
	v_max_f32_e32 v211, 0, v9
	v_fmac_f32_e32 v50, v246, v210
	v_fmac_f32_e32 v51, v247, v211
	v_max_f32_e32 v108, 0, v10
	v_max_f32_e32 v109, 0, v11
	v_fmac_f32_e32 v50, v248, v108
	v_fmac_f32_e32 v51, v249, v109
	s_waitcnt lgkmcnt(2)
	v_mfma_f32_32x32x16_bf16 v[212:227], v[74:77], v[42:45], v[212:227]
	v_max_f32_e32 v210, 0, v12
	v_max_f32_e32 v211, 0, v13
	v_fmac_f32_e32 v50, v250, v210
	v_fmac_f32_e32 v51, v251, v211
	v_max_f32_e32 v108, 0, v14
	v_max_f32_e32 v109, 0, v15
	v_fmac_f32_e32 v50, v252, v108
	v_fmac_f32_e32 v51, v253, v109
	v_max_f32_e32 v210, 0, v16
	v_max_f32_e32 v211, 0, v17
	v_fmac_f32_e32 v50, v254, v210
	v_fmac_f32_e32 v51, v255, v211
	s_waitcnt lgkmcnt(1)
	v_mfma_f32_32x32x16_bf16 v[212:227], v[78:81], v[46:49], v[212:227]
	v_max_f32_e32 v108, 0, v18
	v_max_f32_e32 v109, 0, v19
	v_fmac_f32_e32 v50, v200, v108
	v_fmac_f32_e32 v51, v201, v109
	v_max_f32_e32 v210, 0, v20
	v_max_f32_e32 v211, 0, v21
	v_fmac_f32_e32 v50, v202, v210
	v_fmac_f32_e32 v51, v203, v211
	v_add_f32_e32 v50, v50, v51
	v_ashrrev_i32_e32 v51, 31, v50
	s_waitcnt lgkmcnt(0)
	v_mfma_f32_32x32x16_bf16 v[212:227], v[82:85], v[196:199], v[212:227]
	v_or_b32_e32 v51, 0x80000000, v51
	s_cmpk_gt_i32 s11, 384
	s_cselect_b64 vcc, -1, 0
	v_xor_b32_e32 v50, v51, v50
	v_cndmask_b32_e32 v50, v123, v50, vcc
	global_store_dword v243, v50, s[8:9]
	v_mfma_f32_32x32x16_bf16 v[6:21], v[86:89], v[38:41], 0
	s_add_i32 m0, s10, 0
	s_nop 0
	global_load_lds_dwordx4 v102, s[6:7]
	s_add_i32 m0, s10, 1024
	s_nop 0
	global_load_lds_dwordx4 v110, s[6:7]
	s_add_i32 m0, s10, 2048
	s_nop 0
	global_load_lds_dwordx4 v112, s[6:7]
	s_add_i32 m0, s10, 3072
	s_nop 0
	global_load_lds_dwordx4 v193, s[6:7]
	s_add_u32 s6, s6, 0x8000
	s_addc_u32 s7, s7, 0
	v_max_f32_e32 v108, 0, v212
	v_max_f32_e32 v109, 0, v213
	v_mul_f32_e32 v0, v22, v108
	v_mul_f32_e32 v1, v23, v109
	v_max_f32_e32 v210, 0, v214
	v_max_f32_e32 v211, 0, v215
	v_fmac_f32_e32 v0, v24, v210
	v_fmac_f32_e32 v1, v25, v211
	v_max_f32_e32 v108, 0, v216
	v_max_f32_e32 v109, 0, v217
	v_fmac_f32_e32 v0, v26, v108
	v_fmac_f32_e32 v1, v27, v109
	v_mfma_f32_32x32x16_bf16 v[6:21], v[90:93], v[42:45], v[6:21]
	v_max_f32_e32 v210, 0, v218
	v_max_f32_e32 v211, 0, v219
	v_fmac_f32_e32 v0, v28, v210
	v_fmac_f32_e32 v1, v29, v211
	v_max_f32_e32 v108, 0, v220
	v_max_f32_e32 v109, 0, v221
	v_fmac_f32_e32 v0, v30, v108
	v_fmac_f32_e32 v1, v31, v109
	v_max_f32_e32 v210, 0, v222
	v_max_f32_e32 v211, 0, v223
	v_fmac_f32_e32 v0, v32, v210
	v_fmac_f32_e32 v1, v33, v211
	v_mfma_f32_32x32x16_bf16 v[6:21], v[94:97], v[46:49], v[6:21]
	v_max_f32_e32 v108, 0, v224
	v_max_f32_e32 v109, 0, v225
	v_fmac_f32_e32 v0, v34, v108
	v_fmac_f32_e32 v1, v35, v109
	v_max_f32_e32 v210, 0, v226
	v_max_f32_e32 v211, 0, v227
	v_fmac_f32_e32 v0, v36, v210
	v_fmac_f32_e32 v1, v37, v211
	v_add_f32_e32 v0, v0, v1
	v_ashrrev_i32_e32 v1, 31, v0
	v_mfma_f32_32x32x16_bf16 v[6:21], v[98:101], v[196:199], v[6:21]
	s_waitcnt vmcnt(10)
	v_add_u32_e32 v228, 0x10000, v5
	ds_read_b128 v[38:41], v228 offset:10496
	v_add_u32_e32 v228, 0x10000, v52
	ds_read_b128 v[42:45], v228 offset:10496
	v_add_u32_e32 v228, 0x10000, v55
	ds_read_b128 v[46:49], v228 offset:10496
	v_add_u32_e32 v228, 0x10000, v56
	ds_read_b128 v[196:199], v228 offset:10496
	v_or_b32_e32 v1, 0x80000000, v1
	s_cmpk_gt_i32 s11, 392
	s_cselect_b64 vcc, -1, 0
	v_xor_b32_e32 v0, v1, v0
	v_cndmask_b32_e32 v181, v123, v0, vcc
	s_nop 3
	s_waitcnt lgkmcnt(3)
	v_mfma_f32_32x32x16_bf16 v[212:227], v[70:73], v[38:41], 0
	v_max_f32_e32 v108, 0, v6
	v_max_f32_e32 v109, 0, v7
	v_mul_f32_e32 v50, v244, v108
	v_mul_f32_e32 v51, v245, v109
	v_max_f32_e32 v210, 0, v8
	v_max_f32_e32 v211, 0, v9
	v_fmac_f32_e32 v50, v246, v210
	v_fmac_f32_e32 v51, v247, v211
	v_max_f32_e32 v108, 0, v10
	v_max_f32_e32 v109, 0, v11
	v_fmac_f32_e32 v50, v248, v108
	v_fmac_f32_e32 v51, v249, v109
	s_waitcnt lgkmcnt(2)
	v_mfma_f32_32x32x16_bf16 v[212:227], v[74:77], v[42:45], v[212:227]
	v_max_f32_e32 v210, 0, v12
	v_max_f32_e32 v211, 0, v13
	v_fmac_f32_e32 v50, v250, v210
	v_fmac_f32_e32 v51, v251, v211
	v_max_f32_e32 v108, 0, v14
	v_max_f32_e32 v109, 0, v15
	v_fmac_f32_e32 v50, v252, v108
	v_fmac_f32_e32 v51, v253, v109
	v_max_f32_e32 v210, 0, v16
	v_max_f32_e32 v211, 0, v17
	v_fmac_f32_e32 v50, v254, v210
	v_fmac_f32_e32 v51, v255, v211
	s_waitcnt lgkmcnt(1)
	v_mfma_f32_32x32x16_bf16 v[212:227], v[78:81], v[46:49], v[212:227]
	v_max_f32_e32 v108, 0, v18
	v_max_f32_e32 v109, 0, v19
	v_fmac_f32_e32 v50, v200, v108
	v_fmac_f32_e32 v51, v201, v109
	v_max_f32_e32 v210, 0, v20
	v_max_f32_e32 v211, 0, v21
	v_fmac_f32_e32 v50, v202, v210
	v_fmac_f32_e32 v51, v203, v211
	v_add_f32_e32 v50, v50, v51
	v_ashrrev_i32_e32 v51, 31, v50
	s_waitcnt lgkmcnt(0)
	v_mfma_f32_32x32x16_bf16 v[212:227], v[82:85], v[196:199], v[212:227]
	v_or_b32_e32 v51, 0x80000000, v51
	s_cmpk_gt_i32 s11, 392
	s_cselect_b64 vcc, -1, 0
	v_xor_b32_e32 v50, v51, v50
	v_cndmask_b32_e32 v50, v123, v50, vcc
	global_store_dword v243, v50, s[8:9] offset:2048
	s_add_u32 s8, s8, 0x1000
	s_addc_u32 s9, s9, 0
	v_mfma_f32_32x32x16_bf16 v[6:21], v[86:89], v[38:41], 0
	s_add_i32 m0, s10, 32768
	s_nop 0
	global_load_lds_dwordx4 v102, s[6:7]
	s_add_i32 m0, s10, 33792
	s_nop 0
	global_load_lds_dwordx4 v110, s[6:7]
	s_add_i32 m0, s10, 34816
	s_nop 0
	global_load_lds_dwordx4 v112, s[6:7]
	s_add_i32 m0, s10, 35840
	s_nop 0
	global_load_lds_dwordx4 v193, s[6:7]
	s_add_u32 s6, s6, 0x8000
	s_addc_u32 s7, s7, 0
	v_max_f32_e32 v108, 0, v212
	v_max_f32_e32 v109, 0, v213
	v_mul_f32_e32 v0, v22, v108
	v_mul_f32_e32 v1, v23, v109
	v_max_f32_e32 v210, 0, v214
	v_max_f32_e32 v211, 0, v215
	v_fmac_f32_e32 v0, v24, v210
	v_fmac_f32_e32 v1, v25, v211
	v_max_f32_e32 v108, 0, v216
	v_max_f32_e32 v109, 0, v217
	v_fmac_f32_e32 v0, v26, v108
	v_fmac_f32_e32 v1, v27, v109
	v_mfma_f32_32x32x16_bf16 v[6:21], v[90:93], v[42:45], v[6:21]
	v_max_f32_e32 v210, 0, v218
	v_max_f32_e32 v211, 0, v219
	v_fmac_f32_e32 v0, v28, v210
	v_fmac_f32_e32 v1, v29, v211
	v_max_f32_e32 v108, 0, v220
	v_max_f32_e32 v109, 0, v221
	v_fmac_f32_e32 v0, v30, v108
	v_fmac_f32_e32 v1, v31, v109
	v_max_f32_e32 v210, 0, v222
	v_max_f32_e32 v211, 0, v223
	v_fmac_f32_e32 v0, v32, v210
	v_fmac_f32_e32 v1, v33, v211
	v_mfma_f32_32x32x16_bf16 v[6:21], v[94:97], v[46:49], v[6:21]
	v_max_f32_e32 v108, 0, v224
	v_max_f32_e32 v109, 0, v225
	v_fmac_f32_e32 v0, v34, v108
	v_fmac_f32_e32 v1, v35, v109
	v_max_f32_e32 v210, 0, v226
	v_max_f32_e32 v211, 0, v227
	v_fmac_f32_e32 v0, v36, v210
	v_fmac_f32_e32 v1, v37, v211
	v_add_f32_e32 v0, v0, v1
	v_ashrrev_i32_e32 v1, 31, v0
	v_mfma_f32_32x32x16_bf16 v[6:21], v[98:101], v[196:199], v[6:21]
	s_waitcnt vmcnt(10)
	v_add_u32_e32 v228, 0x10000, v5
	ds_read_b128 v[38:41], v228 offset:43264
	v_add_u32_e32 v228, 0x10000, v52
	ds_read_b128 v[42:45], v228 offset:43264
	v_add_u32_e32 v228, 0x10000, v55
	ds_read_b128 v[46:49], v228 offset:43264
	v_add_u32_e32 v228, 0x10000, v56
	ds_read_b128 v[196:199], v228 offset:43264
	v_or_b32_e32 v1, 0x80000000, v1
	s_cmpk_gt_i32 s11, 400
	s_cselect_b64 vcc, -1, 0
	v_xor_b32_e32 v0, v1, v0
	v_cndmask_b32_e32 v184, v123, v0, vcc
	s_nop 3
	s_waitcnt lgkmcnt(3)
	v_mfma_f32_32x32x16_bf16 v[212:227], v[70:73], v[38:41], 0
	v_max_f32_e32 v108, 0, v6
	v_max_f32_e32 v109, 0, v7
	v_mul_f32_e32 v50, v244, v108
	v_mul_f32_e32 v51, v245, v109
	v_max_f32_e32 v210, 0, v8
	v_max_f32_e32 v211, 0, v9
	v_fmac_f32_e32 v50, v246, v210
	v_fmac_f32_e32 v51, v247, v211
	v_max_f32_e32 v108, 0, v10
	v_max_f32_e32 v109, 0, v11
	v_fmac_f32_e32 v50, v248, v108
	v_fmac_f32_e32 v51, v249, v109
	s_waitcnt lgkmcnt(2)
	v_mfma_f32_32x32x16_bf16 v[212:227], v[74:77], v[42:45], v[212:227]
	v_max_f32_e32 v210, 0, v12
	v_max_f32_e32 v211, 0, v13
	v_fmac_f32_e32 v50, v250, v210
	v_fmac_f32_e32 v51, v251, v211
	v_max_f32_e32 v108, 0, v14
	v_max_f32_e32 v109, 0, v15
	v_fmac_f32_e32 v50, v252, v108
	v_fmac_f32_e32 v51, v253, v109
	v_max_f32_e32 v210, 0, v16
	v_max_f32_e32 v211, 0, v17
	v_fmac_f32_e32 v50, v254, v210
	v_fmac_f32_e32 v51, v255, v211
	s_waitcnt lgkmcnt(1)
	v_mfma_f32_32x32x16_bf16 v[212:227], v[78:81], v[46:49], v[212:227]
	v_max_f32_e32 v108, 0, v18
	v_max_f32_e32 v109, 0, v19
	v_fmac_f32_e32 v50, v200, v108
	v_fmac_f32_e32 v51, v201, v109
	v_max_f32_e32 v210, 0, v20
	v_max_f32_e32 v211, 0, v21
	v_fmac_f32_e32 v50, v202, v210
	v_fmac_f32_e32 v51, v203, v211
	v_add_f32_e32 v50, v50, v51
	v_ashrrev_i32_e32 v51, 31, v50
	s_waitcnt lgkmcnt(0)
	v_mfma_f32_32x32x16_bf16 v[212:227], v[82:85], v[196:199], v[212:227]
	v_or_b32_e32 v51, 0x80000000, v51
	s_cmpk_gt_i32 s11, 400
	s_cselect_b64 vcc, -1, 0
	v_xor_b32_e32 v50, v51, v50
	v_cndmask_b32_e32 v50, v123, v50, vcc
	global_store_dword v243, v50, s[8:9]
	v_mfma_f32_32x32x16_bf16 v[6:21], v[86:89], v[38:41], 0
	s_add_i32 m0, s10, 65536
	s_nop 0
	global_load_lds_dwordx4 v102, s[6:7]
	s_add_i32 m0, s10, 66560
	s_nop 0
	global_load_lds_dwordx4 v110, s[6:7]
	s_add_i32 m0, s10, 67584
	s_nop 0
	global_load_lds_dwordx4 v112, s[6:7]
	s_add_i32 m0, s10, 68608
	s_nop 0
	global_load_lds_dwordx4 v193, s[6:7]
	s_add_u32 s6, s6, 0x8000
	s_addc_u32 s7, s7, 0
	v_max_f32_e32 v108, 0, v212
	v_max_f32_e32 v109, 0, v213
	v_mul_f32_e32 v0, v22, v108
	v_mul_f32_e32 v1, v23, v109
	v_max_f32_e32 v210, 0, v214
	v_max_f32_e32 v211, 0, v215
	v_fmac_f32_e32 v0, v24, v210
	v_fmac_f32_e32 v1, v25, v211
	v_max_f32_e32 v108, 0, v216
	v_max_f32_e32 v109, 0, v217
	v_fmac_f32_e32 v0, v26, v108
	v_fmac_f32_e32 v1, v27, v109
	v_mfma_f32_32x32x16_bf16 v[6:21], v[90:93], v[42:45], v[6:21]
	v_max_f32_e32 v210, 0, v218
	v_max_f32_e32 v211, 0, v219
	v_fmac_f32_e32 v0, v28, v210
	v_fmac_f32_e32 v1, v29, v211
	v_max_f32_e32 v108, 0, v220
	v_max_f32_e32 v109, 0, v221
	v_fmac_f32_e32 v0, v30, v108
	v_fmac_f32_e32 v1, v31, v109
	v_max_f32_e32 v210, 0, v222
	v_max_f32_e32 v211, 0, v223
	v_fmac_f32_e32 v0, v32, v210
	v_fmac_f32_e32 v1, v33, v211
	v_mfma_f32_32x32x16_bf16 v[6:21], v[94:97], v[46:49], v[6:21]
	v_max_f32_e32 v108, 0, v224
	v_max_f32_e32 v109, 0, v225
	v_fmac_f32_e32 v0, v34, v108
	v_fmac_f32_e32 v1, v35, v109
	v_max_f32_e32 v210, 0, v226
	v_max_f32_e32 v211, 0, v227
	v_fmac_f32_e32 v0, v36, v210
	v_fmac_f32_e32 v1, v37, v211
	v_add_f32_e32 v0, v0, v1
	v_ashrrev_i32_e32 v1, 31, v0
	v_mfma_f32_32x32x16_bf16 v[6:21], v[98:101], v[196:199], v[6:21]
	s_waitcnt vmcnt(10)
	ds_read_b128 v[38:41], v5 offset:10496
	ds_read_b128 v[42:45], v52 offset:10496
	ds_read_b128 v[46:49], v55 offset:10496
	ds_read_b128 v[196:199], v56 offset:10496
	v_or_b32_e32 v1, 0x80000000, v1
	s_cmpk_gt_i32 s11, 408
	s_cselect_b64 vcc, -1, 0
	v_xor_b32_e32 v0, v1, v0
	v_cndmask_b32_e32 v183, v123, v0, vcc
	s_nop 3
	s_waitcnt lgkmcnt(3)
	v_mfma_f32_32x32x16_bf16 v[212:227], v[70:73], v[38:41], 0
	v_max_f32_e32 v108, 0, v6
	v_max_f32_e32 v109, 0, v7
	v_mul_f32_e32 v50, v244, v108
	v_mul_f32_e32 v51, v245, v109
	v_max_f32_e32 v210, 0, v8
	v_max_f32_e32 v211, 0, v9
	v_fmac_f32_e32 v50, v246, v210
	v_fmac_f32_e32 v51, v247, v211
	v_max_f32_e32 v108, 0, v10
	v_max_f32_e32 v109, 0, v11
	v_fmac_f32_e32 v50, v248, v108
	v_fmac_f32_e32 v51, v249, v109
	s_waitcnt lgkmcnt(2)
	v_mfma_f32_32x32x16_bf16 v[212:227], v[74:77], v[42:45], v[212:227]
	v_max_f32_e32 v210, 0, v12
	v_max_f32_e32 v211, 0, v13
	v_fmac_f32_e32 v50, v250, v210
	v_fmac_f32_e32 v51, v251, v211
	v_max_f32_e32 v108, 0, v14
	v_max_f32_e32 v109, 0, v15
	v_fmac_f32_e32 v50, v252, v108
	v_fmac_f32_e32 v51, v253, v109
	v_max_f32_e32 v210, 0, v16
	v_max_f32_e32 v211, 0, v17
	v_fmac_f32_e32 v50, v254, v210
	v_fmac_f32_e32 v51, v255, v211
	s_waitcnt lgkmcnt(1)
	v_mfma_f32_32x32x16_bf16 v[212:227], v[78:81], v[46:49], v[212:227]
	v_max_f32_e32 v108, 0, v18
	v_max_f32_e32 v109, 0, v19
	v_fmac_f32_e32 v50, v200, v108
	v_fmac_f32_e32 v51, v201, v109
	v_max_f32_e32 v210, 0, v20
	v_max_f32_e32 v211, 0, v21
	v_fmac_f32_e32 v50, v202, v210
	v_fmac_f32_e32 v51, v203, v211
	v_add_f32_e32 v50, v50, v51
	v_ashrrev_i32_e32 v51, 31, v50
	s_waitcnt lgkmcnt(0)
	v_mfma_f32_32x32x16_bf16 v[212:227], v[82:85], v[196:199], v[212:227]
	v_or_b32_e32 v51, 0x80000000, v51
	s_cmpk_gt_i32 s11, 408
	s_cselect_b64 vcc, -1, 0
	v_xor_b32_e32 v50, v51, v50
	v_cndmask_b32_e32 v50, v123, v50, vcc
	global_store_dword v243, v50, s[8:9] offset:2048
	s_add_u32 s8, s8, 0x1000
	s_addc_u32 s9, s9, 0
	v_mfma_f32_32x32x16_bf16 v[6:21], v[86:89], v[38:41], 0
	s_add_i32 m0, s10, 98304
	s_nop 0
	global_load_lds_dwordx4 v102, s[6:7]
	s_add_i32 m0, s10, 99328
	s_nop 0
	global_load_lds_dwordx4 v110, s[6:7]
	s_add_i32 m0, s10, 100352
	s_nop 0
	global_load_lds_dwordx4 v112, s[6:7]
	s_add_i32 m0, s10, 101376
	s_nop 0
	global_load_lds_dwordx4 v193, s[6:7]
	s_add_u32 s6, s6, 0x8000
	s_addc_u32 s7, s7, 0
	v_max_f32_e32 v108, 0, v212
	v_max_f32_e32 v109, 0, v213
	v_mul_f32_e32 v0, v22, v108
	v_mul_f32_e32 v1, v23, v109
	v_max_f32_e32 v210, 0, v214
	v_max_f32_e32 v211, 0, v215
	v_fmac_f32_e32 v0, v24, v210
	v_fmac_f32_e32 v1, v25, v211
	v_max_f32_e32 v108, 0, v216
	v_max_f32_e32 v109, 0, v217
	v_fmac_f32_e32 v0, v26, v108
	v_fmac_f32_e32 v1, v27, v109
	v_mfma_f32_32x32x16_bf16 v[6:21], v[90:93], v[42:45], v[6:21]
	v_max_f32_e32 v210, 0, v218
	v_max_f32_e32 v211, 0, v219
	v_fmac_f32_e32 v0, v28, v210
	v_fmac_f32_e32 v1, v29, v211
	v_max_f32_e32 v108, 0, v220
	v_max_f32_e32 v109, 0, v221
	v_fmac_f32_e32 v0, v30, v108
	v_fmac_f32_e32 v1, v31, v109
	v_max_f32_e32 v210, 0, v222
	v_max_f32_e32 v211, 0, v223
	v_fmac_f32_e32 v0, v32, v210
	v_fmac_f32_e32 v1, v33, v211
	v_mfma_f32_32x32x16_bf16 v[6:21], v[94:97], v[46:49], v[6:21]
	v_max_f32_e32 v108, 0, v224
	v_max_f32_e32 v109, 0, v225
	v_fmac_f32_e32 v0, v34, v108
	v_fmac_f32_e32 v1, v35, v109
	v_max_f32_e32 v210, 0, v226
	v_max_f32_e32 v211, 0, v227
	v_fmac_f32_e32 v0, v36, v210
	v_fmac_f32_e32 v1, v37, v211
	v_add_f32_e32 v0, v0, v1
	v_ashrrev_i32_e32 v1, 31, v0
	v_mfma_f32_32x32x16_bf16 v[6:21], v[98:101], v[196:199], v[6:21]
	s_waitcnt vmcnt(10)
	ds_read_b128 v[38:41], v5 offset:43264
	ds_read_b128 v[42:45], v52 offset:43264
	ds_read_b128 v[46:49], v55 offset:43264
	ds_read_b128 v[196:199], v56 offset:43264
	v_or_b32_e32 v1, 0x80000000, v1
	s_cmpk_gt_i32 s11, 416
	s_cselect_b64 vcc, -1, 0
	v_xor_b32_e32 v0, v1, v0
	v_cndmask_b32_e32 v187, v123, v0, vcc
	s_nop 3
	s_waitcnt lgkmcnt(3)
	v_mfma_f32_32x32x16_bf16 v[212:227], v[70:73], v[38:41], 0
	v_max_f32_e32 v108, 0, v6
	v_max_f32_e32 v109, 0, v7
	v_mul_f32_e32 v50, v244, v108
	v_mul_f32_e32 v51, v245, v109
	v_max_f32_e32 v210, 0, v8
	v_max_f32_e32 v211, 0, v9
	v_fmac_f32_e32 v50, v246, v210
	v_fmac_f32_e32 v51, v247, v211
	v_max_f32_e32 v108, 0, v10
	v_max_f32_e32 v109, 0, v11
	v_fmac_f32_e32 v50, v248, v108
	v_fmac_f32_e32 v51, v249, v109
	s_waitcnt lgkmcnt(2)
	v_mfma_f32_32x32x16_bf16 v[212:227], v[74:77], v[42:45], v[212:227]
	v_max_f32_e32 v210, 0, v12
	v_max_f32_e32 v211, 0, v13
	v_fmac_f32_e32 v50, v250, v210
	v_fmac_f32_e32 v51, v251, v211
	v_max_f32_e32 v108, 0, v14
	v_max_f32_e32 v109, 0, v15
	v_fmac_f32_e32 v50, v252, v108
	v_fmac_f32_e32 v51, v253, v109
	v_max_f32_e32 v210, 0, v16
	v_max_f32_e32 v211, 0, v17
	v_fmac_f32_e32 v50, v254, v210
	v_fmac_f32_e32 v51, v255, v211
	s_waitcnt lgkmcnt(1)
	v_mfma_f32_32x32x16_bf16 v[212:227], v[78:81], v[46:49], v[212:227]
	v_max_f32_e32 v108, 0, v18
	v_max_f32_e32 v109, 0, v19
	v_fmac_f32_e32 v50, v200, v108
	v_fmac_f32_e32 v51, v201, v109
	v_max_f32_e32 v210, 0, v20
	v_max_f32_e32 v211, 0, v21
	v_fmac_f32_e32 v50, v202, v210
	v_fmac_f32_e32 v51, v203, v211
	v_add_f32_e32 v50, v50, v51
	v_ashrrev_i32_e32 v51, 31, v50
	s_waitcnt lgkmcnt(0)
	v_mfma_f32_32x32x16_bf16 v[212:227], v[82:85], v[196:199], v[212:227]
	v_or_b32_e32 v51, 0x80000000, v51
	s_cmpk_gt_i32 s11, 416
	s_cselect_b64 vcc, -1, 0
	v_xor_b32_e32 v50, v51, v50
	v_cndmask_b32_e32 v50, v123, v50, vcc
	global_store_dword v243, v50, s[8:9]
	v_mfma_f32_32x32x16_bf16 v[6:21], v[86:89], v[38:41], 0
	s_add_i32 m0, s10, 0
	s_nop 0
	global_load_lds_dwordx4 v102, s[6:7]
	s_add_i32 m0, s10, 1024
	s_nop 0
	global_load_lds_dwordx4 v110, s[6:7]
	s_add_i32 m0, s10, 2048
	s_nop 0
	global_load_lds_dwordx4 v112, s[6:7]
	s_add_i32 m0, s10, 3072
	s_nop 0
	global_load_lds_dwordx4 v193, s[6:7]
	s_add_u32 s6, s6, 0x8000
	s_addc_u32 s7, s7, 0
	v_max_f32_e32 v108, 0, v212
	v_max_f32_e32 v109, 0, v213
	v_mul_f32_e32 v0, v22, v108
	v_mul_f32_e32 v1, v23, v109
	v_max_f32_e32 v210, 0, v214
	v_max_f32_e32 v211, 0, v215
	v_fmac_f32_e32 v0, v24, v210
	v_fmac_f32_e32 v1, v25, v211
	v_max_f32_e32 v108, 0, v216
	v_max_f32_e32 v109, 0, v217
	v_fmac_f32_e32 v0, v26, v108
	v_fmac_f32_e32 v1, v27, v109
	v_mfma_f32_32x32x16_bf16 v[6:21], v[90:93], v[42:45], v[6:21]
	v_max_f32_e32 v210, 0, v218
	v_max_f32_e32 v211, 0, v219
	v_fmac_f32_e32 v0, v28, v210
	v_fmac_f32_e32 v1, v29, v211
	v_max_f32_e32 v108, 0, v220
	v_max_f32_e32 v109, 0, v221
	v_fmac_f32_e32 v0, v30, v108
	v_fmac_f32_e32 v1, v31, v109
	v_max_f32_e32 v210, 0, v222
	v_max_f32_e32 v211, 0, v223
	v_fmac_f32_e32 v0, v32, v210
	v_fmac_f32_e32 v1, v33, v211
	v_mfma_f32_32x32x16_bf16 v[6:21], v[94:97], v[46:49], v[6:21]
	v_max_f32_e32 v108, 0, v224
	v_max_f32_e32 v109, 0, v225
	v_fmac_f32_e32 v0, v34, v108
	v_fmac_f32_e32 v1, v35, v109
	v_max_f32_e32 v210, 0, v226
	v_max_f32_e32 v211, 0, v227
	v_fmac_f32_e32 v0, v36, v210
	v_fmac_f32_e32 v1, v37, v211
	v_add_f32_e32 v0, v0, v1
	v_ashrrev_i32_e32 v1, 31, v0
	v_mfma_f32_32x32x16_bf16 v[6:21], v[98:101], v[196:199], v[6:21]
	s_waitcnt vmcnt(10)
	v_add_u32_e32 v228, 0x10000, v5
	ds_read_b128 v[38:41], v228 offset:10496
	v_add_u32_e32 v228, 0x10000, v52
	ds_read_b128 v[42:45], v228 offset:10496
	v_add_u32_e32 v228, 0x10000, v55
	ds_read_b128 v[46:49], v228 offset:10496
	v_add_u32_e32 v228, 0x10000, v56
	ds_read_b128 v[196:199], v228 offset:10496
	v_or_b32_e32 v1, 0x80000000, v1
	s_cmpk_gt_i32 s11, 424
	s_cselect_b64 vcc, -1, 0
	v_xor_b32_e32 v0, v1, v0
	v_cndmask_b32_e32 v186, v123, v0, vcc
	s_nop 3
	s_waitcnt lgkmcnt(3)
	v_mfma_f32_32x32x16_bf16 v[212:227], v[70:73], v[38:41], 0
	v_max_f32_e32 v108, 0, v6
	v_max_f32_e32 v109, 0, v7
	v_mul_f32_e32 v50, v244, v108
	v_mul_f32_e32 v51, v245, v109
	v_max_f32_e32 v210, 0, v8
	v_max_f32_e32 v211, 0, v9
	v_fmac_f32_e32 v50, v246, v210
	v_fmac_f32_e32 v51, v247, v211
	v_max_f32_e32 v108, 0, v10
	v_max_f32_e32 v109, 0, v11
	v_fmac_f32_e32 v50, v248, v108
	v_fmac_f32_e32 v51, v249, v109
	s_waitcnt lgkmcnt(2)
	v_mfma_f32_32x32x16_bf16 v[212:227], v[74:77], v[42:45], v[212:227]
	v_max_f32_e32 v210, 0, v12
	v_max_f32_e32 v211, 0, v13
	v_fmac_f32_e32 v50, v250, v210
	v_fmac_f32_e32 v51, v251, v211
	v_max_f32_e32 v108, 0, v14
	v_max_f32_e32 v109, 0, v15
	v_fmac_f32_e32 v50, v252, v108
	v_fmac_f32_e32 v51, v253, v109
	v_max_f32_e32 v210, 0, v16
	v_max_f32_e32 v211, 0, v17
	v_fmac_f32_e32 v50, v254, v210
	v_fmac_f32_e32 v51, v255, v211
	s_waitcnt lgkmcnt(1)
	v_mfma_f32_32x32x16_bf16 v[212:227], v[78:81], v[46:49], v[212:227]
	v_max_f32_e32 v108, 0, v18
	v_max_f32_e32 v109, 0, v19
	v_fmac_f32_e32 v50, v200, v108
	v_fmac_f32_e32 v51, v201, v109
	v_max_f32_e32 v210, 0, v20
	v_max_f32_e32 v211, 0, v21
	v_fmac_f32_e32 v50, v202, v210
	v_fmac_f32_e32 v51, v203, v211
	v_add_f32_e32 v50, v50, v51
	v_ashrrev_i32_e32 v51, 31, v50
	s_waitcnt lgkmcnt(0)
	v_mfma_f32_32x32x16_bf16 v[212:227], v[82:85], v[196:199], v[212:227]
	v_or_b32_e32 v51, 0x80000000, v51
	s_cmpk_gt_i32 s11, 424
	s_cselect_b64 vcc, -1, 0
	v_xor_b32_e32 v50, v51, v50
	v_cndmask_b32_e32 v50, v123, v50, vcc
	global_store_dword v243, v50, s[8:9] offset:2048
	s_add_u32 s8, s8, 0x1000
	s_addc_u32 s9, s9, 0
	v_mfma_f32_32x32x16_bf16 v[6:21], v[86:89], v[38:41], 0
	s_add_i32 m0, s10, 32768
	s_nop 0
	global_load_lds_dwordx4 v102, s[6:7]
	s_add_i32 m0, s10, 33792
	s_nop 0
	global_load_lds_dwordx4 v110, s[6:7]
	s_add_i32 m0, s10, 34816
	s_nop 0
	global_load_lds_dwordx4 v112, s[6:7]
	s_add_i32 m0, s10, 35840
	s_nop 0
	global_load_lds_dwordx4 v193, s[6:7]
	s_add_u32 s6, s6, 0x8000
	s_addc_u32 s7, s7, 0
	v_max_f32_e32 v108, 0, v212
	v_max_f32_e32 v109, 0, v213
	v_mul_f32_e32 v0, v22, v108
	v_mul_f32_e32 v1, v23, v109
	v_max_f32_e32 v210, 0, v214
	v_max_f32_e32 v211, 0, v215
	v_fmac_f32_e32 v0, v24, v210
	v_fmac_f32_e32 v1, v25, v211
	v_max_f32_e32 v108, 0, v216
	v_max_f32_e32 v109, 0, v217
	v_fmac_f32_e32 v0, v26, v108
	v_fmac_f32_e32 v1, v27, v109
	v_mfma_f32_32x32x16_bf16 v[6:21], v[90:93], v[42:45], v[6:21]
	v_max_f32_e32 v210, 0, v218
	v_max_f32_e32 v211, 0, v219
	v_fmac_f32_e32 v0, v28, v210
	v_fmac_f32_e32 v1, v29, v211
	v_max_f32_e32 v108, 0, v220
	v_max_f32_e32 v109, 0, v221
	v_fmac_f32_e32 v0, v30, v108
	v_fmac_f32_e32 v1, v31, v109
	v_max_f32_e32 v210, 0, v222
	v_max_f32_e32 v211, 0, v223
	v_fmac_f32_e32 v0, v32, v210
	v_fmac_f32_e32 v1, v33, v211
	v_mfma_f32_32x32x16_bf16 v[6:21], v[94:97], v[46:49], v[6:21]
	v_max_f32_e32 v108, 0, v224
	v_max_f32_e32 v109, 0, v225
	v_fmac_f32_e32 v0, v34, v108
	v_fmac_f32_e32 v1, v35, v109
	v_max_f32_e32 v210, 0, v226
	v_max_f32_e32 v211, 0, v227
	v_fmac_f32_e32 v0, v36, v210
	v_fmac_f32_e32 v1, v37, v211
	v_add_f32_e32 v0, v0, v1
	v_ashrrev_i32_e32 v1, 31, v0
	v_mfma_f32_32x32x16_bf16 v[6:21], v[98:101], v[196:199], v[6:21]
	s_waitcnt vmcnt(10)
	v_add_u32_e32 v228, 0x10000, v5
	ds_read_b128 v[38:41], v228 offset:43264
	v_add_u32_e32 v228, 0x10000, v52
	ds_read_b128 v[42:45], v228 offset:43264
	v_add_u32_e32 v228, 0x10000, v55
	ds_read_b128 v[46:49], v228 offset:43264
	v_add_u32_e32 v228, 0x10000, v56
	ds_read_b128 v[196:199], v228 offset:43264
	v_or_b32_e32 v1, 0x80000000, v1
	s_cmpk_gt_i32 s11, 432
	s_cselect_b64 vcc, -1, 0
	v_xor_b32_e32 v0, v1, v0
	v_cndmask_b32_e32 v189, v123, v0, vcc
	s_nop 3
	s_waitcnt lgkmcnt(3)
	v_mfma_f32_32x32x16_bf16 v[212:227], v[70:73], v[38:41], 0
	v_max_f32_e32 v108, 0, v6
	v_max_f32_e32 v109, 0, v7
	v_mul_f32_e32 v50, v244, v108
	v_mul_f32_e32 v51, v245, v109
	v_max_f32_e32 v210, 0, v8
	v_max_f32_e32 v211, 0, v9
	v_fmac_f32_e32 v50, v246, v210
	v_fmac_f32_e32 v51, v247, v211
	v_max_f32_e32 v108, 0, v10
	v_max_f32_e32 v109, 0, v11
	v_fmac_f32_e32 v50, v248, v108
	v_fmac_f32_e32 v51, v249, v109
	s_waitcnt lgkmcnt(2)
	v_mfma_f32_32x32x16_bf16 v[212:227], v[74:77], v[42:45], v[212:227]
	v_max_f32_e32 v210, 0, v12
	v_max_f32_e32 v211, 0, v13
	v_fmac_f32_e32 v50, v250, v210
	v_fmac_f32_e32 v51, v251, v211
	v_max_f32_e32 v108, 0, v14
	v_max_f32_e32 v109, 0, v15
	v_fmac_f32_e32 v50, v252, v108
	v_fmac_f32_e32 v51, v253, v109
	v_max_f32_e32 v210, 0, v16
	v_max_f32_e32 v211, 0, v17
	v_fmac_f32_e32 v50, v254, v210
	v_fmac_f32_e32 v51, v255, v211
	s_waitcnt lgkmcnt(1)
	v_mfma_f32_32x32x16_bf16 v[212:227], v[78:81], v[46:49], v[212:227]
	v_max_f32_e32 v108, 0, v18
	v_max_f32_e32 v109, 0, v19
	v_fmac_f32_e32 v50, v200, v108
	v_fmac_f32_e32 v51, v201, v109
	v_max_f32_e32 v210, 0, v20
	v_max_f32_e32 v211, 0, v21
	v_fmac_f32_e32 v50, v202, v210
	v_fmac_f32_e32 v51, v203, v211
	v_add_f32_e32 v50, v50, v51
	v_ashrrev_i32_e32 v51, 31, v50
	s_waitcnt lgkmcnt(0)
	v_mfma_f32_32x32x16_bf16 v[212:227], v[82:85], v[196:199], v[212:227]
	v_or_b32_e32 v51, 0x80000000, v51
	s_cmpk_gt_i32 s11, 432
	s_cselect_b64 vcc, -1, 0
	v_xor_b32_e32 v50, v51, v50
	v_cndmask_b32_e32 v50, v123, v50, vcc
	global_store_dword v243, v50, s[8:9]
	v_mfma_f32_32x32x16_bf16 v[6:21], v[86:89], v[38:41], 0
	s_add_i32 m0, s10, 65536
	s_nop 0
	global_load_lds_dwordx4 v102, s[6:7]
	s_add_i32 m0, s10, 66560
	s_nop 0
	global_load_lds_dwordx4 v110, s[6:7]
	s_add_i32 m0, s10, 67584
	s_nop 0
	global_load_lds_dwordx4 v112, s[6:7]
	s_add_i32 m0, s10, 68608
	s_nop 0
	global_load_lds_dwordx4 v193, s[6:7]
	s_add_u32 s6, s6, 0x8000
	s_addc_u32 s7, s7, 0
	v_max_f32_e32 v108, 0, v212
	v_max_f32_e32 v109, 0, v213
	v_mul_f32_e32 v0, v22, v108
	v_mul_f32_e32 v1, v23, v109
	v_max_f32_e32 v210, 0, v214
	v_max_f32_e32 v211, 0, v215
	v_fmac_f32_e32 v0, v24, v210
	v_fmac_f32_e32 v1, v25, v211
	v_max_f32_e32 v108, 0, v216
	v_max_f32_e32 v109, 0, v217
	v_fmac_f32_e32 v0, v26, v108
	v_fmac_f32_e32 v1, v27, v109
	v_mfma_f32_32x32x16_bf16 v[6:21], v[90:93], v[42:45], v[6:21]
	v_max_f32_e32 v210, 0, v218
	v_max_f32_e32 v211, 0, v219
	v_fmac_f32_e32 v0, v28, v210
	v_fmac_f32_e32 v1, v29, v211
	v_max_f32_e32 v108, 0, v220
	v_max_f32_e32 v109, 0, v221
	v_fmac_f32_e32 v0, v30, v108
	v_fmac_f32_e32 v1, v31, v109
	v_max_f32_e32 v210, 0, v222
	v_max_f32_e32 v211, 0, v223
	v_fmac_f32_e32 v0, v32, v210
	v_fmac_f32_e32 v1, v33, v211
	v_mfma_f32_32x32x16_bf16 v[6:21], v[94:97], v[46:49], v[6:21]
	v_max_f32_e32 v108, 0, v224
	v_max_f32_e32 v109, 0, v225
	v_fmac_f32_e32 v0, v34, v108
	v_fmac_f32_e32 v1, v35, v109
	v_max_f32_e32 v210, 0, v226
	v_max_f32_e32 v211, 0, v227
	v_fmac_f32_e32 v0, v36, v210
	v_fmac_f32_e32 v1, v37, v211
	v_add_f32_e32 v0, v0, v1
	v_ashrrev_i32_e32 v1, 31, v0
	v_mfma_f32_32x32x16_bf16 v[6:21], v[98:101], v[196:199], v[6:21]
	s_waitcnt vmcnt(10)
	ds_read_b128 v[38:41], v5 offset:10496
	ds_read_b128 v[42:45], v52 offset:10496
	ds_read_b128 v[46:49], v55 offset:10496
	ds_read_b128 v[196:199], v56 offset:10496
	v_or_b32_e32 v1, 0x80000000, v1
	s_cmpk_gt_i32 s11, 440
	s_cselect_b64 vcc, -1, 0
	v_xor_b32_e32 v0, v1, v0
	v_cndmask_b32_e32 v188, v123, v0, vcc
	s_nop 3
	v_max_f32_e32 v108, 0, v6
	v_max_f32_e32 v109, 0, v7
	v_mul_f32_e32 v50, v244, v108
	v_mul_f32_e32 v51, v245, v109
	v_max_f32_e32 v210, 0, v8
	v_max_f32_e32 v211, 0, v9
	v_fmac_f32_e32 v50, v246, v210
	v_fmac_f32_e32 v51, v247, v211
	v_max_f32_e32 v108, 0, v10
	v_max_f32_e32 v109, 0, v11
	v_fmac_f32_e32 v50, v248, v108
	v_fmac_f32_e32 v51, v249, v109
	v_max_f32_e32 v210, 0, v12
	v_max_f32_e32 v211, 0, v13
	v_fmac_f32_e32 v50, v250, v210
	v_fmac_f32_e32 v51, v251, v211
	v_max_f32_e32 v108, 0, v14
	v_max_f32_e32 v109, 0, v15
	v_fmac_f32_e32 v50, v252, v108
	v_fmac_f32_e32 v51, v253, v109
	v_max_f32_e32 v210, 0, v16
	v_max_f32_e32 v211, 0, v17
	v_fmac_f32_e32 v50, v254, v210
	v_fmac_f32_e32 v51, v255, v211
	v_max_f32_e32 v108, 0, v18
	v_max_f32_e32 v109, 0, v19
	v_fmac_f32_e32 v50, v200, v108
	v_fmac_f32_e32 v51, v201, v109
	v_max_f32_e32 v210, 0, v20
	v_max_f32_e32 v211, 0, v21
	v_fmac_f32_e32 v50, v202, v210
	v_fmac_f32_e32 v51, v203, v211
	v_add_f32_e32 v50, v50, v51
	v_ashrrev_i32_e32 v51, 31, v50
	v_or_b32_e32 v51, 0x80000000, v51
	s_cmpk_gt_i32 s11, 440
	s_cselect_b64 vcc, -1, 0
	v_xor_b32_e32 v50, v51, v50
	v_cndmask_b32_e32 v50, v123, v50, vcc
	global_store_dword v243, v50, s[8:9] offset:2048
	s_add_u32 s8, s8, 0x1000
	s_addc_u32 s9, s9, 0
	s_cmpk_gt_i32 s81, 56
	s_cbranch_scc0 .Lix_fill_7
	s_waitcnt lgkmcnt(3)
	v_mfma_f32_32x32x16_bf16 v[212:227], v[70:73], v[38:41], 0
	s_add_i32 m0, s10, 98304
	s_nop 0
	global_load_lds_dwordx4 v102, s[6:7]
	s_waitcnt lgkmcnt(2)
	v_mfma_f32_32x32x16_bf16 v[212:227], v[74:77], v[42:45], v[212:227]
	s_add_i32 m0, s10, 99328
	s_nop 0
	global_load_lds_dwordx4 v110, s[6:7]
	s_waitcnt lgkmcnt(1)
	v_mfma_f32_32x32x16_bf16 v[212:227], v[78:81], v[46:49], v[212:227]
	s_add_i32 m0, s10, 100352
	s_nop 0
	global_load_lds_dwordx4 v112, s[6:7]
	s_waitcnt lgkmcnt(0)
	v_mfma_f32_32x32x16_bf16 v[212:227], v[82:85], v[196:199], v[212:227]
	s_add_i32 m0, s10, 101376
	s_nop 0
	global_load_lds_dwordx4 v193, s[6:7]
	s_add_u32 s6, s6, 0x8000
	s_addc_u32 s7, s7, 0
	v_mfma_f32_32x32x16_bf16 v[6:21], v[86:89], v[38:41], 0
	s_nop 7
	s_nop 2
	v_max_f32_e32 v108, 0, v212
	v_max_f32_e32 v109, 0, v213
	v_mul_f32_e32 v0, v22, v108
	v_mul_f32_e32 v1, v23, v109
	v_max_f32_e32 v210, 0, v214
	v_max_f32_e32 v211, 0, v215
	v_fmac_f32_e32 v0, v24, v210
	v_fmac_f32_e32 v1, v25, v211
	v_max_f32_e32 v108, 0, v216
	v_max_f32_e32 v109, 0, v217
	v_fmac_f32_e32 v0, v26, v108
	v_fmac_f32_e32 v1, v27, v109
	v_mfma_f32_32x32x16_bf16 v[6:21], v[90:93], v[42:45], v[6:21]
	v_max_f32_e32 v210, 0, v218
	v_max_f32_e32 v211, 0, v219
	v_fmac_f32_e32 v0, v28, v210
	v_fmac_f32_e32 v1, v29, v211
	v_max_f32_e32 v108, 0, v220
	v_max_f32_e32 v109, 0, v221
	v_fmac_f32_e32 v0, v30, v108
	v_fmac_f32_e32 v1, v31, v109
	v_max_f32_e32 v210, 0, v222
	v_max_f32_e32 v211, 0, v223
	v_fmac_f32_e32 v0, v32, v210
	v_fmac_f32_e32 v1, v33, v211
	v_mfma_f32_32x32x16_bf16 v[6:21], v[94:97], v[46:49], v[6:21]
	v_max_f32_e32 v108, 0, v224
	v_max_f32_e32 v109, 0, v225
	v_fmac_f32_e32 v0, v34, v108
	v_fmac_f32_e32 v1, v35, v109
	v_max_f32_e32 v210, 0, v226
	v_max_f32_e32 v211, 0, v227
	v_fmac_f32_e32 v0, v36, v210
	v_fmac_f32_e32 v1, v37, v211
	v_add_f32_e32 v0, v0, v1
	v_ashrrev_i32_e32 v1, 31, v0
	v_mfma_f32_32x32x16_bf16 v[6:21], v[98:101], v[196:199], v[6:21]
	s_waitcnt vmcnt(10)
	ds_read_b128 v[38:41], v5 offset:43264
	ds_read_b128 v[42:45], v52 offset:43264
	ds_read_b128 v[46:49], v55 offset:43264
	ds_read_b128 v[196:199], v56 offset:43264
	v_or_b32_e32 v1, 0x80000000, v1
	s_cmpk_gt_i32 s11, 448
	s_cselect_b64 vcc, -1, 0
	v_xor_b32_e32 v0, v1, v0
	v_cndmask_b32_e32 v190, v123, v0, vcc
	s_nop 3
	s_waitcnt lgkmcnt(3)
	v_mfma_f32_32x32x16_bf16 v[212:227], v[70:73], v[38:41], 0
	v_max_f32_e32 v108, 0, v6
	v_max_f32_e32 v109, 0, v7
	v_mul_f32_e32 v50, v244, v108
	v_mul_f32_e32 v51, v245, v109
	v_max_f32_e32 v210, 0, v8
	v_max_f32_e32 v211, 0, v9
	v_fmac_f32_e32 v50, v246, v210
	v_fmac_f32_e32 v51, v247, v211
	v_max_f32_e32 v108, 0, v10
	v_max_f32_e32 v109, 0, v11
	v_fmac_f32_e32 v50, v248, v108
	v_fmac_f32_e32 v51, v249, v109
	s_waitcnt lgkmcnt(2)
	v_mfma_f32_32x32x16_bf16 v[212:227], v[74:77], v[42:45], v[212:227]
	v_max_f32_e32 v210, 0, v12
	v_max_f32_e32 v211, 0, v13
	v_fmac_f32_e32 v50, v250, v210
	v_fmac_f32_e32 v51, v251, v211
	v_max_f32_e32 v108, 0, v14
	v_max_f32_e32 v109, 0, v15
	v_fmac_f32_e32 v50, v252, v108
	v_fmac_f32_e32 v51, v253, v109
	v_max_f32_e32 v210, 0, v16
	v_max_f32_e32 v211, 0, v17
	v_fmac_f32_e32 v50, v254, v210
	v_fmac_f32_e32 v51, v255, v211
	s_waitcnt lgkmcnt(1)
	v_mfma_f32_32x32x16_bf16 v[212:227], v[78:81], v[46:49], v[212:227]
	v_max_f32_e32 v108, 0, v18
	v_max_f32_e32 v109, 0, v19
	v_fmac_f32_e32 v50, v200, v108
	v_fmac_f32_e32 v51, v201, v109
	v_max_f32_e32 v210, 0, v20
	v_max_f32_e32 v211, 0, v21
	v_fmac_f32_e32 v50, v202, v210
	v_fmac_f32_e32 v51, v203, v211
	v_add_f32_e32 v50, v50, v51
	v_ashrrev_i32_e32 v51, 31, v50
	s_waitcnt lgkmcnt(0)
	v_mfma_f32_32x32x16_bf16 v[212:227], v[82:85], v[196:199], v[212:227]
	v_or_b32_e32 v51, 0x80000000, v51
	s_cmpk_gt_i32 s11, 448
	s_cselect_b64 vcc, -1, 0
	v_xor_b32_e32 v50, v51, v50
	v_cndmask_b32_e32 v50, v123, v50, vcc
	global_store_dword v243, v50, s[8:9]
	v_mfma_f32_32x32x16_bf16 v[6:21], v[86:89], v[38:41], 0
	s_add_i32 m0, s10, 0
	s_nop 0
	global_load_lds_dwordx4 v102, s[6:7]
	s_add_i32 m0, s10, 1024
	s_nop 0
	global_load_lds_dwordx4 v110, s[6:7]
	s_add_i32 m0, s10, 2048
	s_nop 0
	global_load_lds_dwordx4 v112, s[6:7]
	s_add_i32 m0, s10, 3072
	s_nop 0
	global_load_lds_dwordx4 v193, s[6:7]
	s_add_u32 s6, s6, 0x8000
	s_addc_u32 s7, s7, 0
	v_max_f32_e32 v108, 0, v212
	v_max_f32_e32 v109, 0, v213
	v_mul_f32_e32 v0, v22, v108
	v_mul_f32_e32 v1, v23, v109
	v_max_f32_e32 v210, 0, v214
	v_max_f32_e32 v211, 0, v215
	v_fmac_f32_e32 v0, v24, v210
	v_fmac_f32_e32 v1, v25, v211
	v_max_f32_e32 v108, 0, v216
	v_max_f32_e32 v109, 0, v217
	v_fmac_f32_e32 v0, v26, v108
	v_fmac_f32_e32 v1, v27, v109
	v_mfma_f32_32x32x16_bf16 v[6:21], v[90:93], v[42:45], v[6:21]
	v_max_f32_e32 v210, 0, v218
	v_max_f32_e32 v211, 0, v219
	v_fmac_f32_e32 v0, v28, v210
	v_fmac_f32_e32 v1, v29, v211
	v_max_f32_e32 v108, 0, v220
	v_max_f32_e32 v109, 0, v221
	v_fmac_f32_e32 v0, v30, v108
	v_fmac_f32_e32 v1, v31, v109
	v_max_f32_e32 v210, 0, v222
	v_max_f32_e32 v211, 0, v223
	v_fmac_f32_e32 v0, v32, v210
	v_fmac_f32_e32 v1, v33, v211
	v_mfma_f32_32x32x16_bf16 v[6:21], v[94:97], v[46:49], v[6:21]
	v_max_f32_e32 v108, 0, v224
	v_max_f32_e32 v109, 0, v225
	v_fmac_f32_e32 v0, v34, v108
	v_fmac_f32_e32 v1, v35, v109
	v_max_f32_e32 v210, 0, v226
	v_max_f32_e32 v211, 0, v227
	v_fmac_f32_e32 v0, v36, v210
	v_fmac_f32_e32 v1, v37, v211
	v_add_f32_e32 v0, v0, v1
	v_ashrrev_i32_e32 v1, 31, v0
	v_mfma_f32_32x32x16_bf16 v[6:21], v[98:101], v[196:199], v[6:21]
	s_waitcnt vmcnt(10)
	v_add_u32_e32 v228, 0x10000, v5
	ds_read_b128 v[38:41], v228 offset:10496
	v_add_u32_e32 v228, 0x10000, v52
	ds_read_b128 v[42:45], v228 offset:10496
	v_add_u32_e32 v228, 0x10000, v55
	ds_read_b128 v[46:49], v228 offset:10496
	v_add_u32_e32 v228, 0x10000, v56
	ds_read_b128 v[196:199], v228 offset:10496
	v_or_b32_e32 v1, 0x80000000, v1
	s_cmpk_gt_i32 s11, 456
	s_cselect_b64 vcc, -1, 0
	v_xor_b32_e32 v0, v1, v0
	v_cndmask_b32_e32 v53, v123, v0, vcc
	s_nop 3
	s_waitcnt lgkmcnt(3)
	v_mfma_f32_32x32x16_bf16 v[212:227], v[70:73], v[38:41], 0
	v_max_f32_e32 v108, 0, v6
	v_max_f32_e32 v109, 0, v7
	v_mul_f32_e32 v50, v244, v108
	v_mul_f32_e32 v51, v245, v109
	v_max_f32_e32 v210, 0, v8
	v_max_f32_e32 v211, 0, v9
	v_fmac_f32_e32 v50, v246, v210
	v_fmac_f32_e32 v51, v247, v211
	v_max_f32_e32 v108, 0, v10
	v_max_f32_e32 v109, 0, v11
	v_fmac_f32_e32 v50, v248, v108
	v_fmac_f32_e32 v51, v249, v109
	s_waitcnt lgkmcnt(2)
	v_mfma_f32_32x32x16_bf16 v[212:227], v[74:77], v[42:45], v[212:227]
	v_max_f32_e32 v210, 0, v12
	v_max_f32_e32 v211, 0, v13
	v_fmac_f32_e32 v50, v250, v210
	v_fmac_f32_e32 v51, v251, v211
	v_max_f32_e32 v108, 0, v14
	v_max_f32_e32 v109, 0, v15
	v_fmac_f32_e32 v50, v252, v108
	v_fmac_f32_e32 v51, v253, v109
	v_max_f32_e32 v210, 0, v16
	v_max_f32_e32 v211, 0, v17
	v_fmac_f32_e32 v50, v254, v210
	v_fmac_f32_e32 v51, v255, v211
	s_waitcnt lgkmcnt(1)
	v_mfma_f32_32x32x16_bf16 v[212:227], v[78:81], v[46:49], v[212:227]
	v_max_f32_e32 v108, 0, v18
	v_max_f32_e32 v109, 0, v19
	v_fmac_f32_e32 v50, v200, v108
	v_fmac_f32_e32 v51, v201, v109
	v_max_f32_e32 v210, 0, v20
	v_max_f32_e32 v211, 0, v21
	v_fmac_f32_e32 v50, v202, v210
	v_fmac_f32_e32 v51, v203, v211
	v_add_f32_e32 v50, v50, v51
	v_ashrrev_i32_e32 v51, 31, v50
	s_waitcnt lgkmcnt(0)
	v_mfma_f32_32x32x16_bf16 v[212:227], v[82:85], v[196:199], v[212:227]
	v_or_b32_e32 v51, 0x80000000, v51
	s_cmpk_gt_i32 s11, 456
	s_cselect_b64 vcc, -1, 0
	v_xor_b32_e32 v50, v51, v50
	v_cndmask_b32_e32 v50, v123, v50, vcc
	global_store_dword v243, v50, s[8:9] offset:2048
	s_add_u32 s8, s8, 0x1000
	s_addc_u32 s9, s9, 0
	v_mfma_f32_32x32x16_bf16 v[6:21], v[86:89], v[38:41], 0
	s_add_i32 m0, s10, 32768
	s_nop 0
	global_load_lds_dwordx4 v102, s[6:7]
	s_add_i32 m0, s10, 33792
	s_nop 0
	global_load_lds_dwordx4 v110, s[6:7]
	s_add_i32 m0, s10, 34816
	s_nop 0
	global_load_lds_dwordx4 v112, s[6:7]
	s_add_i32 m0, s10, 35840
	s_nop 0
	global_load_lds_dwordx4 v193, s[6:7]
	s_add_u32 s6, s6, 0x8000
	s_addc_u32 s7, s7, 0
	v_max_f32_e32 v108, 0, v212
	v_max_f32_e32 v109, 0, v213
	v_mul_f32_e32 v0, v22, v108
	v_mul_f32_e32 v1, v23, v109
	v_max_f32_e32 v210, 0, v214
	v_max_f32_e32 v211, 0, v215
	v_fmac_f32_e32 v0, v24, v210
	v_fmac_f32_e32 v1, v25, v211
	v_max_f32_e32 v108, 0, v216
	v_max_f32_e32 v109, 0, v217
	v_fmac_f32_e32 v0, v26, v108
	v_fmac_f32_e32 v1, v27, v109
	v_mfma_f32_32x32x16_bf16 v[6:21], v[90:93], v[42:45], v[6:21]
	v_max_f32_e32 v210, 0, v218
	v_max_f32_e32 v211, 0, v219
	v_fmac_f32_e32 v0, v28, v210
	v_fmac_f32_e32 v1, v29, v211
	v_max_f32_e32 v108, 0, v220
	v_max_f32_e32 v109, 0, v221
	v_fmac_f32_e32 v0, v30, v108
	v_fmac_f32_e32 v1, v31, v109
	v_max_f32_e32 v210, 0, v222
	v_max_f32_e32 v211, 0, v223
	v_fmac_f32_e32 v0, v32, v210
	v_fmac_f32_e32 v1, v33, v211
	v_mfma_f32_32x32x16_bf16 v[6:21], v[94:97], v[46:49], v[6:21]
	v_max_f32_e32 v108, 0, v224
	v_max_f32_e32 v109, 0, v225
	v_fmac_f32_e32 v0, v34, v108
	v_fmac_f32_e32 v1, v35, v109
	v_max_f32_e32 v210, 0, v226
	v_max_f32_e32 v211, 0, v227
	v_fmac_f32_e32 v0, v36, v210
	v_fmac_f32_e32 v1, v37, v211
	v_add_f32_e32 v0, v0, v1
	v_ashrrev_i32_e32 v1, 31, v0
	v_mfma_f32_32x32x16_bf16 v[6:21], v[98:101], v[196:199], v[6:21]
	s_waitcnt vmcnt(10)
	v_add_u32_e32 v228, 0x10000, v5
	ds_read_b128 v[38:41], v228 offset:43264
	v_add_u32_e32 v228, 0x10000, v52
	ds_read_b128 v[42:45], v228 offset:43264
	v_add_u32_e32 v228, 0x10000, v55
	ds_read_b128 v[46:49], v228 offset:43264
	v_add_u32_e32 v228, 0x10000, v56
	ds_read_b128 v[196:199], v228 offset:43264
	v_or_b32_e32 v1, 0x80000000, v1
	s_cmpk_gt_i32 s11, 464
	s_cselect_b64 vcc, -1, 0
	v_xor_b32_e32 v0, v1, v0
	v_cndmask_b32_e32 v192, v123, v0, vcc
	s_nop 3
	s_waitcnt lgkmcnt(3)
	v_mfma_f32_32x32x16_bf16 v[212:227], v[70:73], v[38:41], 0
	v_max_f32_e32 v108, 0, v6
	v_max_f32_e32 v109, 0, v7
	v_mul_f32_e32 v50, v244, v108
	v_mul_f32_e32 v51, v245, v109
	v_max_f32_e32 v210, 0, v8
	v_max_f32_e32 v211, 0, v9
	v_fmac_f32_e32 v50, v246, v210
	v_fmac_f32_e32 v51, v247, v211
	v_max_f32_e32 v108, 0, v10
	v_max_f32_e32 v109, 0, v11
	v_fmac_f32_e32 v50, v248, v108
	v_fmac_f32_e32 v51, v249, v109
	s_waitcnt lgkmcnt(2)
	v_mfma_f32_32x32x16_bf16 v[212:227], v[74:77], v[42:45], v[212:227]
	v_max_f32_e32 v210, 0, v12
	v_max_f32_e32 v211, 0, v13
	v_fmac_f32_e32 v50, v250, v210
	v_fmac_f32_e32 v51, v251, v211
	v_max_f32_e32 v108, 0, v14
	v_max_f32_e32 v109, 0, v15
	v_fmac_f32_e32 v50, v252, v108
	v_fmac_f32_e32 v51, v253, v109
	v_max_f32_e32 v210, 0, v16
	v_max_f32_e32 v211, 0, v17
	v_fmac_f32_e32 v50, v254, v210
	v_fmac_f32_e32 v51, v255, v211
	s_waitcnt lgkmcnt(1)
	v_mfma_f32_32x32x16_bf16 v[212:227], v[78:81], v[46:49], v[212:227]
	v_max_f32_e32 v108, 0, v18
	v_max_f32_e32 v109, 0, v19
	v_fmac_f32_e32 v50, v200, v108
	v_fmac_f32_e32 v51, v201, v109
	v_max_f32_e32 v210, 0, v20
	v_max_f32_e32 v211, 0, v21
	v_fmac_f32_e32 v50, v202, v210
	v_fmac_f32_e32 v51, v203, v211
	v_add_f32_e32 v50, v50, v51
	v_ashrrev_i32_e32 v51, 31, v50
	s_waitcnt lgkmcnt(0)
	v_mfma_f32_32x32x16_bf16 v[212:227], v[82:85], v[196:199], v[212:227]
	v_or_b32_e32 v51, 0x80000000, v51
	s_cmpk_gt_i32 s11, 464
	s_cselect_b64 vcc, -1, 0
	v_xor_b32_e32 v50, v51, v50
	v_cndmask_b32_e32 v50, v123, v50, vcc
	global_store_dword v243, v50, s[8:9]
	v_mfma_f32_32x32x16_bf16 v[6:21], v[86:89], v[38:41], 0
	s_add_i32 m0, s10, 65536
	s_nop 0
	global_load_lds_dwordx4 v102, s[6:7]
	s_add_i32 m0, s10, 66560
	s_nop 0
	global_load_lds_dwordx4 v110, s[6:7]
	s_add_i32 m0, s10, 67584
	s_nop 0
	global_load_lds_dwordx4 v112, s[6:7]
	s_add_i32 m0, s10, 68608
	s_nop 0
	global_load_lds_dwordx4 v193, s[6:7]
	s_add_u32 s6, s6, 0x8000
	s_addc_u32 s7, s7, 0
	v_max_f32_e32 v108, 0, v212
	v_max_f32_e32 v109, 0, v213
	v_mul_f32_e32 v0, v22, v108
	v_mul_f32_e32 v1, v23, v109
	v_max_f32_e32 v210, 0, v214
	v_max_f32_e32 v211, 0, v215
	v_fmac_f32_e32 v0, v24, v210
	v_fmac_f32_e32 v1, v25, v211
	v_max_f32_e32 v108, 0, v216
	v_max_f32_e32 v109, 0, v217
	v_fmac_f32_e32 v0, v26, v108
	v_fmac_f32_e32 v1, v27, v109
	v_mfma_f32_32x32x16_bf16 v[6:21], v[90:93], v[42:45], v[6:21]
	v_max_f32_e32 v210, 0, v218
	v_max_f32_e32 v211, 0, v219
	v_fmac_f32_e32 v0, v28, v210
	v_fmac_f32_e32 v1, v29, v211
	v_max_f32_e32 v108, 0, v220
	v_max_f32_e32 v109, 0, v221
	v_fmac_f32_e32 v0, v30, v108
	v_fmac_f32_e32 v1, v31, v109
	v_max_f32_e32 v210, 0, v222
	v_max_f32_e32 v211, 0, v223
	v_fmac_f32_e32 v0, v32, v210
	v_fmac_f32_e32 v1, v33, v211
	v_mfma_f32_32x32x16_bf16 v[6:21], v[94:97], v[46:49], v[6:21]
	v_max_f32_e32 v108, 0, v224
	v_max_f32_e32 v109, 0, v225
	v_fmac_f32_e32 v0, v34, v108
	v_fmac_f32_e32 v1, v35, v109
	v_max_f32_e32 v210, 0, v226
	v_max_f32_e32 v211, 0, v227
	v_fmac_f32_e32 v0, v36, v210
	v_fmac_f32_e32 v1, v37, v211
	v_add_f32_e32 v0, v0, v1
	v_ashrrev_i32_e32 v1, 31, v0
	v_mfma_f32_32x32x16_bf16 v[6:21], v[98:101], v[196:199], v[6:21]
	s_waitcnt vmcnt(10)
	ds_read_b128 v[38:41], v5 offset:10496
	ds_read_b128 v[42:45], v52 offset:10496
	ds_read_b128 v[46:49], v55 offset:10496
	ds_read_b128 v[196:199], v56 offset:10496
	v_or_b32_e32 v1, 0x80000000, v1
	s_cmpk_gt_i32 s11, 472
	s_cselect_b64 vcc, -1, 0
	v_xor_b32_e32 v0, v1, v0
	v_cndmask_b32_e32 v191, v123, v0, vcc
	s_nop 3
	s_waitcnt lgkmcnt(3)
	v_mfma_f32_32x32x16_bf16 v[212:227], v[70:73], v[38:41], 0
	v_max_f32_e32 v108, 0, v6
	v_max_f32_e32 v109, 0, v7
	v_mul_f32_e32 v50, v244, v108
	v_mul_f32_e32 v51, v245, v109
	v_max_f32_e32 v210, 0, v8
	v_max_f32_e32 v211, 0, v9
	v_fmac_f32_e32 v50, v246, v210
	v_fmac_f32_e32 v51, v247, v211
	v_max_f32_e32 v108, 0, v10
	v_max_f32_e32 v109, 0, v11
	v_fmac_f32_e32 v50, v248, v108
	v_fmac_f32_e32 v51, v249, v109
	s_waitcnt lgkmcnt(2)
	v_mfma_f32_32x32x16_bf16 v[212:227], v[74:77], v[42:45], v[212:227]
	v_max_f32_e32 v210, 0, v12
	v_max_f32_e32 v211, 0, v13
	v_fmac_f32_e32 v50, v250, v210
	v_fmac_f32_e32 v51, v251, v211
	v_max_f32_e32 v108, 0, v14
	v_max_f32_e32 v109, 0, v15
	v_fmac_f32_e32 v50, v252, v108
	v_fmac_f32_e32 v51, v253, v109
	v_max_f32_e32 v210, 0, v16
	v_max_f32_e32 v211, 0, v17
	v_fmac_f32_e32 v50, v254, v210
	v_fmac_f32_e32 v51, v255, v211
	s_waitcnt lgkmcnt(1)
	v_mfma_f32_32x32x16_bf16 v[212:227], v[78:81], v[46:49], v[212:227]
	v_max_f32_e32 v108, 0, v18
	v_max_f32_e32 v109, 0, v19
	v_fmac_f32_e32 v50, v200, v108
	v_fmac_f32_e32 v51, v201, v109
	v_max_f32_e32 v210, 0, v20
	v_max_f32_e32 v211, 0, v21
	v_fmac_f32_e32 v50, v202, v210
	v_fmac_f32_e32 v51, v203, v211
	v_add_f32_e32 v50, v50, v51
	v_ashrrev_i32_e32 v51, 31, v50
	s_waitcnt lgkmcnt(0)
	v_mfma_f32_32x32x16_bf16 v[212:227], v[82:85], v[196:199], v[212:227]
	v_or_b32_e32 v51, 0x80000000, v51
	s_cmpk_gt_i32 s11, 472
	s_cselect_b64 vcc, -1, 0
	v_xor_b32_e32 v50, v51, v50
	v_cndmask_b32_e32 v50, v123, v50, vcc
	global_store_dword v243, v50, s[8:9] offset:2048
	s_add_u32 s8, s8, 0x1000
	s_addc_u32 s9, s9, 0
	v_mfma_f32_32x32x16_bf16 v[6:21], v[86:89], v[38:41], 0
	s_add_i32 m0, s10, 98304
	s_nop 0
	global_load_lds_dwordx4 v102, s[6:7]
	s_add_i32 m0, s10, 99328
	s_nop 0
	global_load_lds_dwordx4 v110, s[6:7]
	s_add_i32 m0, s10, 100352
	s_nop 0
	global_load_lds_dwordx4 v112, s[6:7]
	s_add_i32 m0, s10, 101376
	s_nop 0
	global_load_lds_dwordx4 v193, s[6:7]
	s_add_u32 s6, s6, 0x8000
	s_addc_u32 s7, s7, 0
	v_max_f32_e32 v108, 0, v212
	v_max_f32_e32 v109, 0, v213
	v_mul_f32_e32 v0, v22, v108
	v_mul_f32_e32 v1, v23, v109
	v_max_f32_e32 v210, 0, v214
	v_max_f32_e32 v211, 0, v215
	v_fmac_f32_e32 v0, v24, v210
	v_fmac_f32_e32 v1, v25, v211
	v_max_f32_e32 v108, 0, v216
	v_max_f32_e32 v109, 0, v217
	v_fmac_f32_e32 v0, v26, v108
	v_fmac_f32_e32 v1, v27, v109
	v_mfma_f32_32x32x16_bf16 v[6:21], v[90:93], v[42:45], v[6:21]
	v_max_f32_e32 v210, 0, v218
	v_max_f32_e32 v211, 0, v219
	v_fmac_f32_e32 v0, v28, v210
	v_fmac_f32_e32 v1, v29, v211
	v_max_f32_e32 v108, 0, v220
	v_max_f32_e32 v109, 0, v221
	v_fmac_f32_e32 v0, v30, v108
	v_fmac_f32_e32 v1, v31, v109
	v_max_f32_e32 v210, 0, v222
	v_max_f32_e32 v211, 0, v223
	v_fmac_f32_e32 v0, v32, v210
	v_fmac_f32_e32 v1, v33, v211
	v_mfma_f32_32x32x16_bf16 v[6:21], v[94:97], v[46:49], v[6:21]
	v_max_f32_e32 v108, 0, v224
	v_max_f32_e32 v109, 0, v225
	v_fmac_f32_e32 v0, v34, v108
	v_fmac_f32_e32 v1, v35, v109
	v_max_f32_e32 v210, 0, v226
	v_max_f32_e32 v211, 0, v227
	v_fmac_f32_e32 v0, v36, v210
	v_fmac_f32_e32 v1, v37, v211
	v_add_f32_e32 v0, v0, v1
	v_ashrrev_i32_e32 v1, 31, v0
	v_mfma_f32_32x32x16_bf16 v[6:21], v[98:101], v[196:199], v[6:21]
	s_waitcnt vmcnt(10)
	ds_read_b128 v[38:41], v5 offset:43264
	ds_read_b128 v[42:45], v52 offset:43264
	ds_read_b128 v[46:49], v55 offset:43264
	ds_read_b128 v[196:199], v56 offset:43264
	v_or_b32_e32 v1, 0x80000000, v1
	s_cmpk_gt_i32 s11, 480
	s_cselect_b64 vcc, -1, 0
	v_xor_b32_e32 v0, v1, v0
	v_cndmask_b32_e32 v3, v123, v0, vcc
	s_nop 3
	s_waitcnt lgkmcnt(3)
	v_mfma_f32_32x32x16_bf16 v[212:227], v[70:73], v[38:41], 0
	v_max_f32_e32 v108, 0, v6
	v_max_f32_e32 v109, 0, v7
	v_mul_f32_e32 v50, v244, v108
	v_mul_f32_e32 v51, v245, v109
	v_max_f32_e32 v210, 0, v8
	v_max_f32_e32 v211, 0, v9
	v_fmac_f32_e32 v50, v246, v210
	v_fmac_f32_e32 v51, v247, v211
	v_max_f32_e32 v108, 0, v10
	v_max_f32_e32 v109, 0, v11
	v_fmac_f32_e32 v50, v248, v108
	v_fmac_f32_e32 v51, v249, v109
	s_waitcnt lgkmcnt(2)
	v_mfma_f32_32x32x16_bf16 v[212:227], v[74:77], v[42:45], v[212:227]
	v_max_f32_e32 v210, 0, v12
	v_max_f32_e32 v211, 0, v13
	v_fmac_f32_e32 v50, v250, v210
	v_fmac_f32_e32 v51, v251, v211
	v_max_f32_e32 v108, 0, v14
	v_max_f32_e32 v109, 0, v15
	v_fmac_f32_e32 v50, v252, v108
	v_fmac_f32_e32 v51, v253, v109
	v_max_f32_e32 v210, 0, v16
	v_max_f32_e32 v211, 0, v17
	v_fmac_f32_e32 v50, v254, v210
	v_fmac_f32_e32 v51, v255, v211
	s_waitcnt lgkmcnt(1)
	v_mfma_f32_32x32x16_bf16 v[212:227], v[78:81], v[46:49], v[212:227]
	v_max_f32_e32 v108, 0, v18
	v_max_f32_e32 v109, 0, v19
	v_fmac_f32_e32 v50, v200, v108
	v_fmac_f32_e32 v51, v201, v109
	v_max_f32_e32 v210, 0, v20
	v_max_f32_e32 v211, 0, v21
	v_fmac_f32_e32 v50, v202, v210
	v_fmac_f32_e32 v51, v203, v211
	v_add_f32_e32 v50, v50, v51
	v_ashrrev_i32_e32 v51, 31, v50
	s_waitcnt lgkmcnt(0)
	v_mfma_f32_32x32x16_bf16 v[212:227], v[82:85], v[196:199], v[212:227]
	v_or_b32_e32 v51, 0x80000000, v51
	s_cmpk_gt_i32 s11, 480
	s_cselect_b64 vcc, -1, 0
	v_xor_b32_e32 v50, v51, v50
	v_cndmask_b32_e32 v50, v123, v50, vcc
	global_store_dword v243, v50, s[8:9]
	v_mfma_f32_32x32x16_bf16 v[6:21], v[86:89], v[38:41], 0
	s_add_i32 m0, s10, 0
	s_nop 0
	global_load_lds_dwordx4 v102, s[6:7]
	s_add_i32 m0, s10, 1024
	s_nop 0
	global_load_lds_dwordx4 v110, s[6:7]
	s_add_i32 m0, s10, 2048
	s_nop 0
	global_load_lds_dwordx4 v112, s[6:7]
	s_add_i32 m0, s10, 3072
	s_nop 0
	global_load_lds_dwordx4 v193, s[6:7]
	s_add_u32 s6, s6, 0x8000
	s_addc_u32 s7, s7, 0
	v_max_f32_e32 v108, 0, v212
	v_max_f32_e32 v109, 0, v213
	v_mul_f32_e32 v0, v22, v108
	v_mul_f32_e32 v1, v23, v109
	v_max_f32_e32 v210, 0, v214
	v_max_f32_e32 v211, 0, v215
	v_fmac_f32_e32 v0, v24, v210
	v_fmac_f32_e32 v1, v25, v211
	v_max_f32_e32 v108, 0, v216
	v_max_f32_e32 v109, 0, v217
	v_fmac_f32_e32 v0, v26, v108
	v_fmac_f32_e32 v1, v27, v109
	v_mfma_f32_32x32x16_bf16 v[6:21], v[90:93], v[42:45], v[6:21]
	v_max_f32_e32 v210, 0, v218
	v_max_f32_e32 v211, 0, v219
	v_fmac_f32_e32 v0, v28, v210
	v_fmac_f32_e32 v1, v29, v211
	v_max_f32_e32 v108, 0, v220
	v_max_f32_e32 v109, 0, v221
	v_fmac_f32_e32 v0, v30, v108
	v_fmac_f32_e32 v1, v31, v109
	v_max_f32_e32 v210, 0, v222
	v_max_f32_e32 v211, 0, v223
	v_fmac_f32_e32 v0, v32, v210
	v_fmac_f32_e32 v1, v33, v211
	v_mfma_f32_32x32x16_bf16 v[6:21], v[94:97], v[46:49], v[6:21]
	v_max_f32_e32 v108, 0, v224
	v_max_f32_e32 v109, 0, v225
	v_fmac_f32_e32 v0, v34, v108
	v_fmac_f32_e32 v1, v35, v109
	v_max_f32_e32 v210, 0, v226
	v_max_f32_e32 v211, 0, v227
	v_fmac_f32_e32 v0, v36, v210
	v_fmac_f32_e32 v1, v37, v211
	v_add_f32_e32 v0, v0, v1
	v_ashrrev_i32_e32 v1, 31, v0
	v_mfma_f32_32x32x16_bf16 v[6:21], v[98:101], v[196:199], v[6:21]
	s_waitcnt vmcnt(10)
	v_add_u32_e32 v228, 0x10000, v5
	ds_read_b128 v[38:41], v228 offset:10496
	v_add_u32_e32 v228, 0x10000, v52
	ds_read_b128 v[42:45], v228 offset:10496
	v_add_u32_e32 v228, 0x10000, v55
	ds_read_b128 v[46:49], v228 offset:10496
	v_add_u32_e32 v228, 0x10000, v56
	ds_read_b128 v[196:199], v228 offset:10496
	v_or_b32_e32 v1, 0x80000000, v1
	s_cmpk_gt_i32 s11, 488
	s_cselect_b64 vcc, -1, 0
	v_xor_b32_e32 v0, v1, v0
	v_cndmask_b32_e32 v2, v123, v0, vcc
	s_nop 3
	s_waitcnt lgkmcnt(3)
	v_mfma_f32_32x32x16_bf16 v[212:227], v[70:73], v[38:41], 0
	v_max_f32_e32 v108, 0, v6
	v_max_f32_e32 v109, 0, v7
	v_mul_f32_e32 v50, v244, v108
	v_mul_f32_e32 v51, v245, v109
	v_max_f32_e32 v210, 0, v8
	v_max_f32_e32 v211, 0, v9
	v_fmac_f32_e32 v50, v246, v210
	v_fmac_f32_e32 v51, v247, v211
	v_max_f32_e32 v108, 0, v10
	v_max_f32_e32 v109, 0, v11
	v_fmac_f32_e32 v50, v248, v108
	v_fmac_f32_e32 v51, v249, v109
	s_waitcnt lgkmcnt(2)
	v_mfma_f32_32x32x16_bf16 v[212:227], v[74:77], v[42:45], v[212:227]
	v_max_f32_e32 v210, 0, v12
	v_max_f32_e32 v211, 0, v13
	v_fmac_f32_e32 v50, v250, v210
	v_fmac_f32_e32 v51, v251, v211
	v_max_f32_e32 v108, 0, v14
	v_max_f32_e32 v109, 0, v15
	v_fmac_f32_e32 v50, v252, v108
	v_fmac_f32_e32 v51, v253, v109
	v_max_f32_e32 v210, 0, v16
	v_max_f32_e32 v211, 0, v17
	v_fmac_f32_e32 v50, v254, v210
	v_fmac_f32_e32 v51, v255, v211
	s_waitcnt lgkmcnt(1)
	v_mfma_f32_32x32x16_bf16 v[212:227], v[78:81], v[46:49], v[212:227]
	v_max_f32_e32 v108, 0, v18
	v_max_f32_e32 v109, 0, v19
	v_fmac_f32_e32 v50, v200, v108
	v_fmac_f32_e32 v51, v201, v109
	v_max_f32_e32 v210, 0, v20
	v_max_f32_e32 v211, 0, v21
	v_fmac_f32_e32 v50, v202, v210
	v_fmac_f32_e32 v51, v203, v211
	v_add_f32_e32 v50, v50, v51
	v_ashrrev_i32_e32 v51, 31, v50
	s_waitcnt lgkmcnt(0)
	v_mfma_f32_32x32x16_bf16 v[212:227], v[82:85], v[196:199], v[212:227]
	v_or_b32_e32 v51, 0x80000000, v51
	s_cmpk_gt_i32 s11, 488
	s_cselect_b64 vcc, -1, 0
	v_xor_b32_e32 v50, v51, v50
	v_cndmask_b32_e32 v50, v123, v50, vcc
	global_store_dword v243, v50, s[8:9] offset:2048
	s_add_u32 s8, s8, 0x1000
	s_addc_u32 s9, s9, 0
	v_mfma_f32_32x32x16_bf16 v[6:21], v[86:89], v[38:41], 0
	s_add_i32 m0, s10, 32768
	s_nop 0
	global_load_lds_dwordx4 v102, s[6:7]
	s_add_i32 m0, s10, 33792
	s_nop 0
	global_load_lds_dwordx4 v110, s[6:7]
	s_add_i32 m0, s10, 34816
	s_nop 0
	global_load_lds_dwordx4 v112, s[6:7]
	s_add_i32 m0, s10, 35840
	s_nop 0
	global_load_lds_dwordx4 v193, s[6:7]
	s_add_u32 s6, s6, 0x8000
	s_addc_u32 s7, s7, 0
	v_max_f32_e32 v108, 0, v212
	v_max_f32_e32 v109, 0, v213
	v_mul_f32_e32 v0, v22, v108
	v_mul_f32_e32 v1, v23, v109
	v_max_f32_e32 v210, 0, v214
	v_max_f32_e32 v211, 0, v215
	v_fmac_f32_e32 v0, v24, v210
	v_fmac_f32_e32 v1, v25, v211
	v_max_f32_e32 v108, 0, v216
	v_max_f32_e32 v109, 0, v217
	v_fmac_f32_e32 v0, v26, v108
	v_fmac_f32_e32 v1, v27, v109
	v_mfma_f32_32x32x16_bf16 v[6:21], v[90:93], v[42:45], v[6:21]
	v_max_f32_e32 v210, 0, v218
	v_max_f32_e32 v211, 0, v219
	v_fmac_f32_e32 v0, v28, v210
	v_fmac_f32_e32 v1, v29, v211
	v_max_f32_e32 v108, 0, v220
	v_max_f32_e32 v109, 0, v221
	v_fmac_f32_e32 v0, v30, v108
	v_fmac_f32_e32 v1, v31, v109
	v_max_f32_e32 v210, 0, v222
	v_max_f32_e32 v211, 0, v223
	v_fmac_f32_e32 v0, v32, v210
	v_fmac_f32_e32 v1, v33, v211
	v_mfma_f32_32x32x16_bf16 v[6:21], v[94:97], v[46:49], v[6:21]
	v_max_f32_e32 v108, 0, v224
	v_max_f32_e32 v109, 0, v225
	v_fmac_f32_e32 v0, v34, v108
	v_fmac_f32_e32 v1, v35, v109
	v_max_f32_e32 v210, 0, v226
	v_max_f32_e32 v211, 0, v227
	v_fmac_f32_e32 v0, v36, v210
	v_fmac_f32_e32 v1, v37, v211
	v_add_f32_e32 v0, v0, v1
	v_ashrrev_i32_e32 v1, 31, v0
	v_mfma_f32_32x32x16_bf16 v[6:21], v[98:101], v[196:199], v[6:21]
	s_waitcnt vmcnt(10)
	v_add_u32_e32 v228, 0x10000, v5
	ds_read_b128 v[38:41], v228 offset:43264
	v_add_u32_e32 v228, 0x10000, v52
	ds_read_b128 v[42:45], v228 offset:43264
	v_add_u32_e32 v228, 0x10000, v55
	ds_read_b128 v[46:49], v228 offset:43264
	v_add_u32_e32 v228, 0x10000, v56
	ds_read_b128 v[196:199], v228 offset:43264
	v_or_b32_e32 v1, 0x80000000, v1
	s_cmpk_gt_i32 s11, 496
	s_cselect_b64 vcc, -1, 0
	v_xor_b32_e32 v0, v1, v0
	v_cndmask_b32_e32 v4, v123, v0, vcc
	s_nop 3
	s_waitcnt lgkmcnt(3)
	v_mfma_f32_32x32x16_bf16 v[212:227], v[70:73], v[38:41], 0
	v_max_f32_e32 v108, 0, v6
	v_max_f32_e32 v109, 0, v7
	v_mul_f32_e32 v50, v244, v108
	v_mul_f32_e32 v51, v245, v109
	v_max_f32_e32 v210, 0, v8
	v_max_f32_e32 v211, 0, v9
	v_fmac_f32_e32 v50, v246, v210
	v_fmac_f32_e32 v51, v247, v211
	v_max_f32_e32 v108, 0, v10
	v_max_f32_e32 v109, 0, v11
	v_fmac_f32_e32 v50, v248, v108
	v_fmac_f32_e32 v51, v249, v109
	s_waitcnt lgkmcnt(2)
	v_mfma_f32_32x32x16_bf16 v[212:227], v[74:77], v[42:45], v[212:227]
	v_max_f32_e32 v210, 0, v12
	v_max_f32_e32 v211, 0, v13
	v_fmac_f32_e32 v50, v250, v210
	v_fmac_f32_e32 v51, v251, v211
	v_max_f32_e32 v108, 0, v14
	v_max_f32_e32 v109, 0, v15
	v_fmac_f32_e32 v50, v252, v108
	v_fmac_f32_e32 v51, v253, v109
	v_max_f32_e32 v210, 0, v16
	v_max_f32_e32 v211, 0, v17
	v_fmac_f32_e32 v50, v254, v210
	v_fmac_f32_e32 v51, v255, v211
	s_waitcnt lgkmcnt(1)
	v_mfma_f32_32x32x16_bf16 v[212:227], v[78:81], v[46:49], v[212:227]
	v_max_f32_e32 v108, 0, v18
	v_max_f32_e32 v109, 0, v19
	v_fmac_f32_e32 v50, v200, v108
	v_fmac_f32_e32 v51, v201, v109
	v_max_f32_e32 v210, 0, v20
	v_max_f32_e32 v211, 0, v21
	v_fmac_f32_e32 v50, v202, v210
	v_fmac_f32_e32 v51, v203, v211
	v_add_f32_e32 v50, v50, v51
	v_ashrrev_i32_e32 v51, 31, v50
	s_waitcnt lgkmcnt(0)
	v_mfma_f32_32x32x16_bf16 v[212:227], v[82:85], v[196:199], v[212:227]
	v_or_b32_e32 v51, 0x80000000, v51
	s_cmpk_gt_i32 s11, 496
	s_cselect_b64 vcc, -1, 0
	v_xor_b32_e32 v50, v51, v50
	v_cndmask_b32_e32 v50, v123, v50, vcc
	global_store_dword v243, v50, s[8:9]
	v_mfma_f32_32x32x16_bf16 v[6:21], v[86:89], v[38:41], 0
	s_add_i32 m0, s10, 65536
	s_nop 0
	global_load_lds_dwordx4 v102, s[6:7]
	s_add_i32 m0, s10, 66560
	s_nop 0
	global_load_lds_dwordx4 v110, s[6:7]
	s_add_i32 m0, s10, 67584
	s_nop 0
	global_load_lds_dwordx4 v112, s[6:7]
	s_add_i32 m0, s10, 68608
	s_nop 0
	global_load_lds_dwordx4 v193, s[6:7]
	s_add_u32 s6, s6, 0x8000
	s_addc_u32 s7, s7, 0
	v_max_f32_e32 v108, 0, v212
	v_max_f32_e32 v109, 0, v213
	v_mul_f32_e32 v0, v22, v108
	v_mul_f32_e32 v1, v23, v109
	v_max_f32_e32 v210, 0, v214
	v_max_f32_e32 v211, 0, v215
	v_fmac_f32_e32 v0, v24, v210
	v_fmac_f32_e32 v1, v25, v211
	v_max_f32_e32 v108, 0, v216
	v_max_f32_e32 v109, 0, v217
	v_fmac_f32_e32 v0, v26, v108
	v_fmac_f32_e32 v1, v27, v109
	v_mfma_f32_32x32x16_bf16 v[6:21], v[90:93], v[42:45], v[6:21]
	v_max_f32_e32 v210, 0, v218
	v_max_f32_e32 v211, 0, v219
	v_fmac_f32_e32 v0, v28, v210
	v_fmac_f32_e32 v1, v29, v211
	v_max_f32_e32 v108, 0, v220
	v_max_f32_e32 v109, 0, v221
	v_fmac_f32_e32 v0, v30, v108
	v_fmac_f32_e32 v1, v31, v109
	v_max_f32_e32 v210, 0, v222
	v_max_f32_e32 v211, 0, v223
	v_fmac_f32_e32 v0, v32, v210
	v_fmac_f32_e32 v1, v33, v211
	v_mfma_f32_32x32x16_bf16 v[6:21], v[94:97], v[46:49], v[6:21]
	v_max_f32_e32 v108, 0, v224
	v_max_f32_e32 v109, 0, v225
	v_fmac_f32_e32 v0, v34, v108
	v_fmac_f32_e32 v1, v35, v109
	v_max_f32_e32 v210, 0, v226
	v_max_f32_e32 v211, 0, v227
	v_fmac_f32_e32 v0, v36, v210
	v_fmac_f32_e32 v1, v37, v211
	v_add_f32_e32 v0, v0, v1
	v_ashrrev_i32_e32 v1, 31, v0
	v_mfma_f32_32x32x16_bf16 v[6:21], v[98:101], v[196:199], v[6:21]
	s_waitcnt vmcnt(10)
	ds_read_b128 v[38:41], v5 offset:10496
	ds_read_b128 v[42:45], v52 offset:10496
	ds_read_b128 v[46:49], v55 offset:10496
	ds_read_b128 v[196:199], v56 offset:10496
	v_or_b32_e32 v1, 0x80000000, v1
	s_cmpk_gt_i32 s11, 504
	s_cselect_b64 vcc, -1, 0
	v_xor_b32_e32 v0, v1, v0
	v_cndmask_b32_e32 v185, v123, v0, vcc
	s_nop 3
	v_max_f32_e32 v108, 0, v6
	v_max_f32_e32 v109, 0, v7
	v_mul_f32_e32 v50, v244, v108
	v_mul_f32_e32 v51, v245, v109
	v_max_f32_e32 v210, 0, v8
	v_max_f32_e32 v211, 0, v9
	v_fmac_f32_e32 v50, v246, v210
	v_fmac_f32_e32 v51, v247, v211
	v_max_f32_e32 v108, 0, v10
	v_max_f32_e32 v109, 0, v11
	v_fmac_f32_e32 v50, v248, v108
	v_fmac_f32_e32 v51, v249, v109
	v_max_f32_e32 v210, 0, v12
	v_max_f32_e32 v211, 0, v13
	v_fmac_f32_e32 v50, v250, v210
	v_fmac_f32_e32 v51, v251, v211
	v_max_f32_e32 v108, 0, v14
	v_max_f32_e32 v109, 0, v15
	v_fmac_f32_e32 v50, v252, v108
	v_fmac_f32_e32 v51, v253, v109
	v_max_f32_e32 v210, 0, v16
	v_max_f32_e32 v211, 0, v17
	v_fmac_f32_e32 v50, v254, v210
	v_fmac_f32_e32 v51, v255, v211
	v_max_f32_e32 v108, 0, v18
	v_max_f32_e32 v109, 0, v19
	v_fmac_f32_e32 v50, v200, v108
	v_fmac_f32_e32 v51, v201, v109
	v_max_f32_e32 v210, 0, v20
	v_max_f32_e32 v211, 0, v21
	v_fmac_f32_e32 v50, v202, v210
	v_fmac_f32_e32 v51, v203, v211
	v_add_f32_e32 v50, v50, v51
	v_ashrrev_i32_e32 v51, 31, v50
	v_or_b32_e32 v51, 0x80000000, v51
	s_cmpk_gt_i32 s11, 504
	s_cselect_b64 vcc, -1, 0
	v_xor_b32_e32 v50, v51, v50
	v_cndmask_b32_e32 v50, v123, v50, vcc
	global_store_dword v243, v50, s[8:9] offset:2048
	s_add_u32 s8, s8, 0x1000
	s_addc_u32 s9, s9, 0
	s_branch .Lix_done
